# fused-LN epilogue: Xb (bf16) n=0/n=1 pieces paired with v_permlane16_swap, one dwordx4 store instead of two dwordx2
# speedup vs baseline: 1.0088x; 1.0001x over previous
.LBB0_87:
	s_or_b64 exec, exec, s[4:5]
	s_lshl_b32 s2, s29, 3
	s_add_i32 s2, s2, 0
	v_lshl_add_u32 v144, v147, 3, s2
	v_readlane_b32 s2, v253, 2
	v_lshlrev_b64 v[48:49], 10, v[176:177]
	v_lshlrev_b64 v[50:51], 2, v[128:129]
	v_readlane_b32 s3, v253, 3
	v_lshl_add_u64 v[176:177], v[48:49], 0, v[128:129]
	s_waitcnt lgkmcnt(0)
	v_lshl_add_u64 v[48:49], s[2:3], 0, v[50:51]
	v_readlane_b32 s2, v253, 4
	v_readlane_b32 s3, v253, 5
	s_barrier
	v_mbcnt_lo_u32_b32 v192, -1, 0
	v_mbcnt_hi_u32_b32 v192, -1, v192
	v_and_b32_e32 v192, 16, v192
	v_lshrrev_b32_e32 v192, 1, v192
	v_mul_u32_u24_e32 v192, 3, v192
	v_add_u32_e32 v192, 0xffffffe0, v192
	v_mov_b32_e32 v193, -1
	s_nop 0
	v_lshl_add_u64 v[50:51], s[2:3], 0, v[50:51]
	s_nop 0
	s_nop 0
	ds_read_b64 v[184:185], v144 offset:8192
	s_waitcnt lgkmcnt(0)
	v_sub_f32_e32 v153, v183, v184
	v_sub_f32_e32 v152, v182, v184
	v_sub_f32_e32 v181, v181, v184
	v_sub_f32_e32 v180, v180, v184
	v_pk_mul_f32 v[180:181], v[184:185], v[180:181] op_sel:[1,0]
	v_pk_mul_f32 v[152:153], v[184:185], v[152:153] op_sel:[1,0]
	v_sub_f32_e32 v173, v173, v184
	v_sub_f32_e32 v172, v172, v184
	v_pk_mul_f32 v[172:173], v[184:185], v[172:173] op_sel:[1,0]
	v_sub_f32_e32 v163, v163, v184
	v_sub_f32_e32 v162, v162, v184
	v_sub_f32_e32 v143, v143, v184
	v_sub_f32_e32 v142, v142, v184
	v_pk_mul_f32 v[142:143], v[184:185], v[142:143] op_sel:[1,0]
	v_pk_mul_f32 v[162:163], v[184:185], v[162:163] op_sel:[1,0]
	v_sub_f32_e32 v137, v137, v184
	v_sub_f32_e32 v136, v136, v184
	v_sub_f32_e32 v135, v135, v184
	v_sub_f32_e32 v134, v134, v184
	v_pk_mul_f32 v[134:135], v[184:185], v[134:135] op_sel:[1,0]
	v_pk_mul_f32 v[136:137], v[184:185], v[136:137] op_sel:[1,0]
	s_waitcnt vmcnt(0)
	v_pk_fma_f32 v[182:183], v[214:215], v[152:153], v[230:231]
	v_pk_fma_f32 v[180:181], v[212:213], v[180:181], v[228:229]
	global_store_dwordx4 v[178:179], v[180:183], off
	v_lshl_add_u64 v[178:179], v[176:177], 1, s[64:65]
	v_cvt_pk_bf16_f32 v152, v180, v181
	v_cvt_pk_bf16_f32 v153, v182, v183
	v_mov_b32_e32 v236, v152
	v_mov_b32_e32 v237, v153
	s_nop 0
	s_nop 0
	v_sub_f32_e32 v153, v175, v184
	v_sub_f32_e32 v152, v174, v184
	v_pk_mul_f32 v[152:153], v[184:185], v[152:153] op_sel:[1,0]
	s_nop 0
	v_pk_fma_f32 v[172:173], v[172:173], v[216:217], v[232:233]
	v_pk_fma_f32 v[174:175], v[152:153], v[218:219], v[234:235]
	v_or_b32_e32 v152, 16, v176
	v_mov_b32_e32 v153, v177
	v_lshl_add_u64 v[178:179], v[152:153], 2, s[66:67]
	v_lshl_add_u64 v[152:153], v[152:153], 1, s[64:65]
	global_store_dwordx4 v[178:179], v[172:175], off
	s_nop 1
	s_nop 1
	v_cvt_pk_bf16_f32 v172, v172, v173
	v_cvt_pk_bf16_f32 v173, v174, v175
	v_mov_b32_e32 v238, v172
	v_mov_b32_e32 v239, v173
	v_lshl_add_u64 v[152:153], v[152:153], 0, v[192:193]
	s_nop 0
	v_permlane16_swap_b32 v236, v238
	v_permlane16_swap_b32 v237, v239
	global_store_dwordx4 v[152:153], v[236:239], off
	s_nop 0
	s_nop 0
	v_or_b32_e32 v152, 0x80, v176
	v_mov_b32_e32 v153, v177
	v_or_b32_e32 v176, 0x90, v176
	s_nop 0
	v_pk_fma_f32 v[174:175], v[162:163], v[222:223], v[244:245]
	v_pk_fma_f32 v[172:173], v[142:143], v[220:221], v[242:243]
	v_lshl_add_u64 v[142:143], v[152:153], 2, s[66:67]
	v_lshl_add_u64 v[152:153], v[152:153], 1, s[64:65]
	global_store_dwordx4 v[142:143], v[172:175], off
	v_cvt_pk_bf16_f32 v142, v172, v173
	v_cvt_pk_bf16_f32 v143, v174, v175
	v_mov_b32_e32 v236, v142
	v_mov_b32_e32 v237, v143
	s_nop 0
	s_nop 0
	v_lshl_add_u64 v[142:143], v[176:177], 2, s[66:67]
	s_nop 0
	v_pk_fma_f32 v[136:137], v[136:137], v[226:227], v[248:249]
	v_pk_fma_f32 v[134:135], v[134:135], v[224:225], v[246:247]
	global_store_dwordx4 v[142:143], v[134:137], off
	s_nop 1
	s_nop 1
	v_cvt_pk_bf16_f32 v134, v134, v135
	v_cvt_pk_bf16_f32 v135, v136, v137
	v_lshl_add_u64 v[136:137], v[176:177], 1, s[64:65]
	v_mov_b32_e32 v238, v134
	v_mov_b32_e32 v239, v135
	v_lshl_add_u64 v[136:137], v[136:137], 0, v[192:193]
	s_nop 0
	v_permlane16_swap_b32 v236, v238
	v_permlane16_swap_b32 v237, v239
	global_store_dwordx4 v[136:137], v[236:239], off
	ds_read_b64 v[136:137], v144 offset:8320
	v_lshlrev_b64 v[134:135], 10, v[170:171]
	s_nop 0
	s_nop 0
	v_lshl_add_u64 v[134:135], v[134:135], 0, v[128:129]
	s_waitcnt lgkmcnt(0)
	v_sub_f32_e32 v143, v169, v136
	v_sub_f32_e32 v142, v168, v136
	v_sub_f32_e32 v153, v167, v136
	v_sub_f32_e32 v152, v166, v136
	v_pk_mul_f32 v[152:153], v[136:137], v[152:153] op_sel:[1,0]
	v_pk_mul_f32 v[142:143], v[136:137], v[142:143] op_sel:[1,0]
	v_sub_f32_e32 v141, v141, v136
	v_sub_f32_e32 v140, v140, v136
	v_sub_f32_e32 v139, v139, v136
	v_sub_f32_e32 v138, v138, v136
	v_pk_mul_f32 v[138:139], v[136:137], v[138:139] op_sel:[1,0]
	v_pk_mul_f32 v[140:141], v[136:137], v[140:141] op_sel:[1,0]
	v_sub_f32_e32 v123, v123, v136
	v_sub_f32_e32 v122, v122, v136
	v_sub_f32_e32 v121, v121, v136
	v_sub_f32_e32 v120, v120, v136
	v_pk_mul_f32 v[120:121], v[136:137], v[120:121] op_sel:[1,0]
	v_pk_mul_f32 v[122:123], v[136:137], v[122:123] op_sel:[1,0]
	v_sub_f32_e32 v115, v115, v136
	v_sub_f32_e32 v114, v114, v136
	v_sub_f32_e32 v113, v113, v136
	v_sub_f32_e32 v112, v112, v136
	v_pk_mul_f32 v[112:113], v[136:137], v[112:113] op_sel:[1,0]
	v_pk_mul_f32 v[114:115], v[136:137], v[114:115] op_sel:[1,0]
	s_nop 0
	v_pk_fma_f32 v[168:169], v[214:215], v[142:143], v[230:231]
	v_pk_fma_f32 v[166:167], v[212:213], v[152:153], v[228:229]
	v_lshl_add_u64 v[152:153], v[134:135], 1, s[64:65]
	global_store_dwordx4 v[164:165], v[166:169], off
	v_cvt_pk_bf16_f32 v142, v166, v167
	v_cvt_pk_bf16_f32 v143, v168, v169
	v_mov_b32_e32 v236, v142
	v_mov_b32_e32 v237, v143
	s_nop 0
	s_nop 0
	v_or_b32_e32 v142, 16, v134
	v_mov_b32_e32 v143, v135
	v_lshl_add_u64 v[152:153], v[142:143], 2, s[66:67]
	s_nop 0
	v_pk_fma_f32 v[140:141], v[140:141], v[218:219], v[234:235]
	v_pk_fma_f32 v[138:139], v[138:139], v[216:217], v[232:233]
	global_store_dwordx4 v[152:153], v[138:141], off
	s_nop 1
	s_nop 1
	v_cvt_pk_bf16_f32 v138, v138, v139
	v_cvt_pk_bf16_f32 v139, v140, v141
	v_lshl_add_u64 v[140:141], v[142:143], 1, s[64:65]
	v_mov_b32_e32 v238, v138
	v_mov_b32_e32 v239, v139
	v_lshl_add_u64 v[140:141], v[140:141], 0, v[192:193]
	s_nop 0
	v_permlane16_swap_b32 v236, v238
	v_permlane16_swap_b32 v237, v239
	global_store_dwordx4 v[140:141], v[236:239], off
	s_nop 0
	s_nop 0
	v_or_b32_e32 v142, 0x80, v134
	v_or_b32_e32 v134, 0x90, v134
	s_nop 0
	v_pk_fma_f32 v[122:123], v[122:123], v[222:223], v[244:245]
	v_pk_fma_f32 v[120:121], v[120:121], v[220:221], v[242:243]
	v_lshl_add_u64 v[138:139], v[142:143], 2, s[66:67]
	global_store_dwordx4 v[138:139], v[120:123], off
	s_nop 1
	s_nop 1
	v_cvt_pk_bf16_f32 v120, v120, v121
	v_cvt_pk_bf16_f32 v121, v122, v123
	v_lshl_add_u64 v[122:123], v[142:143], 1, s[64:65]
	v_mov_b32_e32 v236, v120
	v_mov_b32_e32 v237, v121
	s_nop 0
	s_nop 0
	s_nop 0
	v_pk_fma_f32 v[114:115], v[114:115], v[226:227], v[248:249]
	v_pk_fma_f32 v[112:113], v[112:113], v[224:225], v[246:247]
	v_lshl_add_u64 v[120:121], v[134:135], 2, s[66:67]
	global_store_dwordx4 v[120:121], v[112:115], off
	s_nop 1
	s_nop 1
	v_cvt_pk_bf16_f32 v112, v112, v113
	v_cvt_pk_bf16_f32 v113, v114, v115
	v_lshl_add_u64 v[114:115], v[134:135], 1, s[64:65]
	v_mov_b32_e32 v238, v112
	v_mov_b32_e32 v239, v113
	v_lshl_add_u64 v[114:115], v[114:115], 0, v[192:193]
	s_nop 0
	v_permlane16_swap_b32 v236, v238
	v_permlane16_swap_b32 v237, v239
	global_store_dwordx4 v[114:115], v[236:239], off
	ds_read_b64 v[114:115], v144 offset:8448
	v_lshlrev_b64 v[112:113], 10, v[132:133]
	s_nop 0
	s_nop 0
	v_lshl_add_u64 v[112:113], v[112:113], 0, v[128:129]
	s_waitcnt lgkmcnt(0)
	v_sub_f32_e32 v131, v131, v114
	v_sub_f32_e32 v130, v130, v114
	v_sub_f32_e32 v127, v127, v114
	v_sub_f32_e32 v126, v126, v114
	v_pk_mul_f32 v[126:127], v[114:115], v[126:127] op_sel:[1,0]
	v_pk_mul_f32 v[130:131], v[114:115], v[130:131] op_sel:[1,0]
	v_sub_f32_e32 v117, v117, v114
	v_sub_f32_e32 v116, v116, v114
	v_sub_f32_e32 v119, v119, v114
	v_sub_f32_e32 v118, v118, v114
	v_pk_mul_f32 v[116:117], v[114:115], v[116:117] op_sel:[1,0]
	v_pk_mul_f32 v[118:119], v[114:115], v[118:119] op_sel:[1,0]
	v_sub_f32_e32 v103, v103, v114
	v_sub_f32_e32 v102, v102, v114
	v_sub_f32_e32 v101, v101, v114
	v_sub_f32_e32 v100, v100, v114
	v_pk_mul_f32 v[100:101], v[114:115], v[100:101] op_sel:[1,0]
	v_pk_mul_f32 v[102:103], v[114:115], v[102:103] op_sel:[1,0]
	v_sub_f32_e32 v95, v95, v114
	v_sub_f32_e32 v94, v94, v114
	v_sub_f32_e32 v93, v93, v114
	v_sub_f32_e32 v92, v92, v114
	v_pk_mul_f32 v[92:93], v[114:115], v[92:93] op_sel:[1,0]
	v_pk_mul_f32 v[94:95], v[114:115], v[94:95] op_sel:[1,0]
	s_nop 0
	v_pk_fma_f32 v[122:123], v[214:215], v[130:131], v[230:231]
	v_pk_fma_f32 v[120:121], v[212:213], v[126:127], v[228:229]
	global_store_dwordx4 v[124:125], v[120:123], off
	s_nop 1
	s_nop 1
	v_cvt_pk_bf16_f32 v120, v120, v121
	v_cvt_pk_bf16_f32 v121, v122, v123
	v_lshl_add_u64 v[122:123], v[112:113], 1, s[64:65]
	v_mov_b32_e32 v236, v120
	v_mov_b32_e32 v237, v121
	s_nop 0
	s_nop 0
	s_nop 0
	v_pk_fma_f32 v[116:117], v[116:117], v[216:217], v[232:233]
	v_or_b32_e32 v120, 16, v112
	v_mov_b32_e32 v121, v113
	v_pk_fma_f32 v[118:119], v[118:119], v[218:219], v[234:235]
	v_lshl_add_u64 v[122:123], v[120:121], 2, s[66:67]
	global_store_dwordx4 v[122:123], v[116:119], off
	v_or_b32_e32 v124, 0x80, v112
	v_mov_b32_e32 v125, v113
	v_cvt_pk_bf16_f32 v116, v116, v117
	v_cvt_pk_bf16_f32 v117, v118, v119
	v_lshl_add_u64 v[118:119], v[120:121], 1, s[64:65]
	v_mov_b32_e32 v238, v116
	v_mov_b32_e32 v239, v117
	v_lshl_add_u64 v[118:119], v[118:119], 0, v[192:193]
	s_nop 0
	v_permlane16_swap_b32 v236, v238
	v_permlane16_swap_b32 v237, v239
	global_store_dwordx4 v[118:119], v[236:239], off
	s_nop 0
	s_nop 0
	v_or_b32_e32 v112, 0x90, v112
	s_nop 0
	v_pk_fma_f32 v[102:103], v[102:103], v[222:223], v[244:245]
	v_pk_fma_f32 v[100:101], v[100:101], v[220:221], v[242:243]
	v_lshl_add_u64 v[116:117], v[124:125], 2, s[66:67]
	global_store_dwordx4 v[116:117], v[100:103], off
	s_nop 1
	s_nop 1
	v_cvt_pk_bf16_f32 v100, v100, v101
	v_cvt_pk_bf16_f32 v101, v102, v103
	v_lshl_add_u64 v[102:103], v[124:125], 1, s[64:65]
	v_mov_b32_e32 v236, v100
	v_mov_b32_e32 v237, v101
	s_nop 0
	s_nop 0
	s_nop 0
	v_pk_fma_f32 v[94:95], v[94:95], v[226:227], v[248:249]
	v_pk_fma_f32 v[92:93], v[92:93], v[224:225], v[246:247]
	v_lshl_add_u64 v[100:101], v[112:113], 2, s[66:67]
	global_store_dwordx4 v[100:101], v[92:95], off
	s_nop 1
	s_nop 1
	v_cvt_pk_bf16_f32 v92, v92, v93
	v_cvt_pk_bf16_f32 v93, v94, v95
	v_lshl_add_u64 v[94:95], v[112:113], 1, s[64:65]
	v_mov_b32_e32 v238, v92
	v_mov_b32_e32 v239, v93
	v_lshl_add_u64 v[94:95], v[94:95], 0, v[192:193]
	s_nop 0
	v_permlane16_swap_b32 v236, v238
	v_permlane16_swap_b32 v237, v239
	global_store_dwordx4 v[94:95], v[236:239], off
	ds_read_b64 v[94:95], v144 offset:8576
	v_lshlrev_b64 v[92:93], 10, v[110:111]
	s_nop 0
	s_nop 0
	v_lshl_add_u64 v[92:93], v[92:93], 0, v[128:129]
	s_waitcnt lgkmcnt(0)
	v_sub_f32_e32 v109, v109, v94
	v_sub_f32_e32 v108, v108, v94
	v_sub_f32_e32 v107, v107, v94
	v_sub_f32_e32 v106, v106, v94
	v_pk_mul_f32 v[106:107], v[94:95], v[106:107] op_sel:[1,0]
	v_pk_mul_f32 v[108:109], v[94:95], v[108:109] op_sel:[1,0]
	v_sub_f32_e32 v97, v97, v94
	v_sub_f32_e32 v96, v96, v94
	v_sub_f32_e32 v99, v99, v94
	v_sub_f32_e32 v98, v98, v94
	v_pk_mul_f32 v[96:97], v[94:95], v[96:97] op_sel:[1,0]
	v_pk_mul_f32 v[98:99], v[94:95], v[98:99] op_sel:[1,0]
	v_sub_f32_e32 v83, v83, v94
	v_sub_f32_e32 v82, v82, v94
	v_sub_f32_e32 v81, v81, v94
	v_sub_f32_e32 v80, v80, v94
	v_pk_mul_f32 v[80:81], v[94:95], v[80:81] op_sel:[1,0]
	v_pk_mul_f32 v[82:83], v[94:95], v[82:83] op_sel:[1,0]
	v_sub_f32_e32 v75, v75, v94
	v_sub_f32_e32 v74, v74, v94
	v_sub_f32_e32 v73, v73, v94
	v_sub_f32_e32 v72, v72, v94
	v_pk_mul_f32 v[72:73], v[94:95], v[72:73] op_sel:[1,0]
	v_pk_mul_f32 v[74:75], v[94:95], v[74:75] op_sel:[1,0]
	s_nop 0
	v_pk_fma_f32 v[102:103], v[214:215], v[108:109], v[230:231]
	v_pk_fma_f32 v[100:101], v[212:213], v[106:107], v[228:229]
	global_store_dwordx4 v[104:105], v[100:103], off
	s_nop 1
	s_nop 1
	v_cvt_pk_bf16_f32 v100, v100, v101
	v_cvt_pk_bf16_f32 v101, v102, v103
	v_lshl_add_u64 v[102:103], v[92:93], 1, s[64:65]
	v_mov_b32_e32 v236, v100
	v_mov_b32_e32 v237, v101
	s_nop 0
	s_nop 0
	s_nop 0
	v_pk_fma_f32 v[96:97], v[96:97], v[216:217], v[232:233]
	v_or_b32_e32 v100, 16, v92
	v_mov_b32_e32 v101, v93
	v_pk_fma_f32 v[98:99], v[98:99], v[218:219], v[234:235]
	v_lshl_add_u64 v[102:103], v[100:101], 2, s[66:67]
	global_store_dwordx4 v[102:103], v[96:99], off
	v_or_b32_e32 v104, 0x80, v92
	v_mov_b32_e32 v105, v93
	v_cvt_pk_bf16_f32 v96, v96, v97
	v_cvt_pk_bf16_f32 v97, v98, v99
	v_lshl_add_u64 v[98:99], v[100:101], 1, s[64:65]
	v_mov_b32_e32 v238, v96
	v_mov_b32_e32 v239, v97
	v_lshl_add_u64 v[98:99], v[98:99], 0, v[192:193]
	s_nop 0
	v_permlane16_swap_b32 v236, v238
	v_permlane16_swap_b32 v237, v239
	global_store_dwordx4 v[98:99], v[236:239], off
	s_nop 0
	s_nop 0
	v_or_b32_e32 v92, 0x90, v92
	s_nop 0
	v_pk_fma_f32 v[82:83], v[82:83], v[222:223], v[244:245]
	v_pk_fma_f32 v[80:81], v[80:81], v[220:221], v[242:243]
	v_lshl_add_u64 v[96:97], v[104:105], 2, s[66:67]
	global_store_dwordx4 v[96:97], v[80:83], off
	s_nop 1
	s_nop 1
	v_cvt_pk_bf16_f32 v80, v80, v81
	v_cvt_pk_bf16_f32 v81, v82, v83
	v_lshl_add_u64 v[82:83], v[104:105], 1, s[64:65]
	v_mov_b32_e32 v236, v80
	v_mov_b32_e32 v237, v81
	s_nop 0
	s_nop 0
	s_nop 0
	v_pk_fma_f32 v[74:75], v[74:75], v[226:227], v[248:249]
	v_pk_fma_f32 v[72:73], v[72:73], v[224:225], v[246:247]
	v_lshl_add_u64 v[80:81], v[92:93], 2, s[66:67]
	global_store_dwordx4 v[80:81], v[72:75], off
	s_nop 1
	s_nop 1
	v_cvt_pk_bf16_f32 v72, v72, v73
	v_cvt_pk_bf16_f32 v73, v74, v75
	v_lshl_add_u64 v[74:75], v[92:93], 1, s[64:65]
	v_mov_b32_e32 v238, v72
	v_mov_b32_e32 v239, v73
	v_lshl_add_u64 v[74:75], v[74:75], 0, v[192:193]
	s_nop 0
	v_permlane16_swap_b32 v236, v238
	v_permlane16_swap_b32 v237, v239
	global_store_dwordx4 v[74:75], v[236:239], off
	ds_read_b64 v[74:75], v144 offset:9216
	v_lshlrev_b64 v[72:73], 10, v[90:91]
	s_nop 0
	s_nop 0
	v_lshl_add_u64 v[72:73], v[72:73], 0, v[128:129]
	s_waitcnt lgkmcnt(0)
	v_sub_f32_e32 v89, v89, v74
	v_sub_f32_e32 v88, v88, v74
	v_sub_f32_e32 v87, v87, v74
	v_sub_f32_e32 v86, v86, v74
	v_pk_mul_f32 v[86:87], v[74:75], v[86:87] op_sel:[1,0]
	v_pk_mul_f32 v[88:89], v[74:75], v[88:89] op_sel:[1,0]
	v_sub_f32_e32 v77, v77, v74
	v_sub_f32_e32 v76, v76, v74
	v_sub_f32_e32 v79, v79, v74
	v_sub_f32_e32 v78, v78, v74
	v_pk_mul_f32 v[76:77], v[74:75], v[76:77] op_sel:[1,0]
	v_pk_mul_f32 v[78:79], v[74:75], v[78:79] op_sel:[1,0]
	v_sub_f32_e32 v63, v63, v74
	v_sub_f32_e32 v62, v62, v74
	v_sub_f32_e32 v61, v61, v74
	v_sub_f32_e32 v60, v60, v74
	v_pk_mul_f32 v[60:61], v[74:75], v[60:61] op_sel:[1,0]
	v_pk_mul_f32 v[62:63], v[74:75], v[62:63] op_sel:[1,0]
	v_sub_f32_e32 v55, v55, v74
	v_sub_f32_e32 v54, v54, v74
	v_sub_f32_e32 v53, v53, v74
	v_sub_f32_e32 v52, v52, v74
	v_pk_mul_f32 v[52:53], v[74:75], v[52:53] op_sel:[1,0]
	v_pk_mul_f32 v[54:55], v[74:75], v[54:55] op_sel:[1,0]
	s_nop 0
	v_pk_fma_f32 v[82:83], v[214:215], v[88:89], v[230:231]
	v_pk_fma_f32 v[80:81], v[212:213], v[86:87], v[228:229]
	global_store_dwordx4 v[84:85], v[80:83], off
	s_nop 1
	s_nop 1
	v_cvt_pk_bf16_f32 v80, v80, v81
	v_cvt_pk_bf16_f32 v81, v82, v83
	v_lshl_add_u64 v[82:83], v[72:73], 1, s[64:65]
	v_mov_b32_e32 v236, v80
	v_mov_b32_e32 v237, v81
	s_nop 0
	s_nop 0
	s_nop 0
	v_pk_fma_f32 v[76:77], v[76:77], v[216:217], v[232:233]
	v_or_b32_e32 v80, 16, v72
	v_mov_b32_e32 v81, v73
	v_pk_fma_f32 v[78:79], v[78:79], v[218:219], v[234:235]
	v_lshl_add_u64 v[82:83], v[80:81], 2, s[66:67]
	global_store_dwordx4 v[82:83], v[76:79], off
	v_or_b32_e32 v84, 0x80, v72
	v_mov_b32_e32 v85, v73
	v_cvt_pk_bf16_f32 v76, v76, v77
	v_cvt_pk_bf16_f32 v77, v78, v79
	v_lshl_add_u64 v[78:79], v[80:81], 1, s[64:65]
	v_mov_b32_e32 v238, v76
	v_mov_b32_e32 v239, v77
	v_lshl_add_u64 v[78:79], v[78:79], 0, v[192:193]
	s_nop 0
	v_permlane16_swap_b32 v236, v238
	v_permlane16_swap_b32 v237, v239
	global_store_dwordx4 v[78:79], v[236:239], off
	s_nop 0
	s_nop 0
	v_or_b32_e32 v72, 0x90, v72
	s_nop 0
	v_pk_fma_f32 v[62:63], v[62:63], v[222:223], v[244:245]
	v_pk_fma_f32 v[60:61], v[60:61], v[220:221], v[242:243]
	v_lshl_add_u64 v[76:77], v[84:85], 2, s[66:67]
	global_store_dwordx4 v[76:77], v[60:63], off
	s_nop 1
	s_nop 1
	v_cvt_pk_bf16_f32 v60, v60, v61
	v_cvt_pk_bf16_f32 v61, v62, v63
	v_lshl_add_u64 v[62:63], v[84:85], 1, s[64:65]
	v_mov_b32_e32 v236, v60
	v_mov_b32_e32 v237, v61
	s_nop 0
	s_nop 0
	s_nop 0
	v_pk_fma_f32 v[54:55], v[54:55], v[226:227], v[248:249]
	v_pk_fma_f32 v[52:53], v[52:53], v[224:225], v[246:247]
	v_lshl_add_u64 v[60:61], v[72:73], 2, s[66:67]
	global_store_dwordx4 v[60:61], v[52:55], off
	s_nop 1
	s_nop 1
	v_cvt_pk_bf16_f32 v52, v52, v53
	v_cvt_pk_bf16_f32 v53, v54, v55
	v_lshl_add_u64 v[54:55], v[72:73], 1, s[64:65]
	v_mov_b32_e32 v238, v52
	v_mov_b32_e32 v239, v53
	v_lshl_add_u64 v[54:55], v[54:55], 0, v[192:193]
	s_nop 0
	v_permlane16_swap_b32 v236, v238
	v_permlane16_swap_b32 v237, v239
	global_store_dwordx4 v[54:55], v[236:239], off
	ds_read_b64 v[54:55], v144 offset:9344
	v_lshlrev_b64 v[52:53], 10, v[70:71]
	s_nop 0
	s_nop 0
	v_lshl_add_u64 v[52:53], v[52:53], 0, v[128:129]
	s_waitcnt lgkmcnt(0)
	v_sub_f32_e32 v69, v69, v54
	v_sub_f32_e32 v68, v68, v54
	v_sub_f32_e32 v67, v67, v54
	v_sub_f32_e32 v66, v66, v54
	v_pk_mul_f32 v[66:67], v[54:55], v[66:67] op_sel:[1,0]
	v_pk_mul_f32 v[68:69], v[54:55], v[68:69] op_sel:[1,0]
	v_sub_f32_e32 v57, v57, v54
	v_sub_f32_e32 v56, v56, v54
	v_sub_f32_e32 v59, v59, v54
	v_sub_f32_e32 v58, v58, v54
	v_pk_mul_f32 v[56:57], v[54:55], v[56:57] op_sel:[1,0]
	v_pk_mul_f32 v[58:59], v[54:55], v[58:59] op_sel:[1,0]
	v_sub_f32_e32 v39, v39, v54
	v_sub_f32_e32 v38, v38, v54
	v_sub_f32_e32 v37, v37, v54
	v_sub_f32_e32 v36, v36, v54
	v_pk_mul_f32 v[36:37], v[54:55], v[36:37] op_sel:[1,0]
	v_pk_mul_f32 v[38:39], v[54:55], v[38:39] op_sel:[1,0]
	v_sub_f32_e32 v35, v35, v54
	v_sub_f32_e32 v34, v34, v54
	v_sub_f32_e32 v33, v33, v54
	v_sub_f32_e32 v32, v32, v54
	v_pk_mul_f32 v[32:33], v[54:55], v[32:33] op_sel:[1,0]
	v_pk_mul_f32 v[34:35], v[54:55], v[34:35] op_sel:[1,0]
	s_nop 0
	v_pk_fma_f32 v[62:63], v[214:215], v[68:69], v[230:231]
	v_pk_fma_f32 v[60:61], v[212:213], v[66:67], v[228:229]
	global_store_dwordx4 v[64:65], v[60:63], off
	s_nop 1
	s_nop 1
	v_cvt_pk_bf16_f32 v60, v60, v61
	v_cvt_pk_bf16_f32 v61, v62, v63
	v_lshl_add_u64 v[62:63], v[52:53], 1, s[64:65]
	v_mov_b32_e32 v236, v60
	v_mov_b32_e32 v237, v61
	s_nop 0
	s_nop 0
	s_nop 0
	v_pk_fma_f32 v[56:57], v[56:57], v[216:217], v[232:233]
	v_or_b32_e32 v60, 16, v52
	v_mov_b32_e32 v61, v53
	v_pk_fma_f32 v[58:59], v[58:59], v[218:219], v[234:235]
	v_lshl_add_u64 v[62:63], v[60:61], 2, s[66:67]
	global_store_dwordx4 v[62:63], v[56:59], off
	v_or_b32_e32 v64, 0x80, v52
	v_mov_b32_e32 v65, v53
	v_cvt_pk_bf16_f32 v56, v56, v57
	v_cvt_pk_bf16_f32 v57, v58, v59
	v_lshl_add_u64 v[58:59], v[60:61], 1, s[64:65]
	v_mov_b32_e32 v238, v56
	v_mov_b32_e32 v239, v57
	v_lshl_add_u64 v[58:59], v[58:59], 0, v[192:193]
	s_nop 0
	v_permlane16_swap_b32 v236, v238
	v_permlane16_swap_b32 v237, v239
	global_store_dwordx4 v[58:59], v[236:239], off
	s_nop 0
	s_nop 0
	v_or_b32_e32 v52, 0x90, v52
	s_nop 0
	v_pk_fma_f32 v[38:39], v[38:39], v[222:223], v[244:245]
	v_pk_fma_f32 v[36:37], v[36:37], v[220:221], v[242:243]
	v_lshl_add_u64 v[56:57], v[64:65], 2, s[66:67]
	global_store_dwordx4 v[56:57], v[36:39], off
	s_nop 1
	s_nop 1
	v_cvt_pk_bf16_f32 v36, v36, v37
	v_cvt_pk_bf16_f32 v37, v38, v39
	v_lshl_add_u64 v[38:39], v[64:65], 1, s[64:65]
	v_mov_b32_e32 v236, v36
	v_mov_b32_e32 v237, v37
	s_nop 0
	s_nop 0
	s_nop 0
	v_pk_fma_f32 v[34:35], v[34:35], v[226:227], v[248:249]
	v_pk_fma_f32 v[32:33], v[32:33], v[224:225], v[246:247]
	v_lshl_add_u64 v[36:37], v[52:53], 2, s[66:67]
	global_store_dwordx4 v[36:37], v[32:35], off
	s_nop 1
	s_nop 1
	v_cvt_pk_bf16_f32 v32, v32, v33
	v_cvt_pk_bf16_f32 v33, v34, v35
	v_lshl_add_u64 v[34:35], v[52:53], 1, s[64:65]
	v_mov_b32_e32 v238, v32
	v_mov_b32_e32 v239, v33
	v_lshl_add_u64 v[34:35], v[34:35], 0, v[192:193]
	s_nop 0
	v_permlane16_swap_b32 v236, v238
	v_permlane16_swap_b32 v237, v239
	global_store_dwordx4 v[34:35], v[236:239], off
	ds_read_b64 v[34:35], v144 offset:9472
	s_nop 0
	s_nop 0
	v_lshlrev_b64 v[32:33], 10, v[46:47]
	v_lshl_add_u64 v[32:33], v[32:33], 0, v[128:129]
	s_waitcnt lgkmcnt(0)
	v_sub_f32_e32 v45, v45, v34
	v_sub_f32_e32 v44, v44, v34
	v_sub_f32_e32 v43, v43, v34
	v_sub_f32_e32 v42, v42, v34
	v_pk_mul_f32 v[42:43], v[34:35], v[42:43] op_sel:[1,0]
	v_pk_mul_f32 v[44:45], v[34:35], v[44:45] op_sel:[1,0]
	v_sub_f32_e32 v29, v29, v34
	v_sub_f32_e32 v28, v28, v34
	v_sub_f32_e32 v31, v31, v34
	v_sub_f32_e32 v30, v30, v34
	v_pk_mul_f32 v[28:29], v[34:35], v[28:29] op_sel:[1,0]
	v_pk_mul_f32 v[30:31], v[34:35], v[30:31] op_sel:[1,0]
	v_sub_f32_e32 v23, v23, v34
	v_sub_f32_e32 v22, v22, v34
	v_sub_f32_e32 v21, v21, v34
	v_sub_f32_e32 v20, v20, v34
	v_pk_mul_f32 v[20:21], v[34:35], v[20:21] op_sel:[1,0]
	v_pk_mul_f32 v[22:23], v[34:35], v[22:23] op_sel:[1,0]
	v_sub_f32_e32 v19, v19, v34
	v_sub_f32_e32 v18, v18, v34
	v_sub_f32_e32 v17, v17, v34
	v_sub_f32_e32 v16, v16, v34
	v_pk_mul_f32 v[16:17], v[34:35], v[16:17] op_sel:[1,0]
	v_pk_mul_f32 v[18:19], v[34:35], v[18:19] op_sel:[1,0]
	s_nop 0
	v_pk_fma_f32 v[38:39], v[214:215], v[44:45], v[230:231]
	v_pk_fma_f32 v[36:37], v[212:213], v[42:43], v[228:229]
	global_store_dwordx4 v[40:41], v[36:39], off
	s_nop 1
	s_nop 1
	v_cvt_pk_bf16_f32 v36, v36, v37
	v_cvt_pk_bf16_f32 v37, v38, v39
	v_lshl_add_u64 v[38:39], v[32:33], 1, s[64:65]
	v_mov_b32_e32 v236, v36
	v_mov_b32_e32 v237, v37
	s_nop 0
	s_nop 0
	s_nop 0
	v_pk_fma_f32 v[28:29], v[28:29], v[216:217], v[232:233]
	v_or_b32_e32 v36, 16, v32
	v_mov_b32_e32 v37, v33
	v_pk_fma_f32 v[30:31], v[30:31], v[218:219], v[234:235]
	v_lshl_add_u64 v[38:39], v[36:37], 2, s[66:67]
	global_store_dwordx4 v[38:39], v[28:31], off
	v_or_b32_e32 v40, 0x80, v32
	v_mov_b32_e32 v41, v33
	v_cvt_pk_bf16_f32 v28, v28, v29
	v_cvt_pk_bf16_f32 v29, v30, v31
	v_lshl_add_u64 v[30:31], v[36:37], 1, s[64:65]
	v_mov_b32_e32 v238, v28
	v_mov_b32_e32 v239, v29
	v_lshl_add_u64 v[30:31], v[30:31], 0, v[192:193]
	s_nop 0
	v_permlane16_swap_b32 v236, v238
	v_permlane16_swap_b32 v237, v239
	global_store_dwordx4 v[30:31], v[236:239], off
	s_nop 0
	s_nop 0
	v_or_b32_e32 v32, 0x90, v32
	s_nop 0
	v_pk_fma_f32 v[22:23], v[22:23], v[222:223], v[244:245]
	v_pk_fma_f32 v[20:21], v[20:21], v[220:221], v[242:243]
	v_lshl_add_u64 v[28:29], v[40:41], 2, s[66:67]
	global_store_dwordx4 v[28:29], v[20:23], off
	s_nop 1
	s_nop 1
	v_cvt_pk_bf16_f32 v20, v20, v21
	v_cvt_pk_bf16_f32 v21, v22, v23
	v_lshl_add_u64 v[22:23], v[40:41], 1, s[64:65]
	v_mov_b32_e32 v236, v20
	v_mov_b32_e32 v237, v21
	s_nop 0
	s_nop 0
	s_nop 0
	v_pk_fma_f32 v[18:19], v[18:19], v[226:227], v[248:249]
	v_pk_fma_f32 v[16:17], v[16:17], v[224:225], v[246:247]
	v_lshl_add_u64 v[20:21], v[32:33], 2, s[66:67]
	global_store_dwordx4 v[20:21], v[16:19], off
	s_nop 1
	s_nop 1
	v_cvt_pk_bf16_f32 v16, v16, v17
	v_cvt_pk_bf16_f32 v17, v18, v19
	v_lshl_add_u64 v[18:19], v[32:33], 1, s[64:65]
	v_mov_b32_e32 v238, v16
	v_mov_b32_e32 v239, v17
	v_lshl_add_u64 v[18:19], v[18:19], 0, v[192:193]
	s_nop 0
	v_permlane16_swap_b32 v236, v238
	v_permlane16_swap_b32 v237, v239
	global_store_dwordx4 v[18:19], v[236:239], off
	ds_read_b64 v[18:19], v144 offset:9600
	v_lshlrev_b64 v[16:17], 10, v[26:27]
	s_nop 0
	s_nop 0
	v_lshl_add_u64 v[16:17], v[16:17], 0, v[128:129]
	s_waitcnt lgkmcnt(0)
	v_sub_f32_e32 v15, v15, v18
	v_sub_f32_e32 v14, v14, v18
	v_sub_f32_e32 v13, v13, v18
	v_sub_f32_e32 v12, v12, v18
	v_pk_mul_f32 v[12:13], v[18:19], v[12:13] op_sel:[1,0]
	v_pk_mul_f32 v[14:15], v[18:19], v[14:15] op_sel:[1,0]
	v_sub_f32_e32 v9, v9, v18
	v_sub_f32_e32 v8, v8, v18
	v_sub_f32_e32 v11, v11, v18
	v_sub_f32_e32 v10, v10, v18
	v_pk_mul_f32 v[8:9], v[18:19], v[8:9] op_sel:[1,0]
	v_pk_mul_f32 v[10:11], v[18:19], v[10:11] op_sel:[1,0]
	v_sub_f32_e32 v7, v7, v18
	v_sub_f32_e32 v6, v6, v18
	v_sub_f32_e32 v5, v5, v18
	v_sub_f32_e32 v4, v4, v18
	v_pk_mul_f32 v[4:5], v[18:19], v[4:5] op_sel:[1,0]
	v_pk_mul_f32 v[6:7], v[18:19], v[6:7] op_sel:[1,0]
	v_sub_f32_e32 v3, v3, v18
	v_sub_f32_e32 v2, v2, v18
	v_sub_f32_e32 v1, v1, v18
	v_sub_f32_e32 v0, v0, v18
	v_pk_mul_f32 v[0:1], v[18:19], v[0:1] op_sel:[1,0]
	v_pk_mul_f32 v[2:3], v[18:19], v[2:3] op_sel:[1,0]
	s_nop 0
	v_pk_fma_f32 v[14:15], v[214:215], v[14:15], v[230:231]
	v_pk_fma_f32 v[12:13], v[212:213], v[12:13], v[228:229]
	global_store_dwordx4 v[24:25], v[12:15], off
	s_nop 1
	s_nop 1
	v_cvt_pk_bf16_f32 v12, v12, v13
	v_cvt_pk_bf16_f32 v13, v14, v15
	v_lshl_add_u64 v[14:15], v[16:17], 1, s[64:65]
	v_mov_b32_e32 v236, v12
	v_mov_b32_e32 v237, v13
	s_nop 0
	s_nop 0
	s_nop 0
	v_pk_fma_f32 v[8:9], v[8:9], v[216:217], v[232:233]
	v_or_b32_e32 v12, 16, v16
	v_mov_b32_e32 v13, v17
	v_pk_fma_f32 v[10:11], v[10:11], v[218:219], v[234:235]
	v_lshl_add_u64 v[14:15], v[12:13], 2, s[66:67]
	global_store_dwordx4 v[14:15], v[8:11], off
	v_or_b32_e32 v20, 0x80, v16
	v_mov_b32_e32 v21, v17
	v_cvt_pk_bf16_f32 v8, v8, v9
	v_cvt_pk_bf16_f32 v9, v10, v11
	v_lshl_add_u64 v[10:11], v[12:13], 1, s[64:65]
	v_mov_b32_e32 v238, v8
	v_mov_b32_e32 v239, v9
	v_lshl_add_u64 v[10:11], v[10:11], 0, v[192:193]
	s_nop 0
	v_permlane16_swap_b32 v236, v238
	v_permlane16_swap_b32 v237, v239
	global_store_dwordx4 v[10:11], v[236:239], off
	s_nop 0
	s_nop 0
	v_or_b32_e32 v16, 0x90, v16
	s_nop 0
	v_pk_fma_f32 v[6:7], v[6:7], v[222:223], v[244:245]
	v_pk_fma_f32 v[4:5], v[4:5], v[220:221], v[242:243]
	v_lshl_add_u64 v[8:9], v[20:21], 2, s[66:67]
	global_store_dwordx4 v[8:9], v[4:7], off
	s_nop 1
	s_nop 1
	v_cvt_pk_bf16_f32 v4, v4, v5
	v_cvt_pk_bf16_f32 v5, v6, v7
	v_lshl_add_u64 v[6:7], v[20:21], 1, s[64:65]
	v_mov_b32_e32 v236, v4
	v_mov_b32_e32 v237, v5
	s_nop 0
	s_nop 0
	s_nop 0
	v_pk_fma_f32 v[2:3], v[2:3], v[226:227], v[248:249]
	v_pk_fma_f32 v[0:1], v[0:1], v[224:225], v[246:247]
	v_lshl_add_u64 v[4:5], v[16:17], 2, s[66:67]
	global_store_dwordx4 v[4:5], v[0:3], off
	s_nop 1
	s_nop 1
	v_cvt_pk_bf16_f32 v0, v0, v1
	v_cvt_pk_bf16_f32 v1, v2, v3
	v_lshl_add_u64 v[2:3], v[16:17], 1, s[64:65]
	v_mov_b32_e32 v238, v0
	v_mov_b32_e32 v239, v1
	v_lshl_add_u64 v[2:3], v[2:3], 0, v[192:193]
	s_nop 0
	v_permlane16_swap_b32 v236, v238
	v_permlane16_swap_b32 v237, v239
	global_store_dwordx4 v[2:3], v[236:239], off

.LBB0_209:
	s_andn2_saveexec_b64 s[54:55], s[80:81]
	v_fma_f32 v82, v81, s92, 0.5
	v_fma_f32 v82, -v81, v82, 1.0
	v_mul_f32_e32 v170, v81, v82
	s_or_b64 exec, exec, s[54:55]
	v_lshl_add_u64 v[138:139], s[74:75], 0, v[118:119]
	v_add_co_u32_e32 v84, vcc, 0x13094000, v138
	v_max_f32_e64 v76, -v76, -v76
	s_nop 0
	v_addc_co_u32_e32 v85, vcc, 0, v139, vcc
	global_load_dwordx2 v[168:169], v[84:85], off offset:2560
	v_add_co_u32_e32 v84, vcc, 0x13098000, v138
	v_max_f32_e32 v76, 0, v76
	s_nop 0
	v_addc_co_u32_e32 v85, vcc, 0, v139, vcc
	global_load_dwordx2 v[164:165], v[84:85], off offset:3072
	v_add_co_u32_e32 v84, vcc, 0x1309c000, v138
	v_add_f32_e32 v185, v76, v80
	s_nop 0
	v_addc_co_u32_e32 v85, vcc, 0, v139, vcc
	v_add_co_u32_e32 v140, vcc, 0x130a1000, v138
	global_load_dwordx2 v[162:163], v[84:85], off offset:3584
	s_nop 0
	v_addc_co_u32_e32 v141, vcc, 0, v139, vcc
	global_load_dwordx2 v[166:167], v[140:141], off
	global_load_dwordx2 v[142:143], v[140:141], off offset:2048
	v_add_co_u32_e32 v140, vcc, s97, v138
	v_mfma_f32_16x16x32_bf16 v[84:87], v[72:75], v[0:3], 0
	s_nop 0
	v_addc_co_u32_e32 v141, vcc, 0, v139, vcc
	global_load_dwordx2 v[140:141], v[140:141], off
	s_nop 0
	s_nop 0
	s_nop 0
	s_mov_b32 s100, 0x130e3000
	s_mov_b32 s101, 0
	v_lshl_add_u64 v[248:249], v[138:139], 0, s[100:101]
	global_load_dwordx2 v[216:217], v[248:249], off
	s_mov_b32 s100, 0x130e3800
	s_mov_b32 s101, 0
	v_lshl_add_u64 v[248:249], v[138:139], 0, s[100:101]
	global_load_dwordx2 v[218:219], v[248:249], off
	s_mov_b32 s100, 0x130e6000
	s_mov_b32 s101, 0
	v_lshl_add_u64 v[248:249], v[138:139], 0, s[100:101]
	global_load_dwordx2 v[220:221], v[248:249], off
	s_nop 0
	s_nop 0
	s_nop 0
	s_mov_b32 s100, 0x13125000
	s_mov_b32 s101, 0
	v_lshl_add_u64 v[248:249], v[138:139], 0, s[100:101]
	global_load_dwordx2 v[228:229], v[248:249], off
	s_mov_b32 s100, 0x13125800
	s_mov_b32 s101, 0
	v_lshl_add_u64 v[248:249], v[138:139], 0, s[100:101]
	global_load_dwordx2 v[230:231], v[248:249], off
	s_mov_b32 s100, 0x13128000
	s_mov_b32 s101, 0
	v_lshl_add_u64 v[248:249], v[138:139], 0, s[100:101]
	global_load_dwordx2 v[232:233], v[248:249], off
	s_nop 0
	s_nop 0
	s_nop 0
	s_mov_b32 s100, 0x13167000
	s_mov_b32 s101, 0
	v_lshl_add_u64 v[248:249], v[138:139], 0, s[100:101]
	global_load_dwordx2 v[242:243], v[248:249], off
	s_mov_b32 s100, 0x13167800
	s_mov_b32 s101, 0
	v_lshl_add_u64 v[248:249], v[138:139], 0, s[100:101]
	global_load_dwordx2 v[244:245], v[248:249], off
	s_mov_b32 s100, 0x1316a000
	s_mov_b32 s101, 0
	v_lshl_add_u64 v[248:249], v[138:139], 0, s[100:101]
	global_load_dwordx2 v[246:247], v[248:249], off
	v_mfma_f32_16x16x32_bf16 v[84:87], v[60:63], v[16:19], v[84:87]
	v_mfma_f32_16x16x32_bf16 v[80:83], v[68:71], v[0:3], 0
	v_mfma_f32_16x16x32_bf16 v[80:83], v[64:67], v[16:19], v[80:83]
	s_nop 0
	s_nop 4
	s_nop 0
	s_waitcnt vmcnt(16)
	v_add_f32_e32 v76, v56, v84
	v_mul_f32_e32 v76, 0xbfb8aa3b, v76
	v_exp_f32_e32 v76, v76
	s_nop 0
	v_add_f32_e32 v76, 1.0, v76
	v_rcp_f32_e32 v76, v76
	s_nop 0
	v_mul_f32_e32 v76, 0xc1000000, v76
	v_mul_f32_e32 v76, v185, v76
	v_add_f32_e32 v171, v76, v76
	v_cmp_nlt_f32_e32 vcc, s93, v171
	s_and_saveexec_b64 s[54:55], vcc
	s_xor_b64 s[54:55], exec, s[54:55]
	v_mul_f32_e32 v84, 0x3fb8aa3b, v171
	v_exp_f32_e32 v84, v84
	s_nop 0
	v_sub_f32_e32 v84, 1.0, v84
	s_andn2_saveexec_b64 s[54:55], s[54:55]
	v_fma_f32 v84, v171, s94, 0.5
	v_fma_f32 v84, v171, v84, 1.0
	v_mul_f32_e64 v84, v84, -v171
	s_or_b64 exec, exec, s[54:55]
	v_add_f32_e32 v85, v57, v85
	v_mul_f32_e32 v85, 0xbfb8aa3b, v85
	v_exp_f32_e32 v85, v85
	v_max_f32_e64 v77, -v77, -v77
	v_max_f32_e32 v77, 0, v77
	v_add_f32_e32 v186, v77, v144
	v_add_f32_e32 v85, 1.0, v85
	v_rcp_f32_e32 v85, v85
	s_nop 0
	v_mul_f32_e32 v77, 0xc1000000, v85
	v_mul_f32_e32 v77, v186, v77
	v_add_f32_e32 v144, v77, v77
	v_cmp_nlt_f32_e32 vcc, s93, v144
	s_and_saveexec_b64 s[54:55], vcc
	s_xor_b64 s[54:55], exec, s[54:55]
	v_mul_f32_e32 v85, 0x3fb8aa3b, v144
	v_exp_f32_e32 v85, v85
	s_nop 0
	v_sub_f32_e32 v85, 1.0, v85
	s_andn2_saveexec_b64 s[54:55], s[54:55]
	v_fma_f32 v85, v144, s94, 0.5
	v_fma_f32 v85, v144, v85, 1.0
	v_mul_f32_e64 v85, v85, -v144
	s_or_b64 exec, exec, s[54:55]
	v_add_f32_e32 v86, v58, v86
	v_mul_f32_e32 v86, 0xbfb8aa3b, v86
	v_exp_f32_e32 v86, v86
	v_max_f32_e64 v78, -v78, -v78
	v_max_f32_e32 v78, 0, v78
	v_add_f32_e32 v187, v78, v147
	v_add_f32_e32 v86, 1.0, v86
	v_rcp_f32_e32 v86, v86
	s_nop 0
	v_mul_f32_e32 v78, 0xc1000000, v86
	v_mul_f32_e32 v78, v187, v78
	v_add_f32_e32 v144, v78, v78
	v_cmp_nlt_f32_e32 vcc, s93, v144
	s_and_saveexec_b64 s[54:55], vcc
	s_xor_b64 s[54:55], exec, s[54:55]
	v_mul_f32_e32 v86, 0x3fb8aa3b, v144
	v_exp_f32_e32 v86, v86
	s_nop 0
	v_sub_f32_e32 v86, 1.0, v86
	s_andn2_saveexec_b64 s[54:55], s[54:55]
	v_fma_f32 v86, v144, s94, 0.5
	v_fma_f32 v86, v144, v86, 1.0
	v_mul_f32_e64 v86, v86, -v144
	s_or_b64 exec, exec, s[54:55]
	v_add_f32_e32 v87, v59, v87
	v_mul_f32_e32 v87, 0xbfb8aa3b, v87
	v_exp_f32_e32 v87, v87
	v_max_f32_e64 v79, -v79, -v79
	v_max_f32_e32 v79, 0, v79
	v_add_f32_e32 v188, v79, v170
	v_add_f32_e32 v87, 1.0, v87
	v_rcp_f32_e32 v87, v87
	s_nop 0
	v_mul_f32_e32 v79, 0xc1000000, v87
	v_mul_f32_e32 v87, v188, v79
	v_add_f32_e32 v144, v87, v87
	v_cmp_nlt_f32_e32 vcc, s93, v144
	s_and_saveexec_b64 s[54:55], vcc
	s_xor_b64 s[54:55], exec, s[54:55]
	v_mul_f32_e32 v79, 0x3fb8aa3b, v144
	v_exp_f32_e32 v79, v79
	s_nop 0
	v_sub_f32_e32 v79, 1.0, v79
	s_andn2_saveexec_b64 s[54:55], s[54:55]
	v_fma_f32 v79, v144, s94, 0.5
	v_fma_f32 v79, v144, v79, 1.0
	v_mul_f32_e64 v79, v79, -v144
	s_or_b64 exec, exec, s[54:55]
	s_nop 0
	s_nop 0
	s_waitcnt vmcnt(15)
	v_add_f32_e32 v82, v34, v82
	v_mul_f32_e32 v82, 0xbfb8aa3b, v82
	v_exp_f32_e32 v82, v82
	v_add_f32_e32 v81, v33, v81
	s_nop 0
	s_nop 0
	s_waitcnt vmcnt(14)
	v_cndmask_b32_e64 v144, v169, 0, s[28:29]
	v_cndmask_b32_e64 v147, v168, 0, s[28:29]
	v_add_f32_e32 v82, 1.0, v82
	v_add_f32_e32 v83, v35, v83
	v_mul_f32_e32 v81, 0xbfb8aa3b, v81
	v_lshlrev_b32_e32 v152, 16, v147
	v_and_b32_e32 v153, 0xffff0000, v147
	v_lshlrev_b32_e32 v168, 16, v144
	v_and_b32_e32 v169, 0xffff0000, v144
	s_nop 0
	s_nop 0
	s_waitcnt vmcnt(13)
	v_cndmask_b32_e64 v144, v165, 0, s[30:31]
	v_cndmask_b32_e64 v147, v164, 0, s[30:31]
	v_rcp_f32_e32 v82, v82
	v_sqrt_f32_e32 v86, v86
	v_mul_f32_e32 v83, 0xbfb8aa3b, v83
	v_exp_f32_e32 v81, v81
	v_pk_fma_f32 v[168:169], v[50:51], v[168:169], v[54:55]
	v_pk_fma_f32 v[152:153], v[48:49], v[152:153], v[52:53]
	v_lshlrev_b32_e32 v164, 16, v147
	v_and_b32_e32 v165, 0xffff0000, v147
	v_lshlrev_b32_e32 v170, 16, v144
	v_and_b32_e32 v171, 0xffff0000, v144
	s_nop 0
	s_nop 0
	s_waitcnt vmcnt(12)
	v_cndmask_b32_e64 v144, v163, 0, s[34:35]
	v_cndmask_b32_e64 v147, v162, 0, s[34:35]
	v_exp_f32_e32 v83, v83
	v_pk_fma_f32 v[152:153], v[44:45], v[164:165], v[152:153]
	v_pk_fma_f32 v[164:165], v[46:47], v[170:171], v[168:169]
	v_lshlrev_b32_e32 v162, 16, v147
	v_and_b32_e32 v163, 0xffff0000, v147
	v_lshlrev_b32_e32 v168, 16, v144
	v_and_b32_e32 v169, 0xffff0000, v144
	s_nop 0
	s_nop 0
	s_waitcnt vmcnt(11)
	v_mov_b32_dpp v194, v166 row_shl:13 row_mask:0xf bank_mask:0xf
	v_mov_b32_dpp v195, v167 row_shl:13 row_mask:0xf bank_mask:0xf
	v_mov_b32_dpp v212, v166 row_shl:14 row_mask:0xf bank_mask:0xf
	v_mov_b32_dpp v213, v167 row_shl:14 row_mask:0xf bank_mask:0xf
	v_mov_b32_dpp v214, v166 row_shl:15 row_mask:0xf bank_mask:0xf
	v_mov_b32_dpp v215, v167 row_shl:15 row_mask:0xf bank_mask:0xf
	v_cndmask_b32_e64 v144, v167, 0, s[64:65]
	v_cndmask_b32_e64 v147, v166, 0, s[64:65]
	v_add_f32_e32 v80, v32, v80
	v_pk_fma_f32 v[164:165], v[42:43], v[168:169], v[164:165]
	v_pk_fma_f32 v[152:153], v[40:41], v[162:163], v[152:153]
	v_lshlrev_b32_e32 v162, 16, v147
	v_and_b32_e32 v163, 0xffff0000, v147
	v_lshlrev_b32_e32 v166, 16, v144
	v_and_b32_e32 v167, 0xffff0000, v144
	v_mul_f32_e32 v80, 0xbfb8aa3b, v80
	v_pk_fma_f32 v[152:153], v[36:37], v[162:163], v[152:153]
	v_pk_fma_f32 v[162:163], v[38:39], v[166:167], v[164:165]
	v_mul_f32_e32 v82, v82, v86
	v_add_f32_e32 v81, 1.0, v81
	v_exp_f32_e32 v80, v80
	v_mul_f32_e32 v162, v162, v82
	v_add_f32_e32 v82, 1.0, v83
	v_rcp_f32_e32 v81, v81
	v_sqrt_f32_e32 v83, v85
	v_add_f32_e32 v80, 1.0, v80
	v_rcp_f32_e32 v80, v80
	v_mul_f32_e32 v76, 0x3fb8aa3b, v76
	v_mul_f32_e32 v81, v81, v83
	v_sqrt_f32_e32 v83, v84
	v_exp_f32_e32 v76, v76
	v_mul_f32_e32 v77, 0x3fb8aa3b, v77
	v_mul_f32_e32 v85, 0x3fb8aa3b, v87
	v_mul_f32_e32 v80, v80, v83
	v_mul_f32_e32 v87, v152, v80
	v_exp_f32_e32 v77, v77
	v_mov_b32_e32 v80, 0
	v_rcp_f32_e32 v82, v82
	v_mul_f32_e32 v78, 0x3fb8aa3b, v78
	v_sqrt_f32_e32 v79, v79
	v_mov_b32_dpp v80, v87 row_shr:1 row_mask:0xf bank_mask:0xf
	v_mul_f32_e32 v153, v153, v81
	v_exp_f32_e32 v78, v78
	v_fmac_f32_e32 v87, v76, v80
	v_mov_b32_e32 v80, 0
	v_exp_f32_e32 v85, v85
	v_mul_f32_e32 v79, v82, v79
	v_mov_b32_dpp v80, v153 row_shr:1 row_mask:0xf bank_mask:0xf
	v_fmac_f32_e32 v153, v77, v80
	v_mov_b32_e32 v80, 0
	v_mul_f32_e32 v152, v163, v79
	v_mov_b32_e32 v79, 1.0
	v_mov_b32_dpp v80, v162 row_shr:1 row_mask:0xf bank_mask:0xf
	v_fmac_f32_e32 v162, v78, v80
	v_mov_b32_e32 v80, 0
	v_mov_b32_dpp v79, v76 row_shr:1 row_mask:0xf bank_mask:0xf
	v_mul_f32_e32 v76, v76, v79
	v_mov_b32_dpp v80, v152 row_shr:1 row_mask:0xf bank_mask:0xf
	v_mov_b32_e32 v79, 1.0
	v_fmac_f32_e32 v152, v85, v80
	v_mov_b32_e32 v80, 1.0
	v_mov_b32_e32 v81, 0
	v_mov_b32_dpp v79, v77 row_shr:1 row_mask:0xf bank_mask:0xf
	v_mov_b32_dpp v80, v76 row_shr:2 row_mask:0xf bank_mask:0xf
	v_mov_b32_dpp v81, v87 row_shr:2 row_mask:0xf bank_mask:0xf
	v_mul_f32_e32 v77, v77, v79
	v_mov_b32_e32 v79, 1.0
	v_fmac_f32_e32 v87, v76, v81
	v_mul_f32_e32 v147, v76, v80
	v_mov_b32_e32 v76, 1.0
	v_mov_b32_dpp v79, v78 row_shr:1 row_mask:0xf bank_mask:0xf
	v_mul_f32_e32 v78, v78, v79
	v_mov_b32_dpp v76, v77 row_shr:2 row_mask:0xf bank_mask:0xf
	v_mov_b32_e32 v79, 1.0
	v_mul_f32_e32 v163, v77, v76
	v_mov_b32_e32 v76, 1.0
	v_mov_b32_dpp v79, v85 row_shr:1 row_mask:0xf bank_mask:0xf
	v_mul_f32_e32 v79, v85, v79
	v_mov_b32_dpp v76, v78 row_shr:2 row_mask:0xf bank_mask:0xf
	v_mul_f32_e32 v164, v78, v76
	v_mov_b32_e32 v76, 1.0
	v_mov_b32_e32 v80, 0
	s_nop 0
	s_nop 0
	s_waitcnt vmcnt(9)
	v_lshlrev_b32_e32 v84, 16, v140
	v_mov_b32_dpp v76, v79 row_shr:2 row_mask:0xf bank_mask:0xf
	v_mul_f32_e32 v165, v79, v76
	v_mov_b32_e32 v76, 0
	v_mov_b32_dpp v80, v153 row_shr:2 row_mask:0xf bank_mask:0xf
	v_fmac_f32_e32 v153, v77, v80
	v_mov_b32_dpp v76, v87 row_shr:4 row_mask:0xf bank_mask:0xf
	v_mov_b32_e32 v77, 0
	v_fmac_f32_e32 v87, v147, v76
	v_mov_b32_e32 v76, 0
	v_mov_b32_dpp v77, v162 row_shr:2 row_mask:0xf bank_mask:0xf
	v_fmac_f32_e32 v162, v78, v77
	v_mov_b32_dpp v76, v153 row_shr:4 row_mask:0xf bank_mask:0xf
	v_mov_b32_e32 v77, 0
	v_fmac_f32_e32 v153, v163, v76
	v_mov_b32_e32 v76, 0
	v_mov_b32_dpp v77, v152 row_shr:2 row_mask:0xf bank_mask:0xf
	v_fmac_f32_e32 v152, v79, v77
	v_mov_b32_dpp v76, v162 row_shr:4 row_mask:0xf bank_mask:0xf
	v_fmac_f32_e32 v162, v164, v76
	v_mov_b32_e32 v76, 0
	v_mov_b32_e32 v77, 1.0
	v_mul_f32_e32 v84, 0xbfb8aa3b, v84
	v_mov_b32_dpp v76, v152 row_shr:4 row_mask:0xf bank_mask:0xf
	v_mov_b32_dpp v77, v147 row_shr:4 row_mask:0xf bank_mask:0xf
	v_fmac_f32_e32 v152, v165, v76
	v_lshlrev_b32_e32 v76, 16, v142
	v_and_b32_e32 v78, 0xffff0000, v142
	v_and_b32_e32 v142, 0xffff0000, v140
	v_exp_f32_e32 v140, v84
	v_pk_mul_f32 v[84:85], v[146:147], v[76:77]
	v_mul_f32_e32 v77, 0x3d372713, v76
	v_mul_f32_e32 v77, v77, v76
	v_fmac_f32_e32 v76, v77, v76
	v_mul_f32_e32 v76, 0x3f4c422a, v76
	v_add_f32_e32 v76, v76, v76
	v_mul_f32_e32 v76, 0x3fb8aa3b, v76
	v_exp_f32_e32 v76, v76
	v_add_f32_e32 v77, 1.0, v140
	v_rcp_f32_e32 v144, v77
	v_mov_b32_e32 v77, 1.0
	v_add_f32_e32 v76, 1.0, v76
	v_rcp_f32_e32 v76, v76
	v_mov_b32_e32 v86, 0
	v_mov_b32_dpp v77, v85 row_shr:8 row_mask:0xf bank_mask:0xf
	v_mov_b32_e32 v79, 1.0
	v_fma_f32 v76, v76, -2.0, 1.0
	v_add_f32_e32 v76, 1.0, v76
	v_mov_b32_dpp v86, v87 row_shr:8 row_mask:0xf bank_mask:0xf
	v_pk_mul_f32 v[76:77], v[84:85], v[76:77]
	v_lshlrev_b32_e32 v169, 16, v141
	v_and_b32_e32 v170, 0xffff0000, v141
	v_fmac_f32_e32 v87, v85, v86
	v_pk_mul_f32 v[140:141], v[144:145], v[76:77]
	v_mov_b32_dpp v79, v163 row_shr:4 row_mask:0xf bank_mask:0xf
	v_add_f32_e32 v76, v141, v87
	v_mov_b32_e32 v147, v163
	v_lshlrev_b32_e32 v80, 16, v143
	v_and_b32_e32 v82, 0xffff0000, v143
	v_mul_f32_e32 v171, v140, v76
	v_mul_f32_e32 v76, 0xbfb8aa3b, v142
	v_pk_mul_f32 v[142:143], v[146:147], v[78:79]
	v_mul_f32_e32 v79, 0x3d372713, v78
	v_mul_f32_e32 v79, v79, v78
	v_fmac_f32_e32 v78, v79, v78
	v_mul_f32_e32 v78, 0x3f4c422a, v78
	v_add_f32_e32 v78, v78, v78
	v_exp_f32_e32 v76, v76
	v_mul_f32_e32 v78, 0x3fb8aa3b, v78
	v_exp_f32_e32 v78, v78
	ds_bpermute_b32 v86, v184, v77
	v_add_f32_e32 v76, 1.0, v76
	v_rcp_f32_e32 v144, v76
	v_add_f32_e32 v76, 1.0, v78
	v_rcp_f32_e32 v76, v76
	v_mul_f32_e32 v163, v140, v77
	v_mov_b32_e32 v77, 1.0
	v_mov_b32_e32 v166, 0
	v_fma_f32 v76, v76, -2.0, 1.0
	v_mov_b32_dpp v77, v143 row_shr:8 row_mask:0xf bank_mask:0xf
	v_add_f32_e32 v76, 1.0, v76
	v_mov_b32_dpp v166, v153 row_shr:8 row_mask:0xf bank_mask:0xf
	v_pk_mul_f32 v[76:77], v[142:143], v[76:77]
	v_fmac_f32_e32 v153, v143, v166
	v_pk_mul_f32 v[78:79], v[144:145], v[76:77]
	v_mov_b32_e32 v81, 1.0
	v_add_f32_e32 v76, v79, v153
	v_mul_f32_e32 v79, 0x3d372713, v80
	v_mov_b32_dpp v81, v164 row_shr:4 row_mask:0xf bank_mask:0xf
	v_mov_b32_e32 v147, v164
	v_mul_f32_e32 v79, v79, v80
	v_pk_mul_f32 v[140:141], v[146:147], v[80:81]
	v_fmac_f32_e32 v80, v79, v80
	v_mul_f32_e32 v79, 0x3f4c422a, v80
	ds_bpermute_b32 v85, v184, v153
	v_mul_f32_e32 v153, v78, v76
	v_mul_f32_e32 v76, 0xbfb8aa3b, v169
	v_add_f32_e32 v79, v79, v79
	v_exp_f32_e32 v76, v76
	v_mul_f32_e32 v79, 0x3fb8aa3b, v79
	v_exp_f32_e32 v79, v79
	ds_bpermute_b32 v84, v184, v87
	v_add_f32_e32 v76, 1.0, v76
	v_rcp_f32_e32 v144, v76
	v_add_f32_e32 v76, 1.0, v79
	v_rcp_f32_e32 v76, v76
	ds_bpermute_b32 v87, v184, v77
	v_mul_f32_e32 v164, v78, v77
	v_mov_b32_e32 v77, 1.0
	v_fma_f32 v76, v76, -2.0, 1.0
	v_mov_b32_e32 v167, 0
	v_mov_b32_dpp v77, v141 row_shr:8 row_mask:0xf bank_mask:0xf
	v_add_f32_e32 v76, 1.0, v76
	v_mov_b32_dpp v167, v162 row_shr:8 row_mask:0xf bank_mask:0xf
	v_pk_mul_f32 v[76:77], v[140:141], v[76:77]
	v_fmac_f32_e32 v162, v141, v167
	v_pk_mul_f32 v[78:79], v[144:145], v[76:77]
	v_mov_b32_e32 v83, 1.0
	v_add_f32_e32 v76, v79, v162
	v_mul_f32_e32 v79, 0x3d372713, v82
	v_mov_b32_dpp v83, v165 row_shr:4 row_mask:0xf bank_mask:0xf
	v_mov_b32_e32 v147, v165
	v_mul_f32_e32 v79, v79, v82
	v_pk_mul_f32 v[80:81], v[146:147], v[82:83]
	v_fmac_f32_e32 v82, v79, v82
	v_mul_f32_e32 v79, 0x3f4c422a, v82
	ds_bpermute_b32 v142, v184, v162
	v_mul_f32_e32 v162, v78, v76
	v_mul_f32_e32 v76, 0xbfb8aa3b, v170
	v_add_f32_e32 v79, v79, v79
	v_exp_f32_e32 v76, v76
	v_mul_f32_e32 v79, 0x3fb8aa3b, v79
	v_exp_f32_e32 v79, v79
	ds_bpermute_b32 v140, v184, v77
	v_add_f32_e32 v76, 1.0, v76
	v_rcp_f32_e32 v144, v76
	v_add_f32_e32 v76, 1.0, v79
	v_rcp_f32_e32 v76, v76
	v_mul_f32_e32 v82, v78, v77
	v_mov_b32_e32 v77, 1.0
	v_mov_b32_e32 v168, 0
	v_fma_f32 v76, v76, -2.0, 1.0
	v_mov_b32_dpp v77, v81 row_shr:8 row_mask:0xf bank_mask:0xf
	v_add_f32_e32 v76, 1.0, v76
	v_mov_b32_dpp v168, v152 row_shr:8 row_mask:0xf bank_mask:0xf
	v_pk_mul_f32 v[76:77], v[80:81], v[76:77]
	v_fmac_f32_e32 v152, v81, v168
	v_pk_mul_f32 v[78:79], v[144:145], v[76:77]
	ds_bpermute_b32 v141, v184, v77
	v_add_f32_e32 v76, v79, v152
	v_mul_f32_e32 v79, v78, v76
	ds_bpermute_b32 v143, v184, v152
	v_mul_f32_e32 v83, v78, v77
	v_cvt_pk_bf16_f32 v77, v162, v79
	v_lshl_add_u64 v[78:79], s[74:75], 0, v[134:135]
	v_add_co_u32_e32 v80, vcc, s95, v78
	v_cvt_pk_bf16_f32 v76, v171, v153
	s_nop 1
	v_addc_co_u32_e32 v81, vcc, 0, v79, vcc
	v_add_co_u32_e32 v78, vcc, s96, v78
	global_store_dwordx2 v[80:81], v[76:77], off
	s_nop 0
	v_addc_co_u32_e32 v79, vcc, 0, v79, vcc
	v_cvt_pk_bf16_f32 v76, v163, v164
	v_cvt_pk_bf16_f32 v77, v82, v83
	global_store_dwordx2 v[78:79], v[76:77], off
	s_mov_b32 s54, 0x130d6000
	v_add_co_u32_e32 v80, vcc, s54, v138
	s_mov_b32 s54, 0x130da000
	s_nop 0
	v_addc_co_u32_e32 v81, vcc, 0, v139, vcc
	s_nop 0
	v_add_co_u32_e32 v80, vcc, s54, v138
	s_mov_b32 s54, 0x130de000
	s_nop 0
	v_addc_co_u32_e32 v81, vcc, 0, v139, vcc
	s_nop 0
	v_add_co_u32_e32 v80, vcc, s54, v138
	s_mov_b32 s54, 0x130e3000
	s_nop 0
	v_addc_co_u32_e32 v81, vcc, 0, v139, vcc
	v_add_co_u32_e32 v152, vcc, s54, v138
	s_nop 0
	s_nop 0
	v_addc_co_u32_e32 v153, vcc, 0, v139, vcc
	s_nop 0
	s_nop 0
	v_add_co_u32_e32 v152, vcc, 0x130e6000, v138
	v_mfma_f32_16x16x32_bf16 v[80:83], v[72:75], v[4:7], 0
	s_nop 0
	v_addc_co_u32_e32 v153, vcc, 0, v139, vcc
	s_nop 0
	v_mfma_f32_16x16x32_bf16 v[80:83], v[60:63], v[20:23], v[80:83]
	v_mfma_f32_16x16x32_bf16 v[76:79], v[68:71], v[4:7], 0
	v_mfma_f32_16x16x32_bf16 v[76:79], v[64:67], v[20:23], v[76:79]
	s_nop 5
	v_add_f32_e32 v80, v56, v80
	v_mul_f32_e32 v80, 0xbfb8aa3b, v80
	v_exp_f32_e32 v80, v80
	s_nop 0
	v_add_f32_e32 v80, 1.0, v80
	v_rcp_f32_e32 v80, v80
	s_nop 0
	v_mul_f32_e32 v80, 0xc1000000, v80
	v_mul_f32_e32 v80, v185, v80
	v_add_f32_e32 v147, v80, v80
	v_cmp_nlt_f32_e32 vcc, s93, v147
	s_and_saveexec_b64 s[54:55], vcc
	s_xor_b64 s[54:55], exec, s[54:55]
	v_mul_f32_e32 v144, 0x3fb8aa3b, v147
	v_exp_f32_e32 v144, v144
	s_nop 0
	v_sub_f32_e32 v144, 1.0, v144
	s_andn2_saveexec_b64 s[54:55], s[54:55]
	v_fma_f32 v144, v147, s94, 0.5
	v_fma_f32 v144, v147, v144, 1.0
	v_mul_f32_e64 v144, v144, -v147
	s_or_b64 exec, exec, s[54:55]
	v_add_f32_e32 v81, v57, v81
	v_mul_f32_e32 v81, 0xbfb8aa3b, v81
	v_exp_f32_e32 v81, v81
	s_nop 0
	v_add_f32_e32 v81, 1.0, v81
	v_rcp_f32_e32 v81, v81
	s_nop 0
	v_mul_f32_e32 v81, 0xc1000000, v81
	v_mul_f32_e32 v81, v186, v81
	v_add_f32_e32 v174, v81, v81
	v_cmp_nlt_f32_e32 vcc, s93, v174
	s_and_saveexec_b64 s[54:55], vcc
	s_xor_b64 s[54:55], exec, s[54:55]
	v_mul_f32_e32 v147, 0x3fb8aa3b, v174
	v_exp_f32_e32 v147, v147
	s_nop 0
	v_sub_f32_e32 v147, 1.0, v147
	s_andn2_saveexec_b64 s[54:55], s[54:55]
	v_fma_f32 v147, v174, s94, 0.5
	v_fma_f32 v147, v174, v147, 1.0
	v_mul_f32_e64 v147, v147, -v174
	s_or_b64 exec, exec, s[54:55]
	v_add_f32_e32 v82, v58, v82
	v_mul_f32_e32 v82, 0xbfb8aa3b, v82
	v_exp_f32_e32 v82, v82
	s_nop 0
	v_add_f32_e32 v82, 1.0, v82
	v_rcp_f32_e32 v82, v82
	s_nop 0
	v_mul_f32_e32 v82, 0xc1000000, v82
	v_mul_f32_e32 v82, v187, v82
	v_add_f32_e32 v175, v82, v82
	v_cmp_nlt_f32_e32 vcc, s93, v175
	s_and_saveexec_b64 s[54:55], vcc
	s_xor_b64 s[54:55], exec, s[54:55]
	v_mul_f32_e32 v152, 0x3fb8aa3b, v175
	v_exp_f32_e32 v152, v152
	s_nop 0
	v_sub_f32_e32 v174, 1.0, v152
	s_andn2_saveexec_b64 s[54:55], s[54:55]
	v_fma_f32 v152, v175, s94, 0.5
	v_fma_f32 v152, v175, v152, 1.0
	v_mul_f32_e64 v174, v152, -v175
	s_or_b64 exec, exec, s[54:55]
	v_add_f32_e32 v83, v59, v83
	v_mul_f32_e32 v83, 0xbfb8aa3b, v83
	v_exp_f32_e32 v83, v83
	s_nop 0
	v_add_f32_e32 v83, 1.0, v83
	v_rcp_f32_e32 v83, v83
	s_nop 0
	v_mul_f32_e32 v83, 0xc1000000, v83
	v_mul_f32_e32 v175, v188, v83
	v_add_f32_e32 v176, v175, v175
	v_cmp_nlt_f32_e32 vcc, s93, v176
	s_and_saveexec_b64 s[54:55], vcc
	s_xor_b64 s[54:55], exec, s[54:55]
	v_mul_f32_e32 v83, 0x3fb8aa3b, v176
	v_exp_f32_e32 v83, v83
	s_nop 0
	v_sub_f32_e32 v83, 1.0, v83
	s_andn2_saveexec_b64 s[54:55], s[54:55]
	v_fma_f32 v83, v176, s94, 0.5
	v_fma_f32 v83, v176, v83, 1.0
	v_mul_f32_e64 v83, v83, -v176
	s_or_b64 exec, exec, s[54:55]
	v_add_f32_e32 v78, v34, v78
	v_mul_f32_e32 v78, 0xbfb8aa3b, v78
	s_nop 0
	s_nop 0
	s_waitcnt vmcnt(10)
	v_mov_b32_dpp v194, v216 row_shr:3 row_mask:0xf bank_mask:0xf
	v_mov_b32_dpp v195, v217 row_shr:3 row_mask:0xf bank_mask:0xf
	v_mov_b32_dpp v212, v216 row_shr:2 row_mask:0xf bank_mask:0xf
	v_mov_b32_dpp v213, v217 row_shr:2 row_mask:0xf bank_mask:0xf
	v_mov_b32_dpp v214, v216 row_shr:1 row_mask:0xf bank_mask:0xf
	v_mov_b32_dpp v215, v217 row_shr:1 row_mask:0xf bank_mask:0xf
	v_cndmask_b32_e64 v171, v195, 0, s[36:37]
	v_cndmask_b32_e64 v153, v194, 0, s[36:37]
	v_exp_f32_e32 v78, v78
	v_lshlrev_b32_e32 v152, 16, v153
	v_and_b32_e32 v153, 0xffff0000, v153
	v_lshlrev_b32_e32 v170, 16, v171
	v_and_b32_e32 v171, 0xffff0000, v171
	s_nop 0
	s_nop 0
	v_cndmask_b32_e64 v177, v213, 0, s[38:39]
	v_cndmask_b32_e64 v163, v212, 0, s[38:39]
	v_pk_fma_f32 v[170:171], v[50:51], v[170:171], v[54:55]
	v_pk_fma_f32 v[152:153], v[48:49], v[152:153], v[52:53]
	v_lshlrev_b32_e32 v162, 16, v163
	v_and_b32_e32 v163, 0xffff0000, v163
	v_lshlrev_b32_e32 v176, 16, v177
	v_and_b32_e32 v177, 0xffff0000, v177
	v_pk_fma_f32 v[152:153], v[44:45], v[162:163], v[152:153]
	v_pk_fma_f32 v[162:163], v[46:47], v[176:177], v[170:171]
	s_nop 0
	s_nop 0
	v_cndmask_b32_e64 v171, v215, 0, s[40:41]
	v_cndmask_b32_e64 v169, v214, 0, s[40:41]
	v_add_f32_e32 v77, v33, v77
	v_lshlrev_b32_e32 v168, 16, v169
	v_and_b32_e32 v169, 0xffff0000, v169
	v_add_f32_e32 v78, 1.0, v78
	v_add_f32_e32 v79, v35, v79
	v_mul_f32_e32 v77, 0xbfb8aa3b, v77
	v_pk_fma_f32 v[152:153], v[40:41], v[168:169], v[152:153]
	s_nop 0
	s_nop 0
	v_mov_b32_dpp v222, v216 row_shl:13 row_mask:0xf bank_mask:0xf
	v_mov_b32_dpp v223, v217 row_shl:13 row_mask:0xf bank_mask:0xf
	v_mov_b32_dpp v224, v216 row_shl:14 row_mask:0xf bank_mask:0xf
	v_mov_b32_dpp v225, v217 row_shl:14 row_mask:0xf bank_mask:0xf
	v_mov_b32_dpp v226, v216 row_shl:15 row_mask:0xf bank_mask:0xf
	v_mov_b32_dpp v227, v217 row_shl:15 row_mask:0xf bank_mask:0xf
	v_cndmask_b32_e64 v169, v216, 0, s[64:65]
	v_rcp_f32_e32 v78, v78
	v_sqrt_f32_e32 v172, v174
	v_mul_f32_e32 v79, 0xbfb8aa3b, v79
	v_exp_f32_e32 v77, v77
	v_lshlrev_b32_e32 v170, 16, v171
	v_and_b32_e32 v171, 0xffff0000, v171
	v_exp_f32_e32 v79, v79
	v_pk_fma_f32 v[162:163], v[42:43], v[170:171], v[162:163]
	v_cndmask_b32_e64 v171, v217, 0, s[64:65]
	v_add_f32_e32 v76, v32, v76
	v_lshlrev_b32_e32 v168, 16, v169
	v_and_b32_e32 v169, 0xffff0000, v169
	v_lshlrev_b32_e32 v170, 16, v171
	v_and_b32_e32 v171, 0xffff0000, v171
	v_mul_f32_e32 v76, 0xbfb8aa3b, v76
	v_pk_fma_f32 v[152:153], v[36:37], v[168:169], v[152:153]
	v_pk_fma_f32 v[168:169], v[38:39], v[170:171], v[162:163]
	v_mul_f32_e32 v78, v78, v172
	v_add_f32_e32 v77, 1.0, v77
	v_exp_f32_e32 v76, v76
	v_mul_f32_e32 v171, v168, v78
	v_add_f32_e32 v78, 1.0, v79
	v_rcp_f32_e32 v77, v77
	v_sqrt_f32_e32 v79, v147
	v_add_f32_e32 v76, 1.0, v76
	v_rcp_f32_e32 v76, v76
	v_rcp_f32_e32 v78, v78
	v_mul_f32_e32 v77, v77, v79
	v_sqrt_f32_e32 v79, v144
	v_mul_f32_e32 v80, 0x3fb8aa3b, v80
	v_exp_f32_e32 v80, v80
	v_mul_f32_e32 v144, v153, v77
	v_mul_f32_e32 v76, v76, v79
	v_sqrt_f32_e32 v79, v83
	v_mul_f32_e32 v168, v152, v76
	v_mul_f32_e32 v76, 0x3fb8aa3b, v81
	v_exp_f32_e32 v76, v76
	v_mul_f32_e32 v78, v78, v79
	v_mul_f32_e32 v172, v169, v78
	v_mov_b32_e32 v78, 1.0
	v_mov_b32_e32 v79, v145
	v_mul_f32_e32 v77, 0x3fb8aa3b, v82
	v_mov_b32_dpp v78, v80 row_shr:1 row_mask:0xf bank_mask:0xf
	v_mov_b32_dpp v79, v168 row_shr:1 row_mask:0xf bank_mask:0xf
	v_exp_f32_e32 v77, v77
	v_fmac_f32_e32 v168, v80, v79
	v_mul_f32_e32 v78, v80, v78
	v_mov_b32_e32 v80, v145
	v_mul_f32_e32 v147, 0x3fb8aa3b, v175
	v_exp_f32_e32 v147, v147
	v_mov_b32_dpp v80, v144 row_shr:1 row_mask:0xf bank_mask:0xf
	v_mov_b32_e32 v79, 1.0
	v_fmac_f32_e32 v144, v76, v80
	v_mov_b32_e32 v80, v145
	v_mov_b32_dpp v79, v76 row_shr:1 row_mask:0xf bank_mask:0xf
	v_mul_f32_e32 v76, v76, v79
	v_mov_b32_dpp v80, v171 row_shr:1 row_mask:0xf bank_mask:0xf
	v_mov_b32_e32 v79, 1.0
	v_fmac_f32_e32 v171, v77, v80
	v_mov_b32_e32 v80, v145
	v_mov_b32_dpp v79, v77 row_shr:1 row_mask:0xf bank_mask:0xf
	v_mul_f32_e32 v77, v77, v79
	v_mov_b32_dpp v80, v172 row_shr:1 row_mask:0xf bank_mask:0xf
	v_mov_b32_e32 v79, 1.0
	v_fmac_f32_e32 v172, v147, v80
	v_mov_b32_e32 v80, 1.0
	v_mov_b32_e32 v81, v145
	v_mov_b32_dpp v79, v147 row_shr:1 row_mask:0xf bank_mask:0xf
	v_mov_b32_dpp v80, v78 row_shr:2 row_mask:0xf bank_mask:0xf
	v_mov_b32_dpp v81, v168 row_shr:2 row_mask:0xf bank_mask:0xf
	v_mul_f32_e32 v79, v147, v79
	v_fmac_f32_e32 v168, v78, v81
	v_mul_f32_e32 v147, v78, v80
	v_mov_b32_e32 v78, 1.0
	v_mov_b32_e32 v80, v145
	s_waitcnt lgkmcnt(4)
	v_pk_fma_f32 v[162:163], v[86:87], 0, v[84:85] op_sel_hi:[1,0,1]
	v_mov_b32_dpp v78, v76 row_shr:2 row_mask:0xf bank_mask:0xf
	v_mov_b32_dpp v80, v144 row_shr:2 row_mask:0xf bank_mask:0xf
	v_fmac_f32_e32 v144, v76, v80
	v_mul_f32_e32 v169, v76, v78
	v_mov_b32_e32 v76, 1.0
	v_mov_b32_e32 v78, v145
	s_nop 0
	s_nop 0
	s_waitcnt vmcnt(8)
	v_lshlrev_b32_e32 v84, 16, v220
	v_mov_b32_dpp v76, v77 row_shr:2 row_mask:0xf bank_mask:0xf
	v_mul_f32_e32 v170, v77, v76
	v_mov_b32_e32 v76, 1.0
	v_mov_b32_dpp v78, v171 row_shr:2 row_mask:0xf bank_mask:0xf
	v_fmac_f32_e32 v171, v77, v78
	v_mov_b32_dpp v76, v79 row_shr:2 row_mask:0xf bank_mask:0xf
	v_mul_f32_e32 v173, v79, v76
	v_mov_b32_e32 v76, v145
	v_mov_b32_e32 v77, v145
	v_mul_f32_e32 v84, 0xbfb8aa3b, v84
	v_mov_b32_dpp v76, v168 row_shr:4 row_mask:0xf bank_mask:0xf
	v_fmac_f32_e32 v168, v147, v76
	v_mov_b32_e32 v76, v145
	v_mov_b32_dpp v77, v172 row_shr:2 row_mask:0xf bank_mask:0xf
	v_fmac_f32_e32 v172, v79, v77
	v_mov_b32_dpp v76, v144 row_shr:4 row_mask:0xf bank_mask:0xf
	v_fmac_f32_e32 v144, v169, v76
	v_mov_b32_e32 v76, v145
	v_mov_b32_e32 v77, 1.0
	v_exp_f32_e32 v153, v84
	v_mov_b32_dpp v76, v171 row_shr:4 row_mask:0xf bank_mask:0xf
	v_fmac_f32_e32 v171, v170, v76
	v_mov_b32_e32 v76, v145
	v_mov_b32_dpp v77, v147 row_shr:4 row_mask:0xf bank_mask:0xf
	v_mov_b32_e32 v152, v145
	v_mov_b32_dpp v76, v172 row_shr:4 row_mask:0xf bank_mask:0xf
	v_fmac_f32_e32 v172, v173, v76
	v_lshlrev_b32_e32 v76, 16, v218
	v_pk_mul_f32 v[84:85], v[146:147], v[76:77]
	v_mul_f32_e32 v77, 0x3d372713, v76
	v_mul_f32_e32 v77, v77, v76
	v_fmac_f32_e32 v76, v77, v76
	v_mul_f32_e32 v76, 0x3f4c422a, v76
	v_add_f32_e32 v76, v76, v76
	v_mul_f32_e32 v76, 0x3fb8aa3b, v76
	v_exp_f32_e32 v77, v76
	v_add_f32_e32 v76, 1.0, v153
	v_rcp_f32_e32 v76, v76
	v_mov_b32_dpp v152, v168 row_shr:8 row_mask:0xf bank_mask:0xf
	v_add_f32_e32 v77, 1.0, v77
	v_rcp_f32_e32 v77, v77
	v_mov_b32_e32 v153, 1.0
	v_fmac_f32_e32 v168, v85, v152
	v_mov_b32_e32 v79, 1.0
	v_fma_f32 v77, v77, -2.0, 1.0
	v_mov_b32_dpp v153, v85 row_shr:8 row_mask:0xf bank_mask:0xf
	v_add_f32_e32 v152, 1.0, v77
	v_pk_mul_f32 v[84:85], v[84:85], v[152:153]
	v_mov_b32_e32 v77, v162
	v_lshlrev_b32_e32 v80, 16, v219
	v_and_b32_e32 v82, 0xffff0000, v219
	v_and_b32_e32 v167, 0xffff0000, v220
	v_pk_mul_f32 v[76:77], v[76:77], v[84:85]
	v_mov_b32_dpp v79, v169 row_shr:4 row_mask:0xf bank_mask:0xf
	v_and_b32_e32 v78, 0xffff0000, v218
	v_add_f32_e32 v77, v77, v168
	v_mul_f32_e32 v84, 0xbfb8aa3b, v167
	v_mov_b32_e32 v147, v169
	ds_bpermute_b32 v164, v184, v85
	v_mul_f32_e32 v152, v76, v77
	v_mul_f32_e32 v77, v85, v86
	v_exp_f32_e32 v153, v84
	v_pk_mul_f32 v[84:85], v[146:147], v[78:79]
	v_mul_f32_e32 v79, 0x3d372713, v78
	v_mul_f32_e32 v79, v79, v78
	v_fmac_f32_e32 v78, v79, v78
	v_mul_f32_e32 v78, 0x3f4c422a, v78
	v_add_f32_e32 v78, v78, v78
	v_mul_f32_e32 v78, 0x3fb8aa3b, v78
	v_exp_f32_e32 v78, v78
	v_mul_f32_e32 v179, v76, v77
	v_add_f32_e32 v76, 1.0, v153
	v_rcp_f32_e32 v76, v76
	v_add_f32_e32 v77, 1.0, v78
	v_rcp_f32_e32 v77, v77
	v_mov_b32_e32 v79, 1.0
	v_mov_b32_e32 v174, v145
	v_mov_b32_e32 v81, 1.0
	v_fma_f32 v77, v77, -2.0, 1.0
	v_mov_b32_dpp v79, v85 row_shr:8 row_mask:0xf bank_mask:0xf
	v_add_f32_e32 v78, 1.0, v77
	v_mov_b32_dpp v174, v144 row_shr:8 row_mask:0xf bank_mask:0xf
	v_pk_mul_f32 v[78:79], v[84:85], v[78:79]
	v_mov_b32_e32 v77, v163
	v_lshlrev_b32_e32 v177, 16, v221
	v_fmac_f32_e32 v144, v85, v174
	v_pk_mul_f32 v[76:77], v[76:77], v[78:79]
	v_mov_b32_dpp v81, v170 row_shr:4 row_mask:0xf bank_mask:0xf
	v_add_f32_e32 v77, v77, v144
	v_mul_f32_e32 v78, 0xbfb8aa3b, v177
	v_mov_b32_e32 v147, v170
	v_and_b32_e32 v178, 0xffff0000, v221
	ds_bpermute_b32 v165, v184, v79
	v_mul_f32_e32 v84, v76, v77
	v_mul_f32_e32 v77, v79, v87
	v_exp_f32_e32 v85, v78
	v_pk_mul_f32 v[78:79], v[146:147], v[80:81]
	v_mul_f32_e32 v81, 0x3d372713, v80
	v_mul_f32_e32 v81, v81, v80
	v_fmac_f32_e32 v80, v81, v80
	v_mul_f32_e32 v80, 0x3f4c422a, v80
	v_add_f32_e32 v80, v80, v80
	v_mul_f32_e32 v80, 0x3fb8aa3b, v80
	v_exp_f32_e32 v80, v80
	ds_bpermute_b32 v167, v184, v144
	v_mul_f32_e32 v144, v76, v77
	v_add_f32_e32 v76, 1.0, v85
	v_add_f32_e32 v77, 1.0, v80
	v_rcp_f32_e32 v77, v77
	v_rcp_f32_e32 v76, v76
	v_mov_b32_e32 v175, v145
	v_mov_b32_e32 v81, 1.0
	v_fma_f32 v77, v77, -2.0, 1.0
	s_waitcnt lgkmcnt(3)
	v_pk_fma_f32 v[142:143], v[140:141], 0, v[142:143] op_sel_hi:[1,0,1]
	v_mov_b32_dpp v175, v171 row_shr:8 row_mask:0xf bank_mask:0xf
	v_mov_b32_dpp v81, v79 row_shr:8 row_mask:0xf bank_mask:0xf
	v_add_f32_e32 v80, 1.0, v77
	v_fmac_f32_e32 v171, v79, v175
	v_pk_mul_f32 v[78:79], v[78:79], v[80:81]
	v_mov_b32_e32 v77, v142
	v_mov_b32_e32 v83, 1.0
	v_pk_mul_f32 v[76:77], v[76:77], v[78:79]
	v_mul_f32_e32 v81, 0x3d372713, v82
	v_mov_b32_dpp v83, v173 row_shr:4 row_mask:0xf bank_mask:0xf
	v_add_f32_e32 v77, v77, v171
	v_mul_f32_e32 v78, 0xbfb8aa3b, v178
	v_mov_b32_e32 v147, v173
	v_mul_f32_e32 v81, v81, v82
	ds_bpermute_b32 v166, v184, v168
	ds_bpermute_b32 v168, v184, v79
	v_mul_f32_e32 v85, v76, v77
	v_mul_f32_e32 v77, v79, v140
	v_exp_f32_e32 v80, v78
	v_pk_mul_f32 v[78:79], v[146:147], v[82:83]
	v_fmac_f32_e32 v82, v81, v82
	v_mul_f32_e32 v81, 0x3f4c422a, v82
	v_add_f32_e32 v81, v81, v81
	v_mul_f32_e32 v81, 0x3fb8aa3b, v81
	v_exp_f32_e32 v81, v81
	v_mul_f32_e32 v82, v76, v77
	v_add_f32_e32 v76, 1.0, v80
	v_rcp_f32_e32 v76, v76
	v_add_f32_e32 v77, 1.0, v81
	v_rcp_f32_e32 v77, v77
	v_mov_b32_e32 v176, v145
	v_mov_b32_e32 v81, 1.0
	ds_bpermute_b32 v170, v184, v171
	v_fma_f32 v77, v77, -2.0, 1.0
	v_mov_b32_dpp v176, v172 row_shr:8 row_mask:0xf bank_mask:0xf
	v_mov_b32_dpp v81, v79 row_shr:8 row_mask:0xf bank_mask:0xf
	v_add_f32_e32 v80, 1.0, v77
	v_fmac_f32_e32 v172, v79, v176
	v_pk_mul_f32 v[78:79], v[78:79], v[80:81]
	v_mov_b32_e32 v77, v143
	v_pk_mul_f32 v[76:77], v[76:77], v[78:79]
	v_mul_f32_e32 v78, v79, v141
	v_add_f32_e32 v77, v77, v172
	v_mul_f32_e32 v77, v76, v77
	ds_bpermute_b32 v169, v184, v79
	ds_bpermute_b32 v171, v184, v172
	v_mul_f32_e32 v80, v76, v78
	v_cvt_pk_bf16_f32 v76, v152, v84
	v_cvt_pk_bf16_f32 v77, v85, v77
	v_lshl_add_u64 v[84:85], s[74:75], 0, v[132:133]
	s_mov_b32 s54, 0x25d49000
	v_add_co_u32_e32 v78, vcc, s54, v84
	s_mov_b32 s54, 0x27d49000
	s_nop 0
	v_addc_co_u32_e32 v79, vcc, 0, v85, vcc
	global_store_dwordx2 v[78:79], v[76:77], off
	v_add_co_u32_e32 v78, vcc, s54, v84
	v_cvt_pk_bf16_f32 v76, v179, v144
	v_cvt_pk_bf16_f32 v77, v82, v80
	s_nop 1
	v_addc_co_u32_e32 v79, vcc, 0, v85, vcc
	global_store_dwordx2 v[78:79], v[76:77], off
	s_mov_b32 s54, 0x13118000
	v_add_co_u32_e32 v80, vcc, s54, v138
	s_mov_b32 s54, 0x1311c000
	s_nop 0
	v_addc_co_u32_e32 v81, vcc, 0, v139, vcc
	s_nop 0
	v_add_co_u32_e32 v80, vcc, s54, v138
	s_mov_b32 s54, 0x13120000
	s_nop 0
	v_addc_co_u32_e32 v81, vcc, 0, v139, vcc
	s_nop 0
	v_add_co_u32_e32 v80, vcc, s54, v138
	s_mov_b32 s54, 0x13125000
	s_nop 0
	v_addc_co_u32_e32 v81, vcc, 0, v139, vcc
	v_add_co_u32_e32 v152, vcc, s54, v138
	s_nop 0
	s_nop 0
	v_addc_co_u32_e32 v153, vcc, 0, v139, vcc
	s_nop 0
	s_nop 0
	v_add_co_u32_e32 v152, vcc, 0x13128000, v138
	v_mfma_f32_16x16x32_bf16 v[80:83], v[72:75], v[8:11], 0
	s_nop 0
	v_addc_co_u32_e32 v153, vcc, 0, v139, vcc
	s_nop 0
	v_mfma_f32_16x16x32_bf16 v[80:83], v[60:63], v[24:27], v[80:83]
	v_mfma_f32_16x16x32_bf16 v[76:79], v[68:71], v[8:11], 0
	v_mfma_f32_16x16x32_bf16 v[76:79], v[64:67], v[24:27], v[76:79]
	s_nop 5
	v_add_f32_e32 v80, v56, v80
	v_mul_f32_e32 v80, 0xbfb8aa3b, v80
	v_exp_f32_e32 v80, v80
	s_nop 0
	v_add_f32_e32 v80, 1.0, v80
	v_rcp_f32_e32 v80, v80
	s_nop 0
	v_mul_f32_e32 v80, 0xc1000000, v80
	v_mul_f32_e32 v144, v185, v80
	v_add_f32_e32 v147, v144, v144
	v_cmp_nlt_f32_e32 vcc, s93, v147
	s_and_saveexec_b64 s[54:55], vcc
	s_xor_b64 s[54:55], exec, s[54:55]
	v_mul_f32_e32 v80, 0x3fb8aa3b, v147
	v_exp_f32_e32 v80, v80
	s_nop 0
	v_sub_f32_e32 v80, 1.0, v80
	s_andn2_saveexec_b64 s[54:55], s[54:55]
	v_fma_f32 v80, v147, s94, 0.5
	v_fma_f32 v80, v147, v80, 1.0
	v_mul_f32_e64 v80, v80, -v147
	s_or_b64 exec, exec, s[54:55]
	v_add_f32_e32 v81, v57, v81
	v_mul_f32_e32 v81, 0xbfb8aa3b, v81
	v_exp_f32_e32 v81, v81
	s_nop 0
	v_add_f32_e32 v81, 1.0, v81
	v_rcp_f32_e32 v81, v81
	s_nop 0
	v_mul_f32_e32 v81, 0xc1000000, v81
	v_mul_f32_e32 v81, v186, v81
	v_add_f32_e32 v189, v81, v81
	v_cmp_nlt_f32_e32 vcc, s93, v189
	s_and_saveexec_b64 s[54:55], vcc
	s_xor_b64 s[54:55], exec, s[54:55]
	v_mul_f32_e32 v147, 0x3fb8aa3b, v189
	v_exp_f32_e32 v147, v147
	s_nop 0
	v_sub_f32_e32 v147, 1.0, v147
	s_andn2_saveexec_b64 s[54:55], s[54:55]
	v_fma_f32 v147, v189, s94, 0.5
	v_fma_f32 v147, v189, v147, 1.0
	v_mul_f32_e64 v147, v147, -v189
	s_or_b64 exec, exec, s[54:55]
	v_add_f32_e32 v82, v58, v82
	v_mul_f32_e32 v82, 0xbfb8aa3b, v82
	v_exp_f32_e32 v82, v82
	s_nop 0
	v_add_f32_e32 v82, 1.0, v82
	v_rcp_f32_e32 v82, v82
	s_nop 0
	v_mul_f32_e32 v82, 0xc1000000, v82
	v_mul_f32_e32 v82, v187, v82
	v_add_f32_e32 v189, v82, v82
	v_cmp_nlt_f32_e32 vcc, s93, v189
	s_and_saveexec_b64 s[54:55], vcc
	s_xor_b64 s[54:55], exec, s[54:55]
	v_mul_f32_e32 v152, 0x3fb8aa3b, v189
	v_exp_f32_e32 v152, v152
	s_nop 0
	v_sub_f32_e32 v190, 1.0, v152
	s_andn2_saveexec_b64 s[54:55], s[54:55]
	v_fma_f32 v152, v189, s94, 0.5
	v_fma_f32 v152, v189, v152, 1.0
	v_mul_f32_e64 v190, v152, -v189
	s_or_b64 exec, exec, s[54:55]
	v_add_f32_e32 v83, v59, v83
	v_mul_f32_e32 v83, 0xbfb8aa3b, v83
	v_exp_f32_e32 v83, v83
	s_nop 0
	v_add_f32_e32 v83, 1.0, v83
	v_rcp_f32_e32 v83, v83
	s_nop 0
	v_mul_f32_e32 v83, 0xc1000000, v83
	v_mul_f32_e32 v83, v188, v83
	v_add_f32_e32 v191, v83, v83
	v_cmp_nlt_f32_e32 vcc, s93, v191
	s_and_saveexec_b64 s[54:55], vcc
	s_xor_b64 s[54:55], exec, s[54:55]
	v_mul_f32_e32 v152, 0x3fb8aa3b, v191
	v_exp_f32_e32 v152, v152
	s_nop 0
	v_sub_f32_e32 v189, 1.0, v152
	s_andn2_saveexec_b64 s[54:55], s[54:55]
	v_fma_f32 v152, v191, s94, 0.5
	v_fma_f32 v152, v191, v152, 1.0
	v_mul_f32_e64 v189, v152, -v191
	s_or_b64 exec, exec, s[54:55]
	v_add_f32_e32 v78, v34, v78
	v_mul_f32_e32 v78, 0xbfb8aa3b, v78
	s_nop 0
	s_nop 0
	s_waitcnt vmcnt(9)
	v_mov_b32_dpp v222, v228 row_shr:3 row_mask:0xf bank_mask:0xf
	v_mov_b32_dpp v223, v229 row_shr:3 row_mask:0xf bank_mask:0xf
	v_mov_b32_dpp v224, v228 row_shr:2 row_mask:0xf bank_mask:0xf
	v_mov_b32_dpp v225, v229 row_shr:2 row_mask:0xf bank_mask:0xf
	v_mov_b32_dpp v226, v228 row_shr:1 row_mask:0xf bank_mask:0xf
	v_mov_b32_dpp v227, v229 row_shr:1 row_mask:0xf bank_mask:0xf
	v_cndmask_b32_e64 v181, v223, 0, s[42:43]
	v_cndmask_b32_e64 v153, v222, 0, s[42:43]
	v_exp_f32_e32 v78, v78
	v_lshlrev_b32_e32 v152, 16, v153
	v_and_b32_e32 v153, 0xffff0000, v153
	v_lshlrev_b32_e32 v180, 16, v181
	v_and_b32_e32 v181, 0xffff0000, v181
	s_nop 0
	s_nop 0
	v_cndmask_b32_e64 v191, v225, 0, s[44:45]
	v_cndmask_b32_e64 v177, v224, 0, s[44:45]
	v_pk_fma_f32 v[180:181], v[50:51], v[180:181], v[54:55]
	v_pk_fma_f32 v[152:153], v[48:49], v[152:153], v[52:53]
	v_lshlrev_b32_e32 v176, 16, v177
	v_and_b32_e32 v177, 0xffff0000, v177
	v_lshlrev_b32_e32 v192, 16, v191
	v_and_b32_e32 v193, 0xffff0000, v191
	v_pk_fma_f32 v[152:153], v[44:45], v[176:177], v[152:153]
	v_pk_fma_f32 v[176:177], v[46:47], v[192:193], v[180:181]
	s_nop 0
	s_nop 0
	v_cndmask_b32_e64 v181, v227, 0, s[46:47]
	v_cndmask_b32_e64 v179, v226, 0, s[46:47]
	v_lshlrev_b32_e32 v178, 16, v179
	v_and_b32_e32 v179, 0xffff0000, v179
	v_add_f32_e32 v78, 1.0, v78
	v_add_f32_e32 v79, v35, v79
	v_add_f32_e32 v77, v33, v77
	v_pk_fma_f32 v[152:153], v[40:41], v[178:179], v[152:153]
	s_nop 0
	s_nop 0
	v_mov_b32_dpp v234, v228 row_shl:13 row_mask:0xf bank_mask:0xf
	v_mov_b32_dpp v235, v229 row_shl:13 row_mask:0xf bank_mask:0xf
	v_mov_b32_dpp v236, v228 row_shl:14 row_mask:0xf bank_mask:0xf
	v_mov_b32_dpp v237, v229 row_shl:14 row_mask:0xf bank_mask:0xf
	v_mov_b32_dpp v238, v228 row_shl:15 row_mask:0xf bank_mask:0xf
	v_mov_b32_dpp v239, v229 row_shl:15 row_mask:0xf bank_mask:0xf
	v_cndmask_b32_e64 v179, v228, 0, s[64:65]
	v_rcp_f32_e32 v78, v78
	v_sqrt_f32_e32 v182, v190
	v_mul_f32_e32 v79, 0xbfb8aa3b, v79
	v_mul_f32_e32 v77, 0xbfb8aa3b, v77
	v_lshlrev_b32_e32 v180, 16, v181
	v_and_b32_e32 v181, 0xffff0000, v181
	v_exp_f32_e32 v79, v79
	v_exp_f32_e32 v77, v77
	v_pk_fma_f32 v[176:177], v[42:43], v[180:181], v[176:177]
	v_cndmask_b32_e64 v181, v229, 0, s[64:65]
	v_lshlrev_b32_e32 v180, 16, v181
	v_and_b32_e32 v181, 0xffff0000, v181
	v_add_f32_e32 v76, v32, v76
	v_pk_fma_f32 v[176:177], v[38:39], v[180:181], v[176:177]
	v_mul_f32_e32 v78, v78, v182
	v_mul_f32_e32 v76, 0xbfb8aa3b, v76
	v_lshlrev_b32_e32 v178, 16, v179
	v_and_b32_e32 v179, 0xffff0000, v179
	v_mul_f32_e32 v176, v176, v78
	v_add_f32_e32 v78, 1.0, v79
	v_add_f32_e32 v77, 1.0, v77
	v_exp_f32_e32 v76, v76
	v_pk_fma_f32 v[152:153], v[36:37], v[178:179], v[152:153]
	v_rcp_f32_e32 v178, v78
	v_rcp_f32_e32 v77, v77
	v_sqrt_f32_e32 v78, v147
	v_add_f32_e32 v76, 1.0, v76
	v_rcp_f32_e32 v76, v76
	v_mul_f32_e32 v79, 0x3fb8aa3b, v83
	v_mul_f32_e32 v77, v77, v78
	v_sqrt_f32_e32 v78, v80
	v_mul_f32_e32 v179, v153, v77
	v_mul_f32_e32 v77, 0x3fb8aa3b, v82
	s_waitcnt lgkmcnt(6)
	v_pk_mul_f32 v[82:83], v[86:87], v[164:165]
	v_sqrt_f32_e32 v86, v189
	v_mul_f32_e32 v87, 0x3fb8aa3b, v144
	v_mul_f32_e32 v76, v76, v78
	v_exp_f32_e32 v87, v87
	v_exp_f32_e32 v147, v79
	v_exp_f32_e32 v153, v77
	v_mul_f32_e32 v180, v152, v76
	v_mul_f32_e32 v76, 0x3fb8aa3b, v81
	v_exp_f32_e32 v152, v76
	v_mul_f32_e32 v86, v178, v86
	s_waitcnt lgkmcnt(1)
	v_pk_mul_f32 v[78:79], v[140:141], v[168:169]
	s_waitcnt lgkmcnt(0)
	v_pk_fma_f32 v[76:77], v[142:143], v[168:169], v[170:171]
	v_mul_f32_e32 v144, v177, v86
	v_mov_b32_e32 v86, 1.0
	v_mov_b32_e32 v140, v145
	v_mov_b32_e32 v141, v145
	v_mov_b32_e32 v142, v145
	v_mov_b32_dpp v86, v87 row_shr:1 row_mask:0xf bank_mask:0xf
	v_mov_b32_dpp v140, v180 row_shr:1 row_mask:0xf bank_mask:0xf
	v_mov_b32_dpp v141, v176 row_shr:1 row_mask:0xf bank_mask:0xf
	v_mov_b32_dpp v142, v144 row_shr:1 row_mask:0xf bank_mask:0xf
	v_fmac_f32_e32 v180, v87, v140
	v_mul_f32_e32 v86, v87, v86
	v_mov_b32_e32 v87, 1.0
	v_mov_b32_e32 v140, v145
	v_fmac_f32_e32 v176, v153, v141
	v_mov_b32_e32 v141, 1.0
	v_fmac_f32_e32 v144, v147, v142
	v_mov_b32_e32 v142, 1.0
	v_mov_b32_e32 v143, v145
	v_mov_b32_dpp v87, v152 row_shr:1 row_mask:0xf bank_mask:0xf
	v_mov_b32_dpp v140, v179 row_shr:1 row_mask:0xf bank_mask:0xf
	v_mov_b32_dpp v141, v147 row_shr:1 row_mask:0xf bank_mask:0xf
	v_mov_b32_dpp v142, v86 row_shr:2 row_mask:0xf bank_mask:0xf
	v_mov_b32_dpp v143, v180 row_shr:2 row_mask:0xf bank_mask:0xf
	v_fmac_f32_e32 v179, v152, v140
	v_mul_f32_e32 v87, v152, v87
	v_mov_b32_e32 v140, 1.0
	v_mul_f32_e32 v141, v147, v141
	v_fmac_f32_e32 v180, v86, v143
	v_mul_f32_e32 v147, v86, v142
	v_mov_b32_e32 v86, 1.0
	v_mov_b32_dpp v140, v153 row_shr:1 row_mask:0xf bank_mask:0xf
	v_mul_f32_e32 v140, v153, v140
	v_mov_b32_dpp v86, v87 row_shr:2 row_mask:0xf bank_mask:0xf
	v_mul_f32_e32 v168, v87, v86
	v_mov_b32_e32 v86, 1.0
	v_mov_b32_e32 v142, v145
	v_pk_fma_f32 v[80:81], v[162:163], v[164:165], v[166:167]
	v_mov_b32_dpp v86, v140 row_shr:2 row_mask:0xf bank_mask:0xf
	v_mul_f32_e32 v169, v140, v86
	v_mov_b32_e32 v86, 1.0
	v_mov_b32_dpp v142, v179 row_shr:2 row_mask:0xf bank_mask:0xf
	v_fmac_f32_e32 v179, v87, v142
	v_mov_b32_dpp v86, v141 row_shr:2 row_mask:0xf bank_mask:0xf
	v_mul_f32_e32 v170, v141, v86
	v_mov_b32_e32 v86, v145
	v_mov_b32_e32 v87, v145
	v_mov_b32_e32 v163, v145
	v_mov_b32_dpp v86, v180 row_shr:4 row_mask:0xf bank_mask:0xf
	v_fmac_f32_e32 v180, v147, v86
	v_mov_b32_e32 v86, v145
	v_mov_b32_dpp v87, v176 row_shr:2 row_mask:0xf bank_mask:0xf
	v_fmac_f32_e32 v176, v140, v87
	v_mov_b32_dpp v86, v179 row_shr:4 row_mask:0xf bank_mask:0xf
	v_mov_b32_e32 v87, v145
	v_fmac_f32_e32 v179, v168, v86
	v_mov_b32_e32 v86, v145
	v_mov_b32_dpp v87, v144 row_shr:2 row_mask:0xf bank_mask:0xf
	v_fmac_f32_e32 v144, v141, v87
	v_mov_b32_dpp v86, v176 row_shr:4 row_mask:0xf bank_mask:0xf
	v_fmac_f32_e32 v176, v169, v86
	v_mov_b32_e32 v86, v145
	v_mov_b32_e32 v87, 1.0
	s_nop 0
	s_nop 0
	s_waitcnt vmcnt(7)
	v_lshlrev_b32_e32 v140, 16, v232
	v_mov_b32_dpp v86, v144 row_shr:4 row_mask:0xf bank_mask:0xf
	v_mov_b32_dpp v87, v147 row_shr:4 row_mask:0xf bank_mask:0xf
	v_fmac_f32_e32 v144, v170, v86
	v_lshlrev_b32_e32 v86, 16, v230
	v_mul_f32_e32 v140, 0xbfb8aa3b, v140
	v_exp_f32_e32 v162, v140
	v_pk_mul_f32 v[140:141], v[146:147], v[86:87]
	v_mul_f32_e32 v87, 0x3d372713, v86
	v_mul_f32_e32 v87, v87, v86
	v_fmac_f32_e32 v86, v87, v86
	v_mul_f32_e32 v86, 0x3f4c422a, v86
	v_add_f32_e32 v86, v86, v86
	v_mul_f32_e32 v86, 0x3fb8aa3b, v86
	v_exp_f32_e32 v86, v86
	v_add_f32_e32 v87, 1.0, v162
	v_rcp_f32_e32 v162, v87
	v_mov_b32_e32 v87, 1.0
	v_add_f32_e32 v86, 1.0, v86
	v_rcp_f32_e32 v86, v86
	v_mov_b32_e32 v143, 1.0
	v_mov_b32_dpp v163, v180 row_shr:8 row_mask:0xf bank_mask:0xf
	v_mov_b32_dpp v87, v141 row_shr:8 row_mask:0xf bank_mask:0xf
	v_fma_f32 v86, v86, -2.0, 1.0
	v_add_f32_e32 v86, 1.0, v86
	v_mov_b32_dpp v143, v168 row_shr:4 row_mask:0xf bank_mask:0xf
	v_and_b32_e32 v142, 0xffff0000, v230
	v_fmac_f32_e32 v180, v141, v163
	v_pk_mul_f32 v[166:167], v[140:141], v[86:87]
	v_mov_b32_e32 v163, v80
	v_mov_b32_e32 v147, v168
	ds_bpermute_b32 v86, v184, v167
	v_mul_f32_e32 v87, v82, v167
	v_pk_mul_f32 v[162:163], v[162:163], v[166:167]
	v_pk_mul_f32 v[166:167], v[146:147], v[142:143]
	v_mul_f32_e32 v143, 0x3d372713, v142
	v_mul_f32_e32 v143, v143, v142
	v_fmac_f32_e32 v142, v143, v142
	v_and_b32_e32 v172, 0xffff0000, v232
	v_add_f32_e32 v141, v163, v180
	v_mul_f32_e32 v142, 0x3f4c422a, v142
	v_lshlrev_b32_e32 v152, 16, v231
	v_and_b32_e32 v164, 0xffff0000, v231
	v_mul_f32_e32 v175, v162, v141
	v_mul_f32_e32 v141, 0xbfb8aa3b, v172
	v_add_f32_e32 v142, v142, v142
	v_exp_f32_e32 v141, v141
	v_mul_f32_e32 v142, 0x3fb8aa3b, v142
	v_exp_f32_e32 v143, v142
	v_mul_f32_e32 v168, v162, v87
	v_add_f32_e32 v87, 1.0, v141
	v_rcp_f32_e32 v142, v87
	v_add_f32_e32 v87, 1.0, v143
	v_rcp_f32_e32 v87, v87
	v_mov_b32_e32 v163, 1.0
	v_mov_b32_e32 v153, 1.0
	v_mov_b32_e32 v143, v81
	v_fma_f32 v87, v87, -2.0, 1.0
	v_mov_b32_dpp v163, v167 row_shr:8 row_mask:0xf bank_mask:0xf
	v_add_f32_e32 v162, 1.0, v87
	v_mov_b32_dpp v153, v169 row_shr:4 row_mask:0xf bank_mask:0xf
	v_pk_mul_f32 v[162:163], v[166:167], v[162:163]
	v_mov_b32_e32 v147, v169
	v_mov_b32_e32 v171, v145
	ds_bpermute_b32 v87, v184, v163
	v_mul_f32_e32 v166, v83, v163
	v_pk_mul_f32 v[142:143], v[142:143], v[162:163]
	v_pk_mul_f32 v[162:163], v[146:147], v[152:153]
	v_mul_f32_e32 v147, 0x3d372713, v152
	v_mov_b32_dpp v171, v179 row_shr:8 row_mask:0xf bank_mask:0xf
	v_mul_f32_e32 v147, v147, v152
	v_fmac_f32_e32 v179, v167, v171
	v_fmac_f32_e32 v152, v147, v152
	v_lshlrev_b32_e32 v174, 16, v233
	v_add_f32_e32 v143, v143, v179
	v_mul_f32_e32 v147, 0x3f4c422a, v152
	v_mul_f32_e32 v171, v142, v143
	v_mul_f32_e32 v143, 0xbfb8aa3b, v174
	v_add_f32_e32 v147, v147, v147
	v_exp_f32_e32 v143, v143
	v_mul_f32_e32 v147, 0x3fb8aa3b, v147
	v_exp_f32_e32 v147, v147
	v_mul_f32_e32 v169, v142, v166
	v_add_f32_e32 v142, 1.0, v143
	v_rcp_f32_e32 v152, v142
	v_add_f32_e32 v142, 1.0, v147
	v_rcp_f32_e32 v142, v142
	v_mov_b32_e32 v143, 1.0
	v_mov_b32_e32 v177, v145
	v_mov_b32_e32 v153, v76
	v_fma_f32 v142, v142, -2.0, 1.0
	v_mov_b32_dpp v143, v163 row_shr:8 row_mask:0xf bank_mask:0xf
	v_add_f32_e32 v142, 1.0, v142
	v_mov_b32_dpp v177, v176 row_shr:8 row_mask:0xf bank_mask:0xf
	v_pk_mul_f32 v[166:167], v[162:163], v[142:143]
	v_fmac_f32_e32 v176, v163, v177
	v_pk_mul_f32 v[152:153], v[152:153], v[166:167]
	v_and_b32_e32 v173, 0xffff0000, v233
	v_add_f32_e32 v147, v153, v176
	v_mov_b32_e32 v165, 1.0
	v_mul_f32_e32 v172, v152, v147
	v_mul_f32_e32 v147, 0xbfb8aa3b, v173
	v_mov_b32_dpp v165, v170 row_shr:4 row_mask:0xf bank_mask:0xf
	v_exp_f32_e32 v153, v147
	v_mov_b32_e32 v147, v170
	ds_bpermute_b32 v142, v184, v167
	v_mul_f32_e32 v143, v78, v167
	v_pk_mul_f32 v[166:167], v[146:147], v[164:165]
	v_mul_f32_e32 v147, 0x3d372713, v164
	v_mul_f32_e32 v147, v147, v164
	v_fmac_f32_e32 v164, v147, v164
	v_mul_f32_e32 v147, 0x3f4c422a, v164
	v_add_f32_e32 v147, v147, v147
	v_mul_f32_e32 v147, 0x3fb8aa3b, v147
	v_exp_f32_e32 v147, v147
	v_mul_f32_e32 v170, v152, v143
	v_add_f32_e32 v143, 1.0, v153
	v_rcp_f32_e32 v152, v143
	v_add_f32_e32 v143, 1.0, v147
	v_rcp_f32_e32 v143, v143
	v_mov_b32_e32 v178, v145
	v_mov_b32_e32 v165, 1.0
	ds_bpermute_b32 v140, v184, v180
	v_fma_f32 v143, v143, -2.0, 1.0
	v_mov_b32_dpp v178, v144 row_shr:8 row_mask:0xf bank_mask:0xf
	v_mov_b32_dpp v165, v167 row_shr:8 row_mask:0xf bank_mask:0xf
	v_add_f32_e32 v164, 1.0, v143
	v_fmac_f32_e32 v144, v167, v178
	v_pk_mul_f32 v[164:165], v[166:167], v[164:165]
	ds_bpermute_b32 v141, v184, v179
	ds_bpermute_b32 v162, v184, v176
	ds_bpermute_b32 v143, v184, v165
	ds_bpermute_b32 v163, v184, v144
	v_mov_b32_e32 v153, v77
	s_mov_b32 s54, 0x25d51000
	v_pk_mul_f32 v[152:153], v[152:153], v[164:165]
	v_add_co_u32_e32 v164, vcc, s54, v84
	v_mul_f32_e32 v147, v79, v165
	v_add_f32_e32 v144, v153, v144
	v_addc_co_u32_e32 v165, vcc, 0, v85, vcc
	s_mov_b32 s54, 0x27d51000
	v_mul_f32_e32 v144, v152, v144
	v_mul_f32_e32 v147, v152, v147
	v_cvt_pk_bf16_f32 v152, v175, v171
	v_cvt_pk_bf16_f32 v153, v172, v144
	global_store_dwordx2 v[164:165], v[152:153], off
	v_add_co_u32_e32 v164, vcc, s54, v84
	v_cvt_pk_bf16_f32 v152, v168, v169
	v_cvt_pk_bf16_f32 v153, v170, v147
	s_nop 1
	v_addc_co_u32_e32 v165, vcc, 0, v85, vcc
	global_store_dwordx2 v[164:165], v[152:153], off
	s_mov_b32 s54, 0x1315a000
	v_add_co_u32_e32 v152, vcc, s54, v138
	s_mov_b32 s54, 0x1315e000
	s_nop 0
	v_addc_co_u32_e32 v153, vcc, 0, v139, vcc
	v_add_co_u32_e32 v164, vcc, s54, v138
	s_mov_b32 s54, 0x13162000
	s_nop 0
	v_addc_co_u32_e32 v165, vcc, 0, v139, vcc
	v_add_co_u32_e32 v166, vcc, s54, v138
	s_mov_b32 s54, 0x13167000
	s_nop 0
	v_addc_co_u32_e32 v167, vcc, 0, v139, vcc
	v_add_co_u32_e32 v174, vcc, s54, v138
	v_mfma_f32_16x16x32_bf16 v[72:75], v[72:75], v[12:15], 0
	s_nop 0
	v_addc_co_u32_e32 v175, vcc, 0, v139, vcc
	s_nop 0
	s_nop 0
	s_nop 0
	s_nop 0
	s_nop 0
	v_add_co_u32_e32 v138, vcc, 0x1316a000, v138
	v_mfma_f32_16x16x32_bf16 v[72:75], v[60:63], v[28:31], v[72:75]
	s_nop 0
	v_addc_co_u32_e32 v139, vcc, 0, v139, vcc
	s_nop 0
	s_nop 0
	s_nop 0
	s_nop 2
	v_add_f32_e32 v56, v56, v72
	v_mul_f32_e32 v56, 0xbfb8aa3b, v56
	v_exp_f32_e32 v56, v56
	v_mfma_f32_16x16x32_bf16 v[60:63], v[68:71], v[12:15], 0
	v_add_f32_e32 v56, 1.0, v56
	v_rcp_f32_e32 v56, v56
	v_mfma_f32_16x16x32_bf16 v[60:63], v[64:67], v[28:31], v[60:63]
	v_mul_f32_e32 v56, 0xc1000000, v56
	v_mul_f32_e32 v56, v185, v56
	v_add_f32_e32 v65, v56, v56
	v_cmp_nlt_f32_e32 vcc, s93, v65
	s_and_saveexec_b64 s[54:55], vcc
	s_xor_b64 s[54:55], exec, s[54:55]
	v_mul_f32_e32 v64, 0x3fb8aa3b, v65
	v_exp_f32_e32 v64, v64
	s_nop 0
	v_sub_f32_e32 v64, 1.0, v64
	s_andn2_saveexec_b64 s[54:55], s[54:55]
	v_fma_f32 v64, v65, s94, 0.5
	v_fma_f32 v64, v65, v64, 1.0
	v_mul_f32_e64 v64, v64, -v65
	s_or_b64 exec, exec, s[54:55]
	v_add_f32_e32 v57, v57, v73
	v_mul_f32_e32 v57, 0xbfb8aa3b, v57
	v_exp_f32_e32 v57, v57
	s_nop 0
	v_add_f32_e32 v57, 1.0, v57
	v_rcp_f32_e32 v57, v57
	s_nop 0
	v_mul_f32_e32 v57, 0xc1000000, v57
	v_mul_f32_e32 v57, v186, v57
	v_add_f32_e32 v66, v57, v57
	v_cmp_nlt_f32_e32 vcc, s93, v66
	s_and_saveexec_b64 s[54:55], vcc
	s_xor_b64 s[54:55], exec, s[54:55]
	v_mul_f32_e32 v65, 0x3fb8aa3b, v66
	v_exp_f32_e32 v65, v65
	s_nop 0
	v_sub_f32_e32 v65, 1.0, v65
	s_andn2_saveexec_b64 s[54:55], s[54:55]
	v_fma_f32 v65, v66, s94, 0.5
	v_fma_f32 v65, v66, v65, 1.0
	v_mul_f32_e64 v65, v65, -v66
	s_or_b64 exec, exec, s[54:55]
	v_add_f32_e32 v58, v58, v74
	v_mul_f32_e32 v58, 0xbfb8aa3b, v58
	v_exp_f32_e32 v58, v58
	s_nop 0
	v_add_f32_e32 v58, 1.0, v58
	v_rcp_f32_e32 v58, v58
	s_nop 0
	v_mul_f32_e32 v58, 0xc1000000, v58
	v_mul_f32_e32 v58, v187, v58
	v_add_f32_e32 v67, v58, v58
	v_cmp_nlt_f32_e32 vcc, s93, v67
	s_and_saveexec_b64 s[54:55], vcc
	s_xor_b64 s[54:55], exec, s[54:55]
	v_mul_f32_e32 v66, 0x3fb8aa3b, v67
	v_exp_f32_e32 v66, v66
	s_nop 0
	v_sub_f32_e32 v66, 1.0, v66
	s_andn2_saveexec_b64 s[54:55], s[54:55]
	v_fma_f32 v66, v67, s94, 0.5
	v_fma_f32 v66, v67, v66, 1.0
	v_mul_f32_e64 v66, v66, -v67
	s_or_b64 exec, exec, s[54:55]
	v_add_f32_e32 v59, v59, v75
	v_mul_f32_e32 v59, 0xbfb8aa3b, v59
	v_exp_f32_e32 v59, v59
	s_nop 0
	v_add_f32_e32 v59, 1.0, v59
	v_rcp_f32_e32 v59, v59
	s_nop 0
	v_mul_f32_e32 v59, 0xc1000000, v59
	v_mul_f32_e32 v67, v188, v59
	v_add_f32_e32 v68, v67, v67
	v_cmp_nlt_f32_e32 vcc, s93, v68
	s_and_saveexec_b64 s[54:55], vcc
	s_xor_b64 s[54:55], exec, s[54:55]
	v_mul_f32_e32 v59, 0x3fb8aa3b, v68
	v_exp_f32_e32 v59, v59
	s_nop 0
	v_sub_f32_e32 v59, 1.0, v59
	s_andn2_saveexec_b64 s[54:55], s[54:55]
	v_fma_f32 v59, v68, s94, 0.5
	v_fma_f32 v59, v68, v59, 1.0
	v_mul_f32_e64 v59, v59, -v68
	s_or_b64 exec, exec, s[54:55]
	v_add_f32_e32 v34, v34, v62
	s_nop 0
	s_nop 0
	s_waitcnt vmcnt(8)
	v_mov_b32_dpp v234, v242 row_shr:3 row_mask:0xf bank_mask:0xf
	v_mov_b32_dpp v235, v243 row_shr:3 row_mask:0xf bank_mask:0xf
	v_mov_b32_dpp v236, v242 row_shr:2 row_mask:0xf bank_mask:0xf
	v_mov_b32_dpp v237, v243 row_shr:2 row_mask:0xf bank_mask:0xf
	v_mov_b32_dpp v238, v242 row_shr:1 row_mask:0xf bank_mask:0xf
	v_mov_b32_dpp v239, v243 row_shr:1 row_mask:0xf bank_mask:0xf
	v_cndmask_b32_e64 v69, v234, 0, s[48:49]
	v_mul_f32_e32 v34, 0xbfb8aa3b, v34
	v_lshlrev_b32_e32 v68, 16, v69
	v_and_b32_e32 v69, 0xffff0000, v69
	v_exp_f32_e32 v34, v34
	v_cndmask_b32_e64 v71, v235, 0, s[48:49]
	v_pk_fma_f32 v[48:49], v[48:49], v[68:69], v[52:53]
	s_nop 0
	s_nop 0
	v_cndmask_b32_e64 v53, v236, 0, s[50:51]
	v_lshlrev_b32_e32 v70, 16, v71
	v_and_b32_e32 v71, 0xffff0000, v71
	v_lshlrev_b32_e32 v52, 16, v53
	v_and_b32_e32 v53, 0xffff0000, v53
	v_pk_fma_f32 v[50:51], v[50:51], v[70:71], v[54:55]
	v_cndmask_b32_e64 v55, v237, 0, s[50:51]
	v_pk_fma_f32 v[44:45], v[44:45], v[52:53], v[48:49]
	s_nop 0
	s_nop 0
	v_cndmask_b32_e64 v49, v238, 0, s[52:53]
	v_lshlrev_b32_e32 v54, 16, v55
	v_and_b32_e32 v55, 0xffff0000, v55
	v_lshlrev_b32_e32 v48, 16, v49
	v_and_b32_e32 v49, 0xffff0000, v49
	v_add_f32_e32 v34, 1.0, v34
	v_add_f32_e32 v35, v35, v63
	v_add_f32_e32 v33, v33, v61
	v_pk_fma_f32 v[46:47], v[46:47], v[54:55], v[50:51]
	v_cndmask_b32_e64 v51, v239, 0, s[52:53]
	v_pk_fma_f32 v[40:41], v[40:41], v[48:49], v[44:45]
	v_rcp_f32_e32 v34, v34
	v_sqrt_f32_e32 v48, v66
	v_mul_f32_e32 v35, 0xbfb8aa3b, v35
	v_mul_f32_e32 v33, 0xbfb8aa3b, v33
	v_lshlrev_b32_e32 v50, 16, v51
	v_and_b32_e32 v51, 0xffff0000, v51
	v_exp_f32_e32 v35, v35
	v_exp_f32_e32 v33, v33
	v_pk_fma_f32 v[42:43], v[42:43], v[50:51], v[46:47]
	s_nop 0
	s_nop 0
	v_cndmask_b32_e64 v47, v243, 0, s[64:65]
	v_cndmask_b32_e64 v45, v242, 0, s[64:65]
	v_lshlrev_b32_e32 v44, 16, v45
	v_and_b32_e32 v45, 0xffff0000, v45
	v_lshlrev_b32_e32 v46, 16, v47
	v_and_b32_e32 v47, 0xffff0000, v47
	v_add_f32_e32 v32, v32, v60
	v_pk_fma_f32 v[36:37], v[36:37], v[44:45], v[40:41]
	v_pk_fma_f32 v[40:41], v[38:39], v[46:47], v[42:43]
	v_mul_f32_e32 v34, v34, v48
	v_mul_f32_e32 v32, 0xbfb8aa3b, v32
	v_mul_f32_e32 v54, v40, v34
	v_add_f32_e32 v34, 1.0, v35
	v_add_f32_e32 v33, 1.0, v33
	v_exp_f32_e32 v32, v32
	v_rcp_f32_e32 v40, v34
	v_rcp_f32_e32 v33, v33
	v_sqrt_f32_e32 v34, v65
	v_add_f32_e32 v32, 1.0, v32
	v_rcp_f32_e32 v32, v32
	v_sqrt_f32_e32 v45, v59
	v_mul_f32_e32 v33, v33, v34
	v_sqrt_f32_e32 v34, v64
	v_mul_f32_e32 v46, 0x3fb8aa3b, v56
	v_mul_f32_e32 v55, v37, v33
	v_mul_f32_e32 v33, 0x3fb8aa3b, v58
	v_mul_f32_e32 v32, v32, v34
	v_mul_f32_e32 v58, v36, v32
	v_mul_f32_e32 v32, 0x3fb8aa3b, v57
	v_exp_f32_e32 v46, v46
	v_exp_f32_e32 v44, v32
	v_mul_f32_e32 v40, v40, v45
	v_mul_f32_e32 v56, v41, v40
	v_mov_b32_e32 v41, v145
	v_exp_f32_e32 v43, v33
	v_mul_f32_e32 v35, 0x3fb8aa3b, v67
	v_mov_b32_dpp v41, v58 row_shr:1 row_mask:0xf bank_mask:0xf
	v_fmac_f32_e32 v58, v46, v41
	v_mov_b32_e32 v41, 1.0
	v_mov_b32_e32 v45, v145
	v_exp_f32_e32 v42, v35
	v_mov_b32_dpp v41, v44 row_shr:1 row_mask:0xf bank_mask:0xf
	v_mov_b32_dpp v45, v55 row_shr:1 row_mask:0xf bank_mask:0xf
	v_fmac_f32_e32 v55, v44, v45
	v_mul_f32_e32 v41, v44, v41
	v_mov_b32_e32 v44, 1.0
	v_mov_b32_e32 v45, v145
	v_mov_b32_e32 v40, 1.0
	v_mov_b32_dpp v44, v43 row_shr:1 row_mask:0xf bank_mask:0xf
	v_mov_b32_dpp v45, v54 row_shr:1 row_mask:0xf bank_mask:0xf
	v_fmac_f32_e32 v54, v43, v45
	v_mul_f32_e32 v43, v43, v44
	v_mov_b32_e32 v44, 1.0
	v_mov_b32_e32 v45, v145
	v_mov_b32_dpp v40, v46 row_shr:1 row_mask:0xf bank_mask:0xf
	v_mov_b32_dpp v44, v42 row_shr:1 row_mask:0xf bank_mask:0xf
	v_mov_b32_dpp v45, v56 row_shr:1 row_mask:0xf bank_mask:0xf
	v_mul_f32_e32 v40, v46, v40
	v_fmac_f32_e32 v56, v42, v45
	v_mul_f32_e32 v42, v42, v44
	v_mov_b32_e32 v44, 1.0
	v_mov_b32_e32 v45, v145
	v_mov_b32_e32 v51, v145
	v_mov_b32_dpp v44, v40 row_shr:2 row_mask:0xf bank_mask:0xf
	v_mov_b32_dpp v45, v58 row_shr:2 row_mask:0xf bank_mask:0xf
	v_fmac_f32_e32 v58, v40, v45
	v_mul_f32_e32 v147, v40, v44
	v_mov_b32_e32 v40, 1.0
	v_mov_b32_e32 v44, v145
	s_waitcnt lgkmcnt(3)
	v_pk_fma_f32 v[38:39], v[80:81], v[86:87], v[140:141]
	v_mov_b32_dpp v40, v41 row_shr:2 row_mask:0xf bank_mask:0xf
	v_mul_f32_e32 v57, v41, v40
	v_mov_b32_e32 v40, 1.0
	v_mov_b32_dpp v44, v55 row_shr:2 row_mask:0xf bank_mask:0xf
	v_fmac_f32_e32 v55, v41, v44
	v_mov_b32_dpp v40, v43 row_shr:2 row_mask:0xf bank_mask:0xf
	v_mul_f32_e32 v59, v43, v40
	v_mov_b32_e32 v40, 1.0
	v_mov_b32_e32 v41, v145
	v_mov_b32_e32 v45, 1.0
	v_mov_b32_dpp v40, v42 row_shr:2 row_mask:0xf bank_mask:0xf
	v_mul_f32_e32 v60, v42, v40
	v_mov_b32_e32 v40, v145
	v_mov_b32_dpp v41, v54 row_shr:2 row_mask:0xf bank_mask:0xf
	v_fmac_f32_e32 v54, v43, v41
	v_mov_b32_dpp v40, v58 row_shr:4 row_mask:0xf bank_mask:0xf
	v_fmac_f32_e32 v58, v147, v40
	v_mov_b32_e32 v40, v145
	v_mov_b32_e32 v41, v145
	v_mov_b32_dpp v51, v58 row_shr:8 row_mask:0xf bank_mask:0xf
	v_mov_b32_dpp v40, v55 row_shr:4 row_mask:0xf bank_mask:0xf
	v_fmac_f32_e32 v55, v57, v40
	v_mov_b32_e32 v40, v145
	v_mov_b32_dpp v41, v56 row_shr:2 row_mask:0xf bank_mask:0xf
	v_fmac_f32_e32 v56, v42, v41
	v_mov_b32_dpp v40, v54 row_shr:4 row_mask:0xf bank_mask:0xf
	v_fmac_f32_e32 v54, v59, v40
	v_mov_b32_e32 v40, v145
	v_mov_b32_e32 v41, 1.0
	s_nop 0
	s_nop 0
	s_waitcnt vmcnt(6)
	v_lshlrev_b32_e32 v42, 16, v246
	v_mov_b32_dpp v40, v56 row_shr:4 row_mask:0xf bank_mask:0xf
	v_mov_b32_dpp v41, v147 row_shr:4 row_mask:0xf bank_mask:0xf
	v_fmac_f32_e32 v56, v60, v40
	v_lshlrev_b32_e32 v40, 16, v244
	v_mul_f32_e32 v42, 0xbfb8aa3b, v42
	v_exp_f32_e32 v50, v42
	v_pk_mul_f32 v[42:43], v[146:147], v[40:41]
	v_mul_f32_e32 v41, 0x3d372713, v40
	v_mul_f32_e32 v41, v41, v40
	v_fmac_f32_e32 v40, v41, v40
	v_mul_f32_e32 v40, 0x3f4c422a, v40
	v_add_f32_e32 v40, v40, v40
	v_mul_f32_e32 v40, 0x3fb8aa3b, v40
	v_exp_f32_e32 v40, v40
	v_add_f32_e32 v41, 1.0, v50
	v_rcp_f32_e32 v50, v41
	v_mov_b32_e32 v41, 1.0
	v_add_f32_e32 v40, 1.0, v40
	v_rcp_f32_e32 v40, v40
	v_mov_b32_dpp v41, v43 row_shr:8 row_mask:0xf bank_mask:0xf
	v_pk_mul_f32 v[34:35], v[82:83], v[86:87]
	v_mov_b32_dpp v45, v57 row_shr:4 row_mask:0xf bank_mask:0xf
	v_fma_f32 v40, v40, -2.0, 1.0
	v_add_f32_e32 v40, 1.0, v40
	v_and_b32_e32 v44, 0xffff0000, v244
	v_fmac_f32_e32 v58, v43, v51
	v_pk_mul_f32 v[52:53], v[42:43], v[40:41]
	v_mov_b32_e32 v51, v38
	v_mov_b32_e32 v147, v57
	ds_bpermute_b32 v40, v184, v53
	v_mul_f32_e32 v41, v34, v53
	v_pk_mul_f32 v[50:51], v[50:51], v[52:53]
	v_pk_mul_f32 v[52:53], v[146:147], v[44:45]
	v_mul_f32_e32 v45, 0x3d372713, v44
	v_mul_f32_e32 v45, v45, v44
	v_fmac_f32_e32 v44, v45, v44
	v_and_b32_e32 v64, 0xffff0000, v246
	v_add_f32_e32 v43, v51, v58
	v_mul_f32_e32 v44, 0x3f4c422a, v44
	ds_bpermute_b32 v42, v184, v58
	v_mul_f32_e32 v58, v50, v43
	v_mul_f32_e32 v43, 0xbfb8aa3b, v64
	v_add_f32_e32 v44, v44, v44
	v_exp_f32_e32 v43, v43
	v_mul_f32_e32 v44, 0x3fb8aa3b, v44
	v_exp_f32_e32 v45, v44
	v_mul_f32_e32 v57, v50, v41
	v_add_f32_e32 v41, 1.0, v43
	v_rcp_f32_e32 v44, v41
	v_add_f32_e32 v41, 1.0, v45
	v_rcp_f32_e32 v41, v41
	v_mov_b32_e32 v51, 1.0
	v_mov_b32_e32 v47, 1.0
	v_lshlrev_b32_e32 v46, 16, v245
	v_fma_f32 v41, v41, -2.0, 1.0
	v_mov_b32_dpp v51, v53 row_shr:8 row_mask:0xf bank_mask:0xf
	v_add_f32_e32 v50, 1.0, v41
	v_mov_b32_dpp v47, v59 row_shr:4 row_mask:0xf bank_mask:0xf
	v_pk_mul_f32 v[50:51], v[52:53], v[50:51]
	v_mov_b32_e32 v45, v39
	v_mov_b32_e32 v147, v59
	v_mov_b32_e32 v61, v145
	ds_bpermute_b32 v41, v184, v51
	v_mul_f32_e32 v52, v35, v51
	v_pk_mul_f32 v[44:45], v[44:45], v[50:51]
	v_pk_mul_f32 v[50:51], v[146:147], v[46:47]
	v_mul_f32_e32 v47, 0x3d372713, v46
	v_mov_b32_dpp v61, v55 row_shr:8 row_mask:0xf bank_mask:0xf
	v_mul_f32_e32 v47, v47, v46
	v_fmac_f32_e32 v55, v53, v61
	v_fmac_f32_e32 v46, v47, v46
	v_lshlrev_b32_e32 v65, 16, v247
	v_add_f32_e32 v45, v45, v55
	v_mul_f32_e32 v46, 0x3f4c422a, v46
	ds_bpermute_b32 v43, v184, v55
	v_mul_f32_e32 v55, v44, v45
	v_mul_f32_e32 v45, 0xbfb8aa3b, v65
	v_add_f32_e32 v46, v46, v46
	v_exp_f32_e32 v45, v45
	v_mul_f32_e32 v46, 0x3fb8aa3b, v46
	v_exp_f32_e32 v46, v46
	v_mul_f32_e32 v59, v44, v52
	v_add_f32_e32 v44, 1.0, v45
	v_rcp_f32_e32 v52, v44
	v_add_f32_e32 v44, 1.0, v46
	v_rcp_f32_e32 v44, v44
	v_mov_b32_e32 v62, v145
	v_mov_b32_e32 v45, 1.0
	s_waitcnt lgkmcnt(4)
	v_pk_fma_f32 v[36:37], v[76:77], v[142:143], v[162:163]
	v_fma_f32 v44, v44, -2.0, 1.0
	v_mov_b32_e32 v49, 1.0
	v_mov_b32_dpp v62, v54 row_shr:8 row_mask:0xf bank_mask:0xf
	v_mov_b32_dpp v45, v51 row_shr:8 row_mask:0xf bank_mask:0xf
	v_add_f32_e32 v44, 1.0, v44
	v_pk_mul_f32 v[32:33], v[78:79], v[142:143]
	v_mov_b32_dpp v49, v60 row_shr:4 row_mask:0xf bank_mask:0xf
	v_and_b32_e32 v48, 0xffff0000, v245
	v_fmac_f32_e32 v54, v51, v62
	v_pk_mul_f32 v[50:51], v[50:51], v[44:45]
	v_mov_b32_e32 v53, v36
	v_mov_b32_e32 v147, v60
	ds_bpermute_b32 v44, v184, v51
	v_mul_f32_e32 v45, v32, v51
	v_pk_mul_f32 v[50:51], v[52:53], v[50:51]
	v_pk_mul_f32 v[52:53], v[146:147], v[48:49]
	v_mul_f32_e32 v49, 0x3d372713, v48
	v_mul_f32_e32 v49, v49, v48
	v_fmac_f32_e32 v48, v49, v48
	v_and_b32_e32 v66, 0xffff0000, v247
	v_add_f32_e32 v47, v51, v54
	v_mul_f32_e32 v48, 0x3f4c422a, v48
	ds_bpermute_b32 v46, v184, v54
	v_mul_f32_e32 v54, v50, v47
	v_mul_f32_e32 v47, 0xbfb8aa3b, v66
	v_add_f32_e32 v48, v48, v48
	v_exp_f32_e32 v47, v47
	v_mul_f32_e32 v48, 0x3fb8aa3b, v48
	v_exp_f32_e32 v49, v48
	v_mul_f32_e32 v60, v50, v45
	v_add_f32_e32 v45, 1.0, v47
	v_rcp_f32_e32 v48, v45
	v_add_f32_e32 v45, 1.0, v49
	v_rcp_f32_e32 v45, v45
	v_mov_b32_e32 v63, v145
	v_mov_b32_e32 v51, 1.0
	v_mov_b32_e32 v49, v37
	v_fma_f32 v45, v45, -2.0, 1.0
	v_mov_b32_dpp v63, v56 row_shr:8 row_mask:0xf bank_mask:0xf
	v_mov_b32_dpp v51, v53 row_shr:8 row_mask:0xf bank_mask:0xf
	v_add_f32_e32 v50, 1.0, v45
	v_fmac_f32_e32 v56, v53, v63
	v_pk_mul_f32 v[50:51], v[52:53], v[50:51]
	ds_bpermute_b32 v45, v184, v51
	ds_bpermute_b32 v47, v184, v56
	v_pk_mul_f32 v[48:49], v[48:49], v[50:51]
	s_mov_b32 s54, 0x25d59000
	v_add_f32_e32 v49, v49, v56
	v_add_co_u32_e32 v50, vcc, s54, v84
	v_mul_f32_e32 v52, v33, v51
	v_mul_f32_e32 v49, v48, v49
	v_addc_co_u32_e32 v51, vcc, 0, v85, vcc
	v_mul_f32_e32 v52, v48, v52
	v_cvt_pk_bf16_f32 v48, v58, v55
	v_cvt_pk_bf16_f32 v49, v54, v49
	global_store_dwordx2 v[50:51], v[48:49], off
	v_add_co_u32_e32 v50, vcc, 0x27d59000, v84
	v_cvt_pk_bf16_f32 v48, v57, v59
	v_cvt_pk_bf16_f32 v49, v60, v52
	s_nop 1
	v_addc_co_u32_e32 v51, vcc, 0, v85, vcc
	global_store_dwordx2 v[50:51], v[48:49], off
	s_and_saveexec_b64 s[54:55], s[6:7]
	s_cbranch_execz .LBB0_194
	s_waitcnt lgkmcnt(0)
	v_pk_fma_f32 v[48:49], v[36:37], v[44:45], v[46:47]
	v_pk_mul_f32 v[36:37], v[32:33], v[44:45]
	v_lshl_add_u64 v[32:33], s[74:75], 0, v[130:131]
	v_pk_fma_f32 v[46:47], v[38:39], v[40:41], v[42:43]
	v_add_co_u32_e32 v38, vcc, 0x2dd41000, v32
	v_pk_mul_f32 v[34:35], v[34:35], v[40:41]
	s_nop 0
	v_addc_co_u32_e32 v39, vcc, 0, v33, vcc
	v_add_co_u32_e32 v32, vcc, 0x2de41000, v32
	global_store_dwordx4 v[38:39], v[34:37], off
	s_nop 0
	v_addc_co_u32_e32 v33, vcc, 0, v33, vcc
	global_store_dwordx4 v[32:33], v[46:49], off
	s_branch .LBB0_194
.Ltramp24:
	s_branch .LBB0_24
.LBB0_277:
	s_movk_i32 s0, 0x7f
	v_cmp_gt_u32_sdwa s[42:43], v160, s0 src0_sel:BYTE_0 src1_sel:DWORD
	s_movk_i32 s0, 0x90
	v_mul_u32_u24_sdwa v142, v160, s0 dst_sel:DWORD dst_unused:UNUSED_PAD src0_sel:BYTE_0 src1_sel:DWORD
	v_cmp_eq_u32_e64 s[0:1], 1, v89
	v_lshlrev_b32_e32 v0, 5, v160
	v_and_b32_e32 v39, 0x60, v0
	v_writelane_b32 v254, s0, 20
	v_and_b32_e32 v41, 32, v0
	v_or_b32_e32 v0, 32, v88
	v_writelane_b32 v254, s1, 21
	v_cmp_eq_u32_e64 s[0:1], 2, v89
	v_cmp_gt_u32_e64 s[54:55], 48, v0
	v_lshlrev_b32_e32 v0, 1, v89
	v_writelane_b32 v254, s0, 22
	v_lshlrev_b32_e32 v1, 9, v93
	v_lshlrev_b32_e32 v91, 3, v89
	v_writelane_b32 v254, s1, 23
	v_cmp_eq_u32_e64 s[0:1], 3, v89
	v_mul_u32_u24_e32 v4, 0x2100, v90
	v_lshlrev_b32_e32 v2, 5, v92
	v_writelane_b32 v254, s0, 24
	v_mul_u32_u24_e32 v3, 0x2100, v92
	v_bfe_u32 v139, v160, 2, 6
	v_writelane_b32 v254, s1, 25
	v_cmp_eq_u32_e64 s[0:1], 4, v89
	v_or_b32_e32 v162, 16, v89
	v_mul_u32_u24_e32 v138, 0x110, v90
	v_writelane_b32 v254, s0, 26
	v_mul_u32_u24_e32 v140, 0x110, v139
	v_bfe_u32 v141, v160, 1, 7
	v_writelane_b32 v254, s1, 27
	v_cmp_eq_u32_e64 s[0:1], 5, v89
	s_mov_b32 s2, 0
	v_cmp_eq_u32_sdwa s[10:11], v160, v145 src0_sel:BYTE_0 src1_sel:DWORD
	v_writelane_b32 v254, s0, 28
	v_lshlrev_b32_e32 v143, 12, v93
	v_cmp_gt_u32_e64 s[52:53], 32, v92
	v_writelane_b32 v254, s1, 29
	v_cmp_eq_u32_e64 s[0:1], 6, v89
	v_mul_u32_u24_e32 v147, 0x110, v89
	v_or_b32_e32 v163, 32, v89
	v_writelane_b32 v254, s0, 30
	v_or_b32_e32 v164, 48, v89
	v_mul_u32_u24_e32 v165, 0x110, v41
	v_writelane_b32 v254, s1, 31
	v_cmp_eq_u32_e64 s[0:1], 7, v89
	v_mul_u32_u24_e32 v166, 0x90, v162
	v_mov_b32_e32 v35, v145
	v_writelane_b32 v254, s0, 32
	v_lshlrev_b32_e32 v36, 1, v3
	v_mov_b32_e32 v37, v145
	v_writelane_b32 v254, s1, 33
	v_cmp_eq_u32_e64 s[0:1], 8, v89
	v_lshlrev_b32_e32 v38, 2, v92
	v_lshlrev_b32_e32 v40, 1, v92
	v_writelane_b32 v254, s0, 34
	v_mov_b32_e32 v43, v145
	v_mov_b32_e32 v45, v145
	v_writelane_b32 v254, s1, 35
	v_cmp_eq_u32_e64 s[0:1], 9, v89
	s_movk_i32 s83, 0x6000
	s_nop 0
	v_writelane_b32 v254, s0, 36
	s_nop 1
	v_writelane_b32 v254, s1, 37
	v_cmp_eq_u32_e64 s[0:1], 10, v89
	s_nop 1
	v_writelane_b32 v254, s0, 38
	s_nop 1
	v_writelane_b32 v254, s1, 39
	v_cmp_eq_u32_e64 s[0:1], 11, v89
	s_nop 1
	v_writelane_b32 v254, s0, 40
	s_nop 1
	v_writelane_b32 v254, s1, 41
	v_cmp_eq_u32_e64 s[0:1], 12, v89
	s_nop 1
	v_writelane_b32 v254, s0, 42
	s_nop 1
	v_writelane_b32 v254, s1, 43
	v_cmp_eq_u32_e64 s[0:1], 13, v89
	s_nop 1
	v_writelane_b32 v254, s0, 44
	s_nop 1
	v_writelane_b32 v254, s1, 45
	v_cmp_eq_u32_e64 s[0:1], 14, v89
	s_nop 1
	v_writelane_b32 v254, s0, 46
	s_nop 1
	v_writelane_b32 v254, s1, 47
	v_cmp_eq_u32_e64 s[0:1], 15, v89
	s_nop 1
	v_writelane_b32 v254, s0, 48
	s_nop 1
	v_writelane_b32 v254, s1, 49
	v_cmp_eq_u32_e64 s[0:1], 0, v92
	s_nop 1
	v_writelane_b32 v254, s0, 50
	s_nop 1
	v_writelane_b32 v254, s1, 51
	v_cmp_gt_u32_e64 s[0:1], 2, v92
	s_nop 1
	v_writelane_b32 v254, s0, 52
	s_nop 1
	v_writelane_b32 v254, s1, 53
	v_cmp_gt_u32_e64 s[0:1], 4, v92
	s_nop 1
	v_writelane_b32 v254, s0, 54
	s_nop 1
	v_writelane_b32 v254, s1, 55
	v_cmp_gt_u32_e64 s[0:1], 8, v92
	s_nop 1
	v_writelane_b32 v254, s0, 56
	s_nop 1
	v_writelane_b32 v254, s1, 57
	v_cmp_gt_u32_e64 s[0:1], 16, v92
	s_nop 1
	v_writelane_b32 v254, s0, 58
	s_nop 1
	v_writelane_b32 v254, s1, 59
	s_mov_b32 s0, 0x37f41100
	v_or3_b32 v144, v1, v0, s0
	v_readlane_b32 s0, v253, 17
	v_lshlrev_b32_e32 v0, 5, v89
	v_mov_b32_e32 v1, v145
	v_readlane_b32 s1, v253, 18
	s_nop 1
	v_lshl_add_u64 v[32:33], s[0:1], 0, v[0:1]
	v_or_b32_e32 v0, v4, v91
	s_movk_i32 s0, 0x780
	v_lshlrev_b32_e32 v34, 1, v0
	v_and_or_b32 v0, v2, s0, v39
	s_movk_i32 s0, 0x7c0
	v_lshl_or_b32 v42, v0, 1, v207
	v_and_or_b32 v0, v2, s0, v41
	v_lshl_or_b32 v44, v0, 1, v208
	s_branch .LBB0_279

.LBB0_447:
	s_or_b64 exec, exec, s[4:5]
	v_readlane_b32 s2, v253, 0
	v_readlane_b32 s3, v253, 1
	s_lshl_b64 s[2:3], s[2:3], 2
	s_add_u32 s4, s8, s2
	s_addc_u32 s5, s9, s3
	s_add_u32 s2, s10, s2
	s_addc_u32 s3, s11, s3
	v_lshlrev_b64 v[106:107], 2, v[128:129]
	v_lshlrev_b64 v[0:1], 10, v[172:173]
	v_lshl_add_u64 v[104:105], s[4:5], 0, v[106:107]
	v_lshl_add_u64 v[106:107], s[2:3], 0, v[106:107]
	s_waitcnt lgkmcnt(0)
	s_barrier
	v_mbcnt_lo_u32_b32 v192, -1, 0
	v_mbcnt_hi_u32_b32 v192, -1, v192
	v_and_b32_e32 v192, 16, v192
	v_lshrrev_b32_e32 v192, 1, v192
	v_mul_u32_u24_e32 v192, 3, v192
	v_add_u32_e32 v192, 0xffffffe0, v192
	v_mov_b32_e32 v193, -1
	v_lshl_add_u64 v[172:173], v[0:1], 0, v[128:129]
	s_nop 0
	s_nop 0
	s_lshl_b32 s6, s27, 3
	s_add_i32 s6, s6, 0
	v_lshl_add_u32 v144, v147, 3, s6
	ds_read_b64 v[188:189], v144 offset:8192
	v_cndmask_b32_e64 v147, 0, 1, s[20:21]
	v_cmp_ne_u32_e64 s[2:3], 1, v147
	s_andn2_b64 vcc, exec, s[20:21]
	s_waitcnt lgkmcnt(0)
	v_sub_f32_e32 v153, v187, v188
	v_sub_f32_e32 v152, v186, v188
	v_sub_f32_e32 v185, v185, v188
	v_sub_f32_e32 v184, v184, v188
	v_pk_mul_f32 v[184:185], v[188:189], v[184:185] op_sel:[1,0]
	v_pk_mul_f32 v[152:153], v[188:189], v[152:153] op_sel:[1,0]
	s_waitcnt vmcnt(0)
	v_pk_fma_f32 v[0:1], v[212:213], v[184:185], v[228:229]
	v_pk_fma_f32 v[2:3], v[214:215], v[152:153], v[230:231]
	global_store_dwordx4 v[182:183], v[0:3], off
	v_lshl_add_u64 v[182:183], v[172:173], 1, s[64:65]
	v_cvt_pk_bf16_f32 v152, v0, v1
	v_cvt_pk_bf16_f32 v153, v2, v3
	v_mov_b32_e32 v236, v152
	v_mov_b32_e32 v237, v153
	v_lshl_add_u64 v[182:183], v[172:173], 2, s[72:73]
	s_cbranch_vccnz .LBB0_449
	global_store_dwordx4 v[182:183], v[0:3], off
.LBB0_449:
	s_nop 0
	s_nop 0
	v_mov_b32_e32 v184, v189
	v_mov_b32_e32 v185, v189
	v_sub_f32_e32 v143, v143, v188
	v_sub_f32_e32 v142, v142, v188
	v_sub_f32_e32 v153, v163, v188
	v_sub_f32_e32 v152, v162, v188
	v_pk_mul_f32 v[162:163], v[184:185], v[142:143]
	v_mov_b32_e32 v142, v189
	v_mov_b32_e32 v143, v189
	v_pk_mul_f32 v[152:153], v[142:143], v[152:153]
	s_and_b64 vcc, exec, s[2:3]
	s_nop 0
	v_pk_fma_f32 v[2:3], v[152:153], v[218:219], v[234:235]
	v_or_b32_e32 v152, 16, v172
	v_mov_b32_e32 v153, v173
	v_pk_fma_f32 v[0:1], v[162:163], v[216:217], v[232:233]
	v_lshl_add_u64 v[162:163], v[152:153], 2, s[66:67]
	v_lshl_add_u64 v[152:153], v[152:153], 1, s[64:65]
	global_store_dwordx4 v[162:163], v[0:3], off
	v_cvt_pk_bf16_f32 v162, v0, v1
	v_cvt_pk_bf16_f32 v163, v2, v3
	v_mov_b32_e32 v238, v162
	v_mov_b32_e32 v239, v163
	v_lshl_add_u64 v[152:153], v[152:153], 0, v[192:193]
	s_nop 0
	v_permlane16_swap_b32 v236, v238
	v_permlane16_swap_b32 v237, v239
	global_store_dwordx4 v[152:153], v[236:239], off
	s_cbranch_vccnz .LBB0_451
	global_store_dwordx4 v[182:183], v[0:3], off offset:64
.LBB0_451:
	s_nop 0
	s_nop 0
	v_sub_f32_e32 v123, v123, v188
	v_sub_f32_e32 v122, v122, v188
	v_sub_f32_e32 v121, v121, v188
	v_sub_f32_e32 v120, v120, v188
	v_or_b32_e32 v152, 0x80, v172
	v_mov_b32_e32 v153, v173
	v_pk_mul_f32 v[120:121], v[184:185], v[120:121]
	v_pk_mul_f32 v[122:123], v[142:143], v[122:123]
	s_and_b64 vcc, exec, s[2:3]
	s_nop 0
	v_pk_fma_f32 v[2:3], v[122:123], v[222:223], v[244:245]
	v_pk_fma_f32 v[0:1], v[120:121], v[220:221], v[242:243]
	v_lshl_add_u64 v[120:121], v[152:153], 2, s[66:67]
	v_lshl_add_u64 v[122:123], v[152:153], 1, s[64:65]
	global_store_dwordx4 v[120:121], v[0:3], off
	v_cvt_pk_bf16_f32 v120, v0, v1
	v_cvt_pk_bf16_f32 v121, v2, v3
	v_mov_b32_e32 v236, v120
	v_mov_b32_e32 v237, v121
	s_cbranch_vccnz .LBB0_453
	global_store_dwordx4 v[182:183], v[0:3], off offset:512
.LBB0_453:
	s_nop 0
	s_nop 0
	v_sub_f32_e32 v137, v137, v188
	v_sub_f32_e32 v136, v136, v188
	v_sub_f32_e32 v135, v135, v188
	v_sub_f32_e32 v134, v134, v188
	v_mov_b32_e32 v188, v189
	v_pk_mul_f32 v[134:135], v[184:185], v[134:135]
	v_pk_mul_f32 v[136:137], v[188:189], v[136:137]
	v_or_b32_e32 v172, 0x90, v172
	s_and_b64 vcc, exec, s[2:3]
	s_nop 0
	v_pk_fma_f32 v[2:3], v[136:137], v[226:227], v[248:249]
	v_pk_fma_f32 v[0:1], v[134:135], v[224:225], v[246:247]
	v_lshl_add_u64 v[120:121], v[172:173], 2, s[66:67]
	v_lshl_add_u64 v[122:123], v[172:173], 1, s[64:65]
	global_store_dwordx4 v[120:121], v[0:3], off
	v_cvt_pk_bf16_f32 v120, v0, v1
	v_cvt_pk_bf16_f32 v121, v2, v3
	v_mov_b32_e32 v238, v120
	v_mov_b32_e32 v239, v121
	v_lshl_add_u64 v[122:123], v[122:123], 0, v[192:193]
	s_nop 0
	v_permlane16_swap_b32 v236, v238
	v_permlane16_swap_b32 v237, v239
	global_store_dwordx4 v[122:123], v[236:239], off
	s_cbranch_vccnz .LBB0_455
	global_store_dwordx4 v[182:183], v[0:3], off offset:576
	s_nop 1
.LBB0_455:
	s_nop 1
	v_lshlrev_b64 v[0:1], 10, v[180:181]
	ds_read_b64 v[122:123], v144 offset:8320
	v_lshl_add_u64 v[120:121], v[0:1], 0, v[128:129]
	s_nop 0
	s_nop 0
	s_and_b64 vcc, exec, s[2:3]
	s_waitcnt lgkmcnt(0)
	v_sub_f32_e32 v143, v179, v122
	v_sub_f32_e32 v142, v178, v122
	v_sub_f32_e32 v153, v177, v122
	v_sub_f32_e32 v152, v176, v122
	v_pk_mul_f32 v[152:153], v[122:123], v[152:153] op_sel:[1,0]
	v_pk_mul_f32 v[142:143], v[122:123], v[142:143] op_sel:[1,0]
	s_nop 0
	v_pk_fma_f32 v[0:1], v[212:213], v[152:153], v[228:229]
	v_pk_fma_f32 v[2:3], v[214:215], v[142:143], v[230:231]
	global_store_dwordx4 v[174:175], v[0:3], off
	v_cvt_pk_bf16_f32 v134, v0, v1
	v_cvt_pk_bf16_f32 v135, v2, v3
	v_lshl_add_u64 v[136:137], v[120:121], 1, s[64:65]
	v_mov_b32_e32 v236, v134
	v_mov_b32_e32 v237, v135
	v_lshl_add_u64 v[134:135], v[120:121], 2, s[72:73]
	s_cbranch_vccnz .LBB0_457
	global_store_dwordx4 v[134:135], v[0:3], off
.LBB0_457:
	s_nop 0
	s_nop 0
	v_mov_b32_e32 v136, v123
	v_mov_b32_e32 v137, v123
	v_sub_f32_e32 v139, v139, v122
	v_sub_f32_e32 v138, v138, v122
	v_sub_f32_e32 v141, v141, v122
	v_sub_f32_e32 v140, v140, v122
	v_pk_mul_f32 v[142:143], v[136:137], v[138:139]
	v_mov_b32_e32 v138, v123
	v_mov_b32_e32 v139, v123
	v_pk_mul_f32 v[140:141], v[138:139], v[140:141]
	s_and_b64 vcc, exec, s[2:3]
	s_nop 0
	v_pk_fma_f32 v[2:3], v[140:141], v[218:219], v[234:235]
	v_or_b32_e32 v140, 16, v120
	v_mov_b32_e32 v141, v121
	v_pk_fma_f32 v[0:1], v[142:143], v[216:217], v[232:233]
	v_lshl_add_u64 v[142:143], v[140:141], 2, s[66:67]
	v_lshl_add_u64 v[140:141], v[140:141], 1, s[64:65]
	global_store_dwordx4 v[142:143], v[0:3], off
	v_cvt_pk_bf16_f32 v142, v0, v1
	v_cvt_pk_bf16_f32 v143, v2, v3
	v_mov_b32_e32 v238, v142
	v_mov_b32_e32 v239, v143
	v_lshl_add_u64 v[140:141], v[140:141], 0, v[192:193]
	s_nop 0
	v_permlane16_swap_b32 v236, v238
	v_permlane16_swap_b32 v237, v239
	global_store_dwordx4 v[140:141], v[236:239], off
	s_cbranch_vccnz .LBB0_459
	global_store_dwordx4 v[134:135], v[0:3], off offset:64
.LBB0_459:
	s_nop 0
	s_nop 0
	v_sub_f32_e32 v111, v111, v122
	v_sub_f32_e32 v110, v110, v122
	v_sub_f32_e32 v109, v109, v122
	v_sub_f32_e32 v108, v108, v122
	v_or_b32_e32 v152, 0x80, v120
	v_mov_b32_e32 v153, v121
	v_pk_mul_f32 v[108:109], v[136:137], v[108:109]
	v_pk_mul_f32 v[110:111], v[138:139], v[110:111]
	s_and_b64 vcc, exec, s[2:3]
	s_nop 0
	v_pk_fma_f32 v[2:3], v[110:111], v[222:223], v[244:245]
	v_pk_fma_f32 v[0:1], v[108:109], v[220:221], v[242:243]
	v_lshl_add_u64 v[108:109], v[152:153], 2, s[66:67]
	v_lshl_add_u64 v[110:111], v[152:153], 1, s[64:65]
	global_store_dwordx4 v[108:109], v[0:3], off
	v_cvt_pk_bf16_f32 v108, v0, v1
	v_cvt_pk_bf16_f32 v109, v2, v3
	v_mov_b32_e32 v236, v108
	v_mov_b32_e32 v237, v109
	s_cbranch_vccnz .LBB0_461
	global_store_dwordx4 v[134:135], v[0:3], off offset:512
.LBB0_461:
	s_nop 0
	s_nop 0
	v_sub_f32_e32 v119, v119, v122
	v_sub_f32_e32 v118, v118, v122
	v_sub_f32_e32 v117, v117, v122
	v_sub_f32_e32 v116, v116, v122
	v_mov_b32_e32 v122, v123
	v_pk_mul_f32 v[116:117], v[136:137], v[116:117]
	v_pk_mul_f32 v[118:119], v[122:123], v[118:119]
	v_or_b32_e32 v120, 0x90, v120
	s_and_b64 vcc, exec, s[2:3]
	s_nop 0
	v_pk_fma_f32 v[2:3], v[118:119], v[226:227], v[248:249]
	v_pk_fma_f32 v[0:1], v[116:117], v[224:225], v[246:247]
	v_lshl_add_u64 v[108:109], v[120:121], 2, s[66:67]
	v_lshl_add_u64 v[110:111], v[120:121], 1, s[64:65]
	global_store_dwordx4 v[108:109], v[0:3], off
	v_cvt_pk_bf16_f32 v108, v0, v1
	v_cvt_pk_bf16_f32 v109, v2, v3
	v_mov_b32_e32 v238, v108
	v_mov_b32_e32 v239, v109
	v_lshl_add_u64 v[110:111], v[110:111], 0, v[192:193]
	s_nop 0
	v_permlane16_swap_b32 v236, v238
	v_permlane16_swap_b32 v237, v239
	global_store_dwordx4 v[110:111], v[236:239], off
	s_cbranch_vccnz .LBB0_463
	global_store_dwordx4 v[134:135], v[0:3], off offset:576
	s_nop 1
.LBB0_463:
	s_nop 1
	v_lshlrev_b64 v[0:1], 10, v[170:171]
	ds_read_b64 v[110:111], v144 offset:8448
	v_lshl_add_u64 v[108:109], v[0:1], 0, v[128:129]
	s_nop 0
	s_nop 0
	s_and_b64 vcc, exec, s[2:3]
	s_waitcnt lgkmcnt(0)
	v_sub_f32_e32 v121, v169, v110
	v_sub_f32_e32 v120, v168, v110
	v_sub_f32_e32 v123, v167, v110
	v_sub_f32_e32 v122, v166, v110
	v_pk_mul_f32 v[122:123], v[110:111], v[122:123] op_sel:[1,0]
	v_pk_mul_f32 v[120:121], v[110:111], v[120:121] op_sel:[1,0]
	s_nop 0
	v_pk_fma_f32 v[0:1], v[212:213], v[122:123], v[228:229]
	v_pk_fma_f32 v[2:3], v[214:215], v[120:121], v[230:231]
	global_store_dwordx4 v[164:165], v[0:3], off
	v_cvt_pk_bf16_f32 v116, v0, v1
	v_cvt_pk_bf16_f32 v117, v2, v3
	v_lshl_add_u64 v[118:119], v[108:109], 1, s[64:65]
	v_mov_b32_e32 v236, v116
	v_mov_b32_e32 v237, v117
	v_lshl_add_u64 v[116:117], v[108:109], 2, s[72:73]
	s_cbranch_vccnz .LBB0_465
	global_store_dwordx4 v[116:117], v[0:3], off
.LBB0_465:
	s_nop 0
	s_nop 0
	v_mov_b32_e32 v118, v111
	v_mov_b32_e32 v119, v111
	v_sub_f32_e32 v113, v113, v110
	v_sub_f32_e32 v112, v112, v110
	v_sub_f32_e32 v115, v115, v110
	v_sub_f32_e32 v114, v114, v110
	v_pk_mul_f32 v[134:135], v[118:119], v[112:113]
	v_mov_b32_e32 v112, v111
	v_mov_b32_e32 v113, v111
	v_pk_mul_f32 v[114:115], v[112:113], v[114:115]
	s_and_b64 vcc, exec, s[2:3]
	s_nop 0
	v_pk_fma_f32 v[2:3], v[114:115], v[218:219], v[234:235]
	v_or_b32_e32 v114, 16, v108
	v_mov_b32_e32 v115, v109
	v_pk_fma_f32 v[0:1], v[134:135], v[216:217], v[232:233]
	v_lshl_add_u64 v[120:121], v[114:115], 2, s[66:67]
	v_lshl_add_u64 v[114:115], v[114:115], 1, s[64:65]
	global_store_dwordx4 v[120:121], v[0:3], off
	v_cvt_pk_bf16_f32 v120, v0, v1
	v_cvt_pk_bf16_f32 v121, v2, v3
	v_mov_b32_e32 v238, v120
	v_mov_b32_e32 v239, v121
	v_lshl_add_u64 v[114:115], v[114:115], 0, v[192:193]
	s_nop 0
	v_permlane16_swap_b32 v236, v238
	v_permlane16_swap_b32 v237, v239
	global_store_dwordx4 v[114:115], v[236:239], off
	s_cbranch_vccnz .LBB0_467
	global_store_dwordx4 v[116:117], v[0:3], off offset:64
.LBB0_467:
	s_nop 0
	s_nop 0
	v_sub_f32_e32 v87, v87, v110
	v_sub_f32_e32 v86, v86, v110
	v_sub_f32_e32 v85, v85, v110
	v_sub_f32_e32 v84, v84, v110
	v_or_b32_e32 v114, 0x80, v108
	v_mov_b32_e32 v115, v109
	v_pk_mul_f32 v[84:85], v[118:119], v[84:85]
	v_pk_mul_f32 v[86:87], v[112:113], v[86:87]
	s_and_b64 vcc, exec, s[2:3]
	s_nop 0
	v_pk_fma_f32 v[2:3], v[86:87], v[222:223], v[244:245]
	v_pk_fma_f32 v[0:1], v[84:85], v[220:221], v[242:243]
	v_lshl_add_u64 v[84:85], v[114:115], 2, s[66:67]
	v_lshl_add_u64 v[86:87], v[114:115], 1, s[64:65]
	global_store_dwordx4 v[84:85], v[0:3], off
	v_cvt_pk_bf16_f32 v84, v0, v1
	v_cvt_pk_bf16_f32 v85, v2, v3
	v_mov_b32_e32 v236, v84
	v_mov_b32_e32 v237, v85
	s_cbranch_vccnz .LBB0_469
	global_store_dwordx4 v[116:117], v[0:3], off offset:512
.LBB0_469:
	s_nop 0
	s_nop 0
	v_sub_f32_e32 v95, v95, v110
	v_sub_f32_e32 v94, v94, v110
	v_sub_f32_e32 v93, v93, v110
	v_sub_f32_e32 v92, v92, v110
	v_mov_b32_e32 v110, v111
	v_pk_mul_f32 v[92:93], v[118:119], v[92:93]
	v_pk_mul_f32 v[94:95], v[110:111], v[94:95]
	v_or_b32_e32 v108, 0x90, v108
	s_and_b64 vcc, exec, s[2:3]
	s_nop 0
	v_pk_fma_f32 v[2:3], v[94:95], v[226:227], v[248:249]
	v_pk_fma_f32 v[0:1], v[92:93], v[224:225], v[246:247]
	v_lshl_add_u64 v[84:85], v[108:109], 2, s[66:67]
	v_lshl_add_u64 v[86:87], v[108:109], 1, s[64:65]
	global_store_dwordx4 v[84:85], v[0:3], off
	v_cvt_pk_bf16_f32 v84, v0, v1
	v_cvt_pk_bf16_f32 v85, v2, v3
	v_mov_b32_e32 v238, v84
	v_mov_b32_e32 v239, v85
	v_lshl_add_u64 v[86:87], v[86:87], 0, v[192:193]
	s_nop 0
	v_permlane16_swap_b32 v236, v238
	v_permlane16_swap_b32 v237, v239
	global_store_dwordx4 v[86:87], v[236:239], off
	s_cbranch_vccnz .LBB0_471
	global_store_dwordx4 v[116:117], v[0:3], off offset:576
	s_nop 1
.LBB0_471:
	s_nop 1
	v_lshlrev_b64 v[0:1], 10, v[132:133]
	ds_read_b64 v[86:87], v144 offset:8576
	v_lshl_add_u64 v[84:85], v[0:1], 0, v[128:129]
	s_nop 0
	s_nop 0
	s_and_b64 vcc, exec, s[2:3]
	s_waitcnt lgkmcnt(0)
	v_sub_f32_e32 v109, v131, v86
	v_sub_f32_e32 v108, v130, v86
	v_sub_f32_e32 v111, v127, v86
	v_sub_f32_e32 v110, v126, v86
	v_pk_mul_f32 v[110:111], v[86:87], v[110:111] op_sel:[1,0]
	v_pk_mul_f32 v[108:109], v[86:87], v[108:109] op_sel:[1,0]
	s_nop 0
	v_pk_fma_f32 v[0:1], v[212:213], v[110:111], v[228:229]
	v_pk_fma_f32 v[2:3], v[214:215], v[108:109], v[230:231]
	global_store_dwordx4 v[124:125], v[0:3], off
	v_cvt_pk_bf16_f32 v92, v0, v1
	v_cvt_pk_bf16_f32 v93, v2, v3
	v_lshl_add_u64 v[94:95], v[84:85], 1, s[64:65]
	v_mov_b32_e32 v236, v92
	v_mov_b32_e32 v237, v93
	v_lshl_add_u64 v[92:93], v[84:85], 2, s[72:73]
	s_cbranch_vccnz .LBB0_473
	global_store_dwordx4 v[92:93], v[0:3], off
.LBB0_473:
	s_nop 0
	s_nop 0
	v_mov_b32_e32 v94, v87
	v_mov_b32_e32 v95, v87
	v_sub_f32_e32 v89, v89, v86
	v_sub_f32_e32 v88, v88, v86
	v_sub_f32_e32 v91, v91, v86
	v_sub_f32_e32 v90, v90, v86
	v_pk_mul_f32 v[112:113], v[94:95], v[88:89]
	v_mov_b32_e32 v88, v87
	v_mov_b32_e32 v89, v87
	v_pk_mul_f32 v[90:91], v[88:89], v[90:91]
	s_and_b64 vcc, exec, s[2:3]
	s_nop 0
	v_pk_fma_f32 v[2:3], v[90:91], v[218:219], v[234:235]
	v_or_b32_e32 v90, 16, v84
	v_mov_b32_e32 v91, v85
	v_pk_fma_f32 v[0:1], v[112:113], v[216:217], v[232:233]
	v_lshl_add_u64 v[108:109], v[90:91], 2, s[66:67]
	v_lshl_add_u64 v[90:91], v[90:91], 1, s[64:65]
	global_store_dwordx4 v[108:109], v[0:3], off
	v_cvt_pk_bf16_f32 v108, v0, v1
	v_cvt_pk_bf16_f32 v109, v2, v3
	v_mov_b32_e32 v238, v108
	v_mov_b32_e32 v239, v109
	v_lshl_add_u64 v[90:91], v[90:91], 0, v[192:193]
	s_nop 0
	v_permlane16_swap_b32 v236, v238
	v_permlane16_swap_b32 v237, v239
	global_store_dwordx4 v[90:91], v[236:239], off
	s_cbranch_vccnz .LBB0_475
	global_store_dwordx4 v[92:93], v[0:3], off offset:64
.LBB0_475:
	s_nop 0
	s_nop 0
	v_sub_f32_e32 v71, v71, v86
	v_sub_f32_e32 v70, v70, v86
	v_sub_f32_e32 v69, v69, v86
	v_sub_f32_e32 v68, v68, v86
	v_or_b32_e32 v90, 0x80, v84
	v_mov_b32_e32 v91, v85
	v_pk_mul_f32 v[68:69], v[94:95], v[68:69]
	v_pk_mul_f32 v[70:71], v[88:89], v[70:71]
	s_and_b64 vcc, exec, s[2:3]
	s_nop 0
	v_pk_fma_f32 v[2:3], v[70:71], v[222:223], v[244:245]
	v_pk_fma_f32 v[0:1], v[68:69], v[220:221], v[242:243]
	v_lshl_add_u64 v[68:69], v[90:91], 2, s[66:67]
	v_lshl_add_u64 v[70:71], v[90:91], 1, s[64:65]
	global_store_dwordx4 v[68:69], v[0:3], off
	v_cvt_pk_bf16_f32 v68, v0, v1
	v_cvt_pk_bf16_f32 v69, v2, v3
	v_mov_b32_e32 v236, v68
	v_mov_b32_e32 v237, v69
	s_cbranch_vccnz .LBB0_477
	global_store_dwordx4 v[92:93], v[0:3], off offset:512
.LBB0_477:
	s_nop 0
	s_nop 0
	v_sub_f32_e32 v75, v75, v86
	v_sub_f32_e32 v74, v74, v86
	v_sub_f32_e32 v73, v73, v86
	v_sub_f32_e32 v72, v72, v86
	v_mov_b32_e32 v86, v87
	v_pk_mul_f32 v[72:73], v[94:95], v[72:73]
	v_pk_mul_f32 v[74:75], v[86:87], v[74:75]
	v_or_b32_e32 v84, 0x90, v84
	s_and_b64 vcc, exec, s[2:3]
	s_nop 0
	v_pk_fma_f32 v[2:3], v[74:75], v[226:227], v[248:249]
	v_pk_fma_f32 v[0:1], v[72:73], v[224:225], v[246:247]
	v_lshl_add_u64 v[68:69], v[84:85], 2, s[66:67]
	v_lshl_add_u64 v[70:71], v[84:85], 1, s[64:65]
	global_store_dwordx4 v[68:69], v[0:3], off
	v_cvt_pk_bf16_f32 v68, v0, v1
	v_cvt_pk_bf16_f32 v69, v2, v3
	v_mov_b32_e32 v238, v68
	v_mov_b32_e32 v239, v69
	v_lshl_add_u64 v[70:71], v[70:71], 0, v[192:193]
	s_nop 0
	v_permlane16_swap_b32 v236, v238
	v_permlane16_swap_b32 v237, v239
	global_store_dwordx4 v[70:71], v[236:239], off
	s_cbranch_vccnz .LBB0_479
	global_store_dwordx4 v[92:93], v[0:3], off offset:576
	s_nop 1
.LBB0_479:
	s_nop 1
	v_lshlrev_b64 v[0:1], 10, v[102:103]
	ds_read_b64 v[70:71], v144 offset:9216
	v_lshl_add_u64 v[68:69], v[0:1], 0, v[128:129]
	s_nop 0
	s_nop 0
	s_and_b64 vcc, exec, s[2:3]
	s_waitcnt lgkmcnt(0)
	v_sub_f32_e32 v85, v101, v70
	v_sub_f32_e32 v84, v100, v70
	v_sub_f32_e32 v87, v99, v70
	v_sub_f32_e32 v86, v98, v70
	v_pk_mul_f32 v[86:87], v[70:71], v[86:87] op_sel:[1,0]
	v_pk_mul_f32 v[84:85], v[70:71], v[84:85] op_sel:[1,0]
	s_nop 0
	v_pk_fma_f32 v[0:1], v[212:213], v[86:87], v[228:229]
	v_pk_fma_f32 v[2:3], v[214:215], v[84:85], v[230:231]
	global_store_dwordx4 v[96:97], v[0:3], off
	v_cvt_pk_bf16_f32 v72, v0, v1
	v_cvt_pk_bf16_f32 v73, v2, v3
	v_lshl_add_u64 v[74:75], v[68:69], 1, s[64:65]
	v_mov_b32_e32 v236, v72
	v_mov_b32_e32 v237, v73
	v_lshl_add_u64 v[72:73], v[68:69], 2, s[72:73]
	s_cbranch_vccnz .LBB0_481
	global_store_dwordx4 v[72:73], v[0:3], off
.LBB0_481:
	s_nop 0
	s_nop 0
	v_mov_b32_e32 v74, v71
	v_mov_b32_e32 v75, v71
	v_sub_f32_e32 v65, v65, v70
	v_sub_f32_e32 v64, v64, v70
	v_sub_f32_e32 v67, v67, v70
	v_sub_f32_e32 v66, v66, v70
	v_pk_mul_f32 v[88:89], v[74:75], v[64:65]
	v_mov_b32_e32 v64, v71
	v_mov_b32_e32 v65, v71
	v_pk_mul_f32 v[66:67], v[64:65], v[66:67]
	s_and_b64 vcc, exec, s[2:3]
	s_nop 0
	v_pk_fma_f32 v[2:3], v[66:67], v[218:219], v[234:235]
	v_or_b32_e32 v66, 16, v68
	v_mov_b32_e32 v67, v69
	v_pk_fma_f32 v[0:1], v[88:89], v[216:217], v[232:233]
	v_lshl_add_u64 v[84:85], v[66:67], 2, s[66:67]
	v_lshl_add_u64 v[66:67], v[66:67], 1, s[64:65]
	global_store_dwordx4 v[84:85], v[0:3], off
	v_cvt_pk_bf16_f32 v84, v0, v1
	v_cvt_pk_bf16_f32 v85, v2, v3
	v_mov_b32_e32 v238, v84
	v_mov_b32_e32 v239, v85
	v_lshl_add_u64 v[66:67], v[66:67], 0, v[192:193]
	s_nop 0
	v_permlane16_swap_b32 v236, v238
	v_permlane16_swap_b32 v237, v239
	global_store_dwordx4 v[66:67], v[236:239], off
	s_cbranch_vccnz .LBB0_483
	global_store_dwordx4 v[72:73], v[0:3], off offset:64
.LBB0_483:
	s_nop 0
	s_nop 0
	v_sub_f32_e32 v55, v55, v70
	v_sub_f32_e32 v54, v54, v70
	v_sub_f32_e32 v53, v53, v70
	v_sub_f32_e32 v52, v52, v70
	v_or_b32_e32 v66, 0x80, v68
	v_mov_b32_e32 v67, v69
	v_pk_mul_f32 v[52:53], v[74:75], v[52:53]
	v_pk_mul_f32 v[54:55], v[64:65], v[54:55]
	s_and_b64 vcc, exec, s[2:3]
	s_nop 0
	v_pk_fma_f32 v[2:3], v[54:55], v[222:223], v[244:245]
	v_pk_fma_f32 v[0:1], v[52:53], v[220:221], v[242:243]
	v_lshl_add_u64 v[52:53], v[66:67], 2, s[66:67]
	v_lshl_add_u64 v[54:55], v[66:67], 1, s[64:65]
	global_store_dwordx4 v[52:53], v[0:3], off
	v_cvt_pk_bf16_f32 v52, v0, v1
	v_cvt_pk_bf16_f32 v53, v2, v3
	v_mov_b32_e32 v236, v52
	v_mov_b32_e32 v237, v53
	s_cbranch_vccnz .LBB0_485
	global_store_dwordx4 v[72:73], v[0:3], off offset:512
.LBB0_485:
	s_nop 0
	s_nop 0
	v_sub_f32_e32 v51, v51, v70
	v_sub_f32_e32 v50, v50, v70
	v_sub_f32_e32 v49, v49, v70
	v_sub_f32_e32 v48, v48, v70
	v_mov_b32_e32 v70, v71
	v_pk_mul_f32 v[48:49], v[74:75], v[48:49]
	v_pk_mul_f32 v[50:51], v[70:71], v[50:51]
	v_or_b32_e32 v68, 0x90, v68
	s_and_b64 vcc, exec, s[2:3]
	s_nop 0
	v_pk_fma_f32 v[2:3], v[50:51], v[226:227], v[248:249]
	v_pk_fma_f32 v[0:1], v[48:49], v[224:225], v[246:247]
	v_lshl_add_u64 v[48:49], v[68:69], 2, s[66:67]
	v_lshl_add_u64 v[50:51], v[68:69], 1, s[64:65]
	global_store_dwordx4 v[48:49], v[0:3], off
	v_cvt_pk_bf16_f32 v48, v0, v1
	v_cvt_pk_bf16_f32 v49, v2, v3
	v_mov_b32_e32 v238, v48
	v_mov_b32_e32 v239, v49
	v_lshl_add_u64 v[50:51], v[50:51], 0, v[192:193]
	s_nop 0
	v_permlane16_swap_b32 v236, v238
	v_permlane16_swap_b32 v237, v239
	global_store_dwordx4 v[50:51], v[236:239], off
	s_cbranch_vccnz .LBB0_487
	global_store_dwordx4 v[72:73], v[0:3], off offset:576
	s_nop 1
.LBB0_487:
	s_nop 1
	v_lshlrev_b64 v[0:1], 10, v[82:83]
	ds_read_b64 v[50:51], v144 offset:9344
	v_lshl_add_u64 v[48:49], v[0:1], 0, v[128:129]
	s_nop 0
	s_nop 0
	s_and_b64 vcc, exec, s[2:3]
	s_waitcnt lgkmcnt(0)
	v_sub_f32_e32 v65, v81, v50
	v_sub_f32_e32 v64, v80, v50
	v_sub_f32_e32 v67, v79, v50
	v_sub_f32_e32 v66, v78, v50
	v_pk_mul_f32 v[66:67], v[50:51], v[66:67] op_sel:[1,0]
	v_pk_mul_f32 v[64:65], v[50:51], v[64:65] op_sel:[1,0]
	s_nop 0
	v_pk_fma_f32 v[0:1], v[212:213], v[66:67], v[228:229]
	v_pk_fma_f32 v[2:3], v[214:215], v[64:65], v[230:231]
	global_store_dwordx4 v[76:77], v[0:3], off
	v_cvt_pk_bf16_f32 v52, v0, v1
	v_cvt_pk_bf16_f32 v53, v2, v3
	v_lshl_add_u64 v[54:55], v[48:49], 1, s[64:65]
	v_mov_b32_e32 v236, v52
	v_mov_b32_e32 v237, v53
	v_lshl_add_u64 v[52:53], v[48:49], 2, s[72:73]
	s_cbranch_vccnz .LBB0_489
	global_store_dwordx4 v[52:53], v[0:3], off
.LBB0_489:
	s_nop 0
	s_nop 0
	v_mov_b32_e32 v54, v51
	v_mov_b32_e32 v55, v51
	v_sub_f32_e32 v45, v45, v50
	v_sub_f32_e32 v44, v44, v50
	v_sub_f32_e32 v47, v47, v50
	v_sub_f32_e32 v46, v46, v50
	v_pk_mul_f32 v[68:69], v[54:55], v[44:45]
	v_mov_b32_e32 v44, v51
	v_mov_b32_e32 v45, v51
	v_pk_mul_f32 v[46:47], v[44:45], v[46:47]
	s_and_b64 vcc, exec, s[2:3]
	s_nop 0
	v_pk_fma_f32 v[2:3], v[46:47], v[218:219], v[234:235]
	v_or_b32_e32 v46, 16, v48
	v_mov_b32_e32 v47, v49
	v_pk_fma_f32 v[0:1], v[68:69], v[216:217], v[232:233]
	v_lshl_add_u64 v[64:65], v[46:47], 2, s[66:67]
	v_lshl_add_u64 v[46:47], v[46:47], 1, s[64:65]
	global_store_dwordx4 v[64:65], v[0:3], off
	v_cvt_pk_bf16_f32 v64, v0, v1
	v_cvt_pk_bf16_f32 v65, v2, v3
	v_mov_b32_e32 v238, v64
	v_mov_b32_e32 v239, v65
	v_lshl_add_u64 v[46:47], v[46:47], 0, v[192:193]
	s_nop 0
	v_permlane16_swap_b32 v236, v238
	v_permlane16_swap_b32 v237, v239
	global_store_dwordx4 v[46:47], v[236:239], off
	s_cbranch_vccnz .LBB0_491
	global_store_dwordx4 v[52:53], v[0:3], off offset:64
.LBB0_491:
	s_nop 0
	s_nop 0
	v_sub_f32_e32 v39, v39, v50
	v_sub_f32_e32 v38, v38, v50
	v_sub_f32_e32 v37, v37, v50
	v_sub_f32_e32 v36, v36, v50
	v_or_b32_e32 v46, 0x80, v48
	v_mov_b32_e32 v47, v49
	v_pk_mul_f32 v[36:37], v[54:55], v[36:37]
	v_pk_mul_f32 v[38:39], v[44:45], v[38:39]
	s_and_b64 vcc, exec, s[2:3]
	s_nop 0
	v_pk_fma_f32 v[2:3], v[38:39], v[222:223], v[244:245]
	v_pk_fma_f32 v[0:1], v[36:37], v[220:221], v[242:243]
	v_lshl_add_u64 v[36:37], v[46:47], 2, s[66:67]
	v_lshl_add_u64 v[38:39], v[46:47], 1, s[64:65]
	global_store_dwordx4 v[36:37], v[0:3], off
	v_cvt_pk_bf16_f32 v36, v0, v1
	v_cvt_pk_bf16_f32 v37, v2, v3
	v_mov_b32_e32 v236, v36
	v_mov_b32_e32 v237, v37
	s_cbranch_vccnz .LBB0_493
	global_store_dwordx4 v[52:53], v[0:3], off offset:512
.LBB0_493:
	s_nop 0
	s_nop 0
	v_sub_f32_e32 v35, v35, v50
	v_sub_f32_e32 v34, v34, v50
	v_sub_f32_e32 v33, v33, v50
	v_sub_f32_e32 v32, v32, v50
	v_mov_b32_e32 v50, v51
	v_pk_mul_f32 v[32:33], v[54:55], v[32:33]
	v_pk_mul_f32 v[34:35], v[50:51], v[34:35]
	v_or_b32_e32 v48, 0x90, v48
	s_and_b64 vcc, exec, s[2:3]
	s_nop 0
	v_pk_fma_f32 v[2:3], v[34:35], v[226:227], v[248:249]
	v_pk_fma_f32 v[0:1], v[32:33], v[224:225], v[246:247]
	v_lshl_add_u64 v[32:33], v[48:49], 2, s[66:67]
	v_lshl_add_u64 v[34:35], v[48:49], 1, s[64:65]
	global_store_dwordx4 v[32:33], v[0:3], off
	v_cvt_pk_bf16_f32 v32, v0, v1
	v_cvt_pk_bf16_f32 v33, v2, v3
	v_mov_b32_e32 v238, v32
	v_mov_b32_e32 v239, v33
	v_lshl_add_u64 v[34:35], v[34:35], 0, v[192:193]
	s_nop 0
	v_permlane16_swap_b32 v236, v238
	v_permlane16_swap_b32 v237, v239
	global_store_dwordx4 v[34:35], v[236:239], off
	s_cbranch_vccnz .LBB0_495
	global_store_dwordx4 v[52:53], v[0:3], off offset:576
	s_nop 1
.LBB0_495:
	s_nop 1
	v_lshlrev_b64 v[0:1], 10, v[62:63]
	ds_read_b64 v[34:35], v144 offset:9472
	v_lshl_add_u64 v[32:33], v[0:1], 0, v[128:129]
	s_nop 0
	s_nop 0
	s_and_b64 vcc, exec, s[2:3]
	s_waitcnt lgkmcnt(0)
	v_sub_f32_e32 v45, v61, v34
	v_sub_f32_e32 v44, v60, v34
	v_sub_f32_e32 v47, v59, v34
	v_sub_f32_e32 v46, v58, v34
	v_pk_mul_f32 v[46:47], v[34:35], v[46:47] op_sel:[1,0]
	v_pk_mul_f32 v[44:45], v[34:35], v[44:45] op_sel:[1,0]
	s_nop 0
	v_pk_fma_f32 v[0:1], v[212:213], v[46:47], v[228:229]
	v_pk_fma_f32 v[2:3], v[214:215], v[44:45], v[230:231]
	global_store_dwordx4 v[56:57], v[0:3], off
	v_cvt_pk_bf16_f32 v36, v0, v1
	v_cvt_pk_bf16_f32 v37, v2, v3
	v_lshl_add_u64 v[38:39], v[32:33], 1, s[64:65]
	v_mov_b32_e32 v236, v36
	v_mov_b32_e32 v237, v37
	v_lshl_add_u64 v[36:37], v[32:33], 2, s[72:73]
	s_cbranch_vccnz .LBB0_497
	global_store_dwordx4 v[36:37], v[0:3], off
.LBB0_497:
	s_nop 0
	s_nop 0
	v_mov_b32_e32 v38, v35
	v_mov_b32_e32 v39, v35
	v_sub_f32_e32 v25, v25, v34
	v_sub_f32_e32 v24, v24, v34
	v_sub_f32_e32 v27, v27, v34
	v_sub_f32_e32 v26, v26, v34
	v_pk_mul_f32 v[48:49], v[38:39], v[24:25]
	v_mov_b32_e32 v24, v35
	v_mov_b32_e32 v25, v35
	v_pk_mul_f32 v[26:27], v[24:25], v[26:27]
	s_and_b64 vcc, exec, s[2:3]
	s_nop 0
	v_pk_fma_f32 v[2:3], v[26:27], v[218:219], v[234:235]
	v_or_b32_e32 v26, 16, v32
	v_mov_b32_e32 v27, v33
	v_pk_fma_f32 v[0:1], v[48:49], v[216:217], v[232:233]
	v_lshl_add_u64 v[44:45], v[26:27], 2, s[66:67]
	v_lshl_add_u64 v[26:27], v[26:27], 1, s[64:65]
	global_store_dwordx4 v[44:45], v[0:3], off
	v_cvt_pk_bf16_f32 v44, v0, v1
	v_cvt_pk_bf16_f32 v45, v2, v3
	v_mov_b32_e32 v238, v44
	v_mov_b32_e32 v239, v45
	v_lshl_add_u64 v[26:27], v[26:27], 0, v[192:193]
	s_nop 0
	v_permlane16_swap_b32 v236, v238
	v_permlane16_swap_b32 v237, v239
	global_store_dwordx4 v[26:27], v[236:239], off
	s_cbranch_vccnz .LBB0_499
	global_store_dwordx4 v[36:37], v[0:3], off offset:64
.LBB0_499:
	s_nop 0
	s_nop 0
	v_sub_f32_e32 v23, v23, v34
	v_sub_f32_e32 v22, v22, v34
	v_sub_f32_e32 v21, v21, v34
	v_sub_f32_e32 v20, v20, v34
	v_or_b32_e32 v26, 0x80, v32
	v_mov_b32_e32 v27, v33
	v_pk_mul_f32 v[20:21], v[38:39], v[20:21]
	v_pk_mul_f32 v[22:23], v[24:25], v[22:23]
	s_and_b64 vcc, exec, s[2:3]
	s_nop 0
	v_pk_fma_f32 v[2:3], v[22:23], v[222:223], v[244:245]
	v_pk_fma_f32 v[0:1], v[20:21], v[220:221], v[242:243]
	v_lshl_add_u64 v[20:21], v[26:27], 2, s[66:67]
	v_lshl_add_u64 v[22:23], v[26:27], 1, s[64:65]
	global_store_dwordx4 v[20:21], v[0:3], off
	v_cvt_pk_bf16_f32 v20, v0, v1
	v_cvt_pk_bf16_f32 v21, v2, v3
	v_mov_b32_e32 v236, v20
	v_mov_b32_e32 v237, v21
	s_cbranch_vccnz .LBB0_501
	global_store_dwordx4 v[36:37], v[0:3], off offset:512
.LBB0_501:
	s_nop 0
	s_nop 0
	v_sub_f32_e32 v19, v19, v34
	v_sub_f32_e32 v18, v18, v34
	v_sub_f32_e32 v17, v17, v34
	v_sub_f32_e32 v16, v16, v34
	v_mov_b32_e32 v34, v35
	v_pk_mul_f32 v[16:17], v[38:39], v[16:17]
	v_pk_mul_f32 v[18:19], v[34:35], v[18:19]
	v_or_b32_e32 v32, 0x90, v32
	s_and_b64 vcc, exec, s[2:3]
	s_nop 0
	v_pk_fma_f32 v[2:3], v[18:19], v[226:227], v[248:249]
	v_pk_fma_f32 v[0:1], v[16:17], v[224:225], v[246:247]
	v_lshl_add_u64 v[16:17], v[32:33], 2, s[66:67]
	v_lshl_add_u64 v[18:19], v[32:33], 1, s[64:65]
	global_store_dwordx4 v[16:17], v[0:3], off
	v_cvt_pk_bf16_f32 v16, v0, v1
	v_cvt_pk_bf16_f32 v17, v2, v3
	v_mov_b32_e32 v238, v16
	v_mov_b32_e32 v239, v17
	v_lshl_add_u64 v[18:19], v[18:19], 0, v[192:193]
	s_nop 0
	v_permlane16_swap_b32 v236, v238
	v_permlane16_swap_b32 v237, v239
	global_store_dwordx4 v[18:19], v[236:239], off
	s_cbranch_vccnz .LBB0_503
	global_store_dwordx4 v[36:37], v[0:3], off offset:576
	s_nop 1
.LBB0_503:
	s_nop 1
	v_lshlrev_b64 v[0:1], 10, v[42:43]
	ds_read_b64 v[18:19], v144 offset:9600
	v_lshl_add_u64 v[16:17], v[0:1], 0, v[128:129]
	s_nop 0
	s_nop 0
	s_and_b64 vcc, exec, s[2:3]
	s_waitcnt lgkmcnt(0)
	v_sub_f32_e32 v25, v41, v18
	v_sub_f32_e32 v24, v40, v18
	v_sub_f32_e32 v27, v31, v18
	v_sub_f32_e32 v26, v30, v18
	v_pk_mul_f32 v[26:27], v[18:19], v[26:27] op_sel:[1,0]
	v_pk_mul_f32 v[24:25], v[18:19], v[24:25] op_sel:[1,0]
	s_nop 0
	v_pk_fma_f32 v[0:1], v[212:213], v[26:27], v[228:229]
	v_pk_fma_f32 v[2:3], v[214:215], v[24:25], v[230:231]
	global_store_dwordx4 v[28:29], v[0:3], off
	v_cvt_pk_bf16_f32 v20, v0, v1
	v_cvt_pk_bf16_f32 v21, v2, v3
	v_lshl_add_u64 v[22:23], v[16:17], 1, s[64:65]
	v_mov_b32_e32 v236, v20
	v_mov_b32_e32 v237, v21
	v_lshl_add_u64 v[20:21], v[16:17], 2, s[72:73]
	s_cbranch_vccnz .LBB0_505
	global_store_dwordx4 v[20:21], v[0:3], off
.LBB0_505:
	s_nop 0
	s_nop 0
	v_mov_b32_e32 v22, v19
	v_mov_b32_e32 v23, v19
	v_sub_f32_e32 v13, v13, v18
	v_sub_f32_e32 v12, v12, v18
	v_sub_f32_e32 v15, v15, v18
	v_sub_f32_e32 v14, v14, v18
	v_pk_mul_f32 v[28:29], v[22:23], v[12:13]
	v_mov_b32_e32 v12, v19
	v_mov_b32_e32 v13, v19
	v_pk_mul_f32 v[14:15], v[12:13], v[14:15]
	s_and_b64 vcc, exec, s[2:3]
	s_nop 0
	v_pk_fma_f32 v[2:3], v[14:15], v[218:219], v[234:235]
	v_or_b32_e32 v14, 16, v16
	v_mov_b32_e32 v15, v17
	v_pk_fma_f32 v[0:1], v[28:29], v[216:217], v[232:233]
	v_lshl_add_u64 v[24:25], v[14:15], 2, s[66:67]
	v_lshl_add_u64 v[14:15], v[14:15], 1, s[64:65]
	global_store_dwordx4 v[24:25], v[0:3], off
	v_cvt_pk_bf16_f32 v24, v0, v1
	v_cvt_pk_bf16_f32 v25, v2, v3
	v_mov_b32_e32 v238, v24
	v_mov_b32_e32 v239, v25
	v_lshl_add_u64 v[14:15], v[14:15], 0, v[192:193]
	s_nop 0
	v_permlane16_swap_b32 v236, v238
	v_permlane16_swap_b32 v237, v239
	global_store_dwordx4 v[14:15], v[236:239], off
	s_cbranch_vccnz .LBB0_507
	global_store_dwordx4 v[20:21], v[0:3], off offset:64
.LBB0_507:
	s_nop 0
	s_nop 0
	v_sub_f32_e32 v7, v7, v18
	v_sub_f32_e32 v6, v6, v18
	v_sub_f32_e32 v5, v5, v18
	v_sub_f32_e32 v4, v4, v18
	v_or_b32_e32 v14, 0x80, v16
	v_mov_b32_e32 v15, v17
	v_pk_mul_f32 v[4:5], v[22:23], v[4:5]
	v_pk_mul_f32 v[6:7], v[12:13], v[6:7]
	s_and_b64 vcc, exec, s[2:3]
	s_nop 0
	v_pk_fma_f32 v[2:3], v[6:7], v[222:223], v[244:245]
	v_pk_fma_f32 v[0:1], v[4:5], v[220:221], v[242:243]
	v_lshl_add_u64 v[4:5], v[14:15], 2, s[66:67]
	v_lshl_add_u64 v[6:7], v[14:15], 1, s[64:65]
	global_store_dwordx4 v[4:5], v[0:3], off
	v_cvt_pk_bf16_f32 v4, v0, v1
	v_cvt_pk_bf16_f32 v5, v2, v3
	v_mov_b32_e32 v236, v4
	v_mov_b32_e32 v237, v5
	s_cbranch_vccnz .LBB0_509
	global_store_dwordx4 v[20:21], v[0:3], off offset:512
.LBB0_509:
	s_nop 0
	s_nop 0
	v_sub_f32_e32 v11, v11, v18
	v_sub_f32_e32 v10, v10, v18
	v_sub_f32_e32 v9, v9, v18
	v_sub_f32_e32 v8, v8, v18
	v_mov_b32_e32 v18, v19
	v_or_b32_e32 v16, 0x90, v16
	v_pk_mul_f32 v[8:9], v[22:23], v[8:9]
	v_pk_mul_f32 v[10:11], v[18:19], v[10:11]
	v_lshl_add_u64 v[12:13], v[16:17], 2, s[66:67]
	v_lshl_add_u64 v[14:15], v[16:17], 1, s[64:65]
	s_and_b64 vcc, exec, s[2:3]
	s_nop 0
	v_pk_fma_f32 v[2:3], v[10:11], v[226:227], v[248:249]
	v_pk_fma_f32 v[0:1], v[8:9], v[224:225], v[246:247]
	global_store_dwordx4 v[12:13], v[0:3], off
	v_cvt_pk_bf16_f32 v4, v0, v1
	v_cvt_pk_bf16_f32 v5, v2, v3
	v_mov_b32_e32 v238, v4
	v_mov_b32_e32 v239, v5
	v_lshl_add_u64 v[14:15], v[14:15], 0, v[192:193]
	s_nop 0
	v_permlane16_swap_b32 v236, v238
	v_permlane16_swap_b32 v237, v239
	global_store_dwordx4 v[14:15], v[236:239], off
	s_cbranch_vccnz .LBB0_511
	global_store_dwordx4 v[20:21], v[0:3], off offset:576
